# rope element sequences: loop-invariant lane-class compares (fq==1, fq>0) kept only in the first element of each row group (224 of 256 elements)
# speedup vs baseline: 1.0011x; 1.0011x over previous
; DI void rope8(float (&v)[8], const float* __restrict__ rope, int s, int fq) {
;     const f32x4 c0 = *(const f32x4*)(rope + s * 16), c1 = *(const f32x4*)(rope + s * 16 + 4), s0 = *(const f32x4*)(rope + s * 16 + 8), s1 = *(const f32x4*)(rope + s * 16 + 12);
;     const float cs[8] = {c0[0], c0[1], c0[2], c0[3], c1[0], c1[1], c1[2], c1[3]}, sn[8] = {s0[0], s0[1], s0[2], s0[3], s1[0], s1[1], s1[2], s1[3]};
; #pragma unroll
;     for (int e = 0; e < 8; ++e) {
;         const float other = __shfl_xor(v[e], 16);
;         const float a = v[e] * cs[e], bq = other * sn[e];
;         v[e] = (fq == 0) ? (a - bq) : ((fq == 1) ? (a + bq) : v[e]);
;     }
; }
.LBB0_201:
	s_andn2_b64 vcc, exec, s[6:7]
	s_cbranch_vccnz .LBB0_251
	v_and_b32_e32 v11, 64, v183
	v_xor_b32_e32 v10, 16, v183
	v_add_u32_e32 v11, 64, v11
	v_cmp_lt_i32_e32 vcc, v10, v11
	v_lshlrev_b32_e32 v138, 6, v154
	s_nop 0
	v_cndmask_b32_e32 v10, v183, v10, vcc
	v_lshlrev_b32_e32 v186, 2, v10
	global_load_dwordx4 v[142:145], v138, s[68:69]
	global_load_dwordx4 v[10:13], v138, s[68:69] offset:32
	global_load_dwordx4 v[14:17], v138, s[68:69] offset:48
	s_nop 0
	global_load_dwordx4 v[138:141], v138, s[68:69] offset:16
	v_mov_b32_e32 v224, v2
	v_mov_b32_e32 v225, v2
	v_cmp_eq_u32_e64 s[0:1], 1, v1
	s_nop 0
	v_permlane16_swap_b32_e32 v224, v225
	v_cndmask_b32_e64 v187, v225, v224, s[0:1]
	v_cmp_lt_i32_e32 vcc, 0, v1
	s_waitcnt vmcnt(3)
	v_mul_f32_e32 v142, v2, v142
	s_waitcnt vmcnt(2) lgkmcnt(0)
	v_mul_f32_e32 v187, v10, v187
	v_sub_f32_e32 v10, v142, v187
	v_add_f32_e32 v142, v142, v187
	v_cndmask_b32_e64 v142, v2, v142, s[0:1]
	v_cndmask_b32_e32 v10, v10, v142, vcc
	v_mov_b32_e32 v224, v3
	v_mov_b32_e32 v225, v3
	s_nop 1
	v_permlane16_swap_b32_e32 v224, v225
	v_cndmask_b32_e64 v187, v225, v224, s[0:1]
	v_mul_f32_e32 v142, v3, v143
	s_waitcnt lgkmcnt(0)
	v_mul_f32_e32 v143, v11, v187
	v_sub_f32_e32 v11, v142, v143
	v_add_f32_e32 v142, v142, v143
	v_cndmask_b32_e64 v142, v3, v142, s[0:1]
	v_cndmask_b32_e32 v11, v11, v142, vcc
	v_mov_b32_e32 v224, v4
	v_mov_b32_e32 v225, v4
	s_nop 1
	v_permlane16_swap_b32_e32 v224, v225
	v_cndmask_b32_e64 v143, v225, v224, s[0:1]
	v_mul_f32_e32 v142, v4, v144
	s_waitcnt lgkmcnt(0)
	v_mul_f32_e32 v143, v12, v143
	v_sub_f32_e32 v12, v142, v143
	v_add_f32_e32 v142, v142, v143
	v_cndmask_b32_e64 v142, v4, v142, s[0:1]
	v_cndmask_b32_e32 v12, v12, v142, vcc
	v_mov_b32_e32 v224, v5
	v_mov_b32_e32 v225, v5
	s_nop 1
	v_permlane16_swap_b32_e32 v224, v225
	v_cndmask_b32_e64 v143, v225, v224, s[0:1]
	v_mul_f32_e32 v142, v5, v145
	s_waitcnt lgkmcnt(0)
	v_mul_f32_e32 v143, v13, v143
	v_sub_f32_e32 v13, v142, v143
	v_add_f32_e32 v142, v142, v143
	v_cndmask_b32_e64 v142, v5, v142, s[0:1]
	v_cndmask_b32_e32 v13, v13, v142, vcc
	v_mov_b32_e32 v224, v6
	v_mov_b32_e32 v225, v6
	s_nop 1
	v_permlane16_swap_b32_e32 v224, v225
	v_cndmask_b32_e64 v142, v225, v224, s[0:1]
	s_waitcnt vmcnt(0)
	v_mul_f32_e32 v138, v6, v138
	s_waitcnt lgkmcnt(0)
	v_mul_f32_e32 v142, v14, v142
	v_sub_f32_e32 v14, v138, v142
	v_add_f32_e32 v138, v138, v142
	v_cndmask_b32_e64 v138, v6, v138, s[0:1]
	v_cndmask_b32_e32 v14, v14, v138, vcc
	v_mov_b32_e32 v224, v7
	v_mov_b32_e32 v225, v7
	s_nop 1
	v_permlane16_swap_b32_e32 v224, v225
	v_cndmask_b32_e64 v142, v225, v224, s[0:1]
	v_mul_f32_e32 v138, v7, v139
	s_waitcnt lgkmcnt(0)
	v_mul_f32_e32 v139, v15, v142
	v_sub_f32_e32 v15, v138, v139
	v_add_f32_e32 v138, v138, v139
	v_cndmask_b32_e64 v138, v7, v138, s[0:1]
	v_cndmask_b32_e32 v15, v15, v138, vcc
	v_mov_b32_e32 v224, v8
	v_mov_b32_e32 v225, v8
	s_nop 1
	v_permlane16_swap_b32_e32 v224, v225
	v_cndmask_b32_e64 v139, v225, v224, s[0:1]
	v_mul_f32_e32 v138, v8, v140
	s_waitcnt lgkmcnt(0)
	v_mul_f32_e32 v139, v16, v139
	v_sub_f32_e32 v16, v138, v139
	v_add_f32_e32 v138, v138, v139
	v_cndmask_b32_e64 v138, v8, v138, s[0:1]
	v_cndmask_b32_e32 v16, v16, v138, vcc
	v_mov_b32_e32 v224, v9
	v_mov_b32_e32 v225, v9
	s_nop 1
	v_permlane16_swap_b32_e32 v224, v225
	v_cndmask_b32_e64 v139, v225, v224, s[0:1]
	v_mul_f32_e32 v138, v9, v141
	s_waitcnt lgkmcnt(0)
	v_mul_f32_e32 v139, v17, v139
	v_sub_f32_e32 v17, v138, v139
	v_add_f32_e32 v138, v138, v139
	v_cndmask_b32_e64 v138, v9, v138, s[0:1]
	v_cndmask_b32_e32 v17, v17, v138, vcc

; DI void rope8(float (&v)[8], const float* __restrict__ rope, int s, int fq) {
;     const f32x4 c0 = *(const f32x4*)(rope + s * 16), c1 = *(const f32x4*)(rope + s * 16 + 4), s0 = *(const f32x4*)(rope + s * 16 + 8), s1 = *(const f32x4*)(rope + s * 16 + 12);
;     const float cs[8] = {c0[0], c0[1], c0[2], c0[3], c1[0], c1[1], c1[2], c1[3]}, sn[8] = {s0[0], s0[1], s0[2], s0[3], s1[0], s1[1], s1[2], s1[3]};
; #pragma unroll
;     for (int e = 0; e < 8; ++e) {
;         const float other = __shfl_xor(v[e], 16);
;         const float a = v[e] * cs[e], bq = other * sn[e];
;         v[e] = (fq == 0) ? (a - bq) : ((fq == 1) ? (a + bq) : v[e]);
;     }
; }
.LBB0_267:
	s_andn2_b64 vcc, exec, s[8:9]
	s_cbranch_vccnz .LBB0_317
	v_and_b32_e32 v11, 64, v183
	v_xor_b32_e32 v10, 16, v183
	v_add_u32_e32 v11, 64, v11
	v_cmp_lt_i32_e32 vcc, v10, v11
	v_lshlrev_b32_e32 v130, 6, v140
	s_nop 0
	v_cndmask_b32_e32 v10, v183, v10, vcc
	v_lshlrev_b32_e32 v141, 2, v10
	global_load_dwordx4 v[134:137], v130, s[68:69]
	global_load_dwordx4 v[10:13], v130, s[68:69] offset:32
	global_load_dwordx4 v[14:17], v130, s[68:69] offset:48
	s_nop 0
	global_load_dwordx4 v[130:133], v130, s[68:69] offset:16
	v_mov_b32_e32 v224, v2
	v_mov_b32_e32 v225, v2
	v_cmp_eq_u32_e64 s[0:1], 1, v1
	s_nop 0
	v_permlane16_swap_b32_e32 v224, v225
	v_cndmask_b32_e64 v142, v225, v224, s[0:1]
	v_cmp_lt_i32_e32 vcc, 0, v1
	s_waitcnt vmcnt(3)
	v_mul_f32_e32 v134, v2, v134
	s_waitcnt vmcnt(2) lgkmcnt(0)
	v_mul_f32_e32 v142, v10, v142
	v_sub_f32_e32 v10, v134, v142
	v_add_f32_e32 v134, v134, v142
	v_cndmask_b32_e64 v134, v2, v134, s[0:1]
	v_cndmask_b32_e32 v10, v10, v134, vcc
	v_mov_b32_e32 v224, v3
	v_mov_b32_e32 v225, v3
	s_nop 1
	v_permlane16_swap_b32_e32 v224, v225
	v_cndmask_b32_e64 v142, v225, v224, s[0:1]
	v_mul_f32_e32 v134, v3, v135
	s_waitcnt lgkmcnt(0)
	v_mul_f32_e32 v135, v11, v142
	v_sub_f32_e32 v11, v134, v135
	v_add_f32_e32 v134, v134, v135
	v_cndmask_b32_e64 v134, v3, v134, s[0:1]
	v_cndmask_b32_e32 v11, v11, v134, vcc
	v_mov_b32_e32 v224, v4
	v_mov_b32_e32 v225, v4
	s_nop 1
	v_permlane16_swap_b32_e32 v224, v225
	v_cndmask_b32_e64 v135, v225, v224, s[0:1]
	v_mul_f32_e32 v134, v4, v136
	s_waitcnt lgkmcnt(0)
	v_mul_f32_e32 v135, v12, v135
	v_sub_f32_e32 v12, v134, v135
	v_add_f32_e32 v134, v134, v135
	v_cndmask_b32_e64 v134, v4, v134, s[0:1]
	v_cndmask_b32_e32 v12, v12, v134, vcc
	v_mov_b32_e32 v224, v5
	v_mov_b32_e32 v225, v5
	s_nop 1
	v_permlane16_swap_b32_e32 v224, v225
	v_cndmask_b32_e64 v135, v225, v224, s[0:1]
	v_mul_f32_e32 v134, v5, v137
	s_waitcnt lgkmcnt(0)
	v_mul_f32_e32 v135, v13, v135
	v_sub_f32_e32 v13, v134, v135
	v_add_f32_e32 v134, v134, v135
	v_cndmask_b32_e64 v134, v5, v134, s[0:1]
	v_cndmask_b32_e32 v13, v13, v134, vcc
	v_mov_b32_e32 v224, v6
	v_mov_b32_e32 v225, v6
	s_nop 1
	v_permlane16_swap_b32_e32 v224, v225
	v_cndmask_b32_e64 v134, v225, v224, s[0:1]
	s_waitcnt vmcnt(0)
	v_mul_f32_e32 v130, v6, v130
	s_waitcnt lgkmcnt(0)
	v_mul_f32_e32 v134, v14, v134
	v_sub_f32_e32 v14, v130, v134
	v_add_f32_e32 v130, v130, v134
	v_cndmask_b32_e64 v130, v6, v130, s[0:1]
	v_cndmask_b32_e32 v14, v14, v130, vcc
	v_mov_b32_e32 v224, v7
	v_mov_b32_e32 v225, v7
	s_nop 1
	v_permlane16_swap_b32_e32 v224, v225
	v_cndmask_b32_e64 v134, v225, v224, s[0:1]
	v_mul_f32_e32 v130, v7, v131
	s_waitcnt lgkmcnt(0)
	v_mul_f32_e32 v131, v15, v134
	v_sub_f32_e32 v15, v130, v131
	v_add_f32_e32 v130, v130, v131
	v_cndmask_b32_e64 v130, v7, v130, s[0:1]
	v_cndmask_b32_e32 v15, v15, v130, vcc
	v_mov_b32_e32 v224, v8
	v_mov_b32_e32 v225, v8
	s_nop 1
	v_permlane16_swap_b32_e32 v224, v225
	v_cndmask_b32_e64 v131, v225, v224, s[0:1]
	v_mul_f32_e32 v130, v8, v132
	s_waitcnt lgkmcnt(0)
	v_mul_f32_e32 v131, v16, v131
	v_sub_f32_e32 v16, v130, v131
	v_add_f32_e32 v130, v130, v131
	v_cndmask_b32_e64 v130, v8, v130, s[0:1]
	v_cndmask_b32_e32 v16, v16, v130, vcc
	v_mov_b32_e32 v224, v9
	v_mov_b32_e32 v225, v9
	s_nop 1
	v_permlane16_swap_b32_e32 v224, v225
	v_cndmask_b32_e64 v131, v225, v224, s[0:1]
	v_mul_f32_e32 v130, v9, v133
	s_waitcnt lgkmcnt(0)
	v_mul_f32_e32 v131, v17, v131
	v_sub_f32_e32 v17, v130, v131
	v_add_f32_e32 v130, v130, v131
	v_cndmask_b32_e64 v130, v9, v130, s[0:1]
	v_cndmask_b32_e32 v17, v17, v130, vcc

; DI void rope8(float (&v)[8], const float* __restrict__ rope, int s, int fq) {
;     const f32x4 c0 = *(const f32x4*)(rope + s * 16), c1 = *(const f32x4*)(rope + s * 16 + 4), s0 = *(const f32x4*)(rope + s * 16 + 8), s1 = *(const f32x4*)(rope + s * 16 + 12);
;     const float cs[8] = {c0[0], c0[1], c0[2], c0[3], c1[0], c1[1], c1[2], c1[3]}, sn[8] = {s0[0], s0[1], s0[2], s0[3], s1[0], s1[1], s1[2], s1[3]};
; #pragma unroll
;     for (int e = 0; e < 8; ++e) {
;         const float other = __shfl_xor(v[e], 16);
;         const float a = v[e] * cs[e], bq = other * sn[e];
;         v[e] = (fq == 0) ? (a - bq) : ((fq == 1) ? (a + bq) : v[e]);
;     }
; }
.LBB0_333:
	s_andn2_b64 vcc, exec, s[8:9]
	s_cbranch_vccnz .LBB0_383
	v_and_b32_e32 v11, 64, v183
	v_xor_b32_e32 v10, 16, v183
	v_add_u32_e32 v11, 64, v11
	v_cmp_lt_i32_e32 vcc, v10, v11
	v_lshlrev_b32_e32 v122, 6, v132
	s_nop 0
	v_cndmask_b32_e32 v10, v183, v10, vcc
	v_lshlrev_b32_e32 v133, 2, v10
	global_load_dwordx4 v[126:129], v122, s[68:69]
	global_load_dwordx4 v[10:13], v122, s[68:69] offset:32
	global_load_dwordx4 v[14:17], v122, s[68:69] offset:48
	s_nop 0
	global_load_dwordx4 v[122:125], v122, s[68:69] offset:16
	v_mov_b32_e32 v224, v2
	v_mov_b32_e32 v225, v2
	v_cmp_eq_u32_e64 s[0:1], 1, v1
	s_nop 0
	v_permlane16_swap_b32_e32 v224, v225
	v_cndmask_b32_e64 v134, v225, v224, s[0:1]
	v_cmp_lt_i32_e32 vcc, 0, v1
	s_waitcnt vmcnt(3)
	v_mul_f32_e32 v126, v2, v126
	s_waitcnt vmcnt(2) lgkmcnt(0)
	v_mul_f32_e32 v134, v10, v134
	v_sub_f32_e32 v10, v126, v134
	v_add_f32_e32 v126, v126, v134
	v_cndmask_b32_e64 v126, v2, v126, s[0:1]
	v_cndmask_b32_e32 v10, v10, v126, vcc
	v_mov_b32_e32 v224, v3
	v_mov_b32_e32 v225, v3
	s_nop 1
	v_permlane16_swap_b32_e32 v224, v225
	v_cndmask_b32_e64 v134, v225, v224, s[0:1]
	v_mul_f32_e32 v126, v3, v127
	s_waitcnt lgkmcnt(0)
	v_mul_f32_e32 v127, v11, v134
	v_sub_f32_e32 v11, v126, v127
	v_add_f32_e32 v126, v126, v127
	v_cndmask_b32_e64 v126, v3, v126, s[0:1]
	v_cndmask_b32_e32 v11, v11, v126, vcc
	v_mov_b32_e32 v224, v4
	v_mov_b32_e32 v225, v4
	s_nop 1
	v_permlane16_swap_b32_e32 v224, v225
	v_cndmask_b32_e64 v127, v225, v224, s[0:1]
	v_mul_f32_e32 v126, v4, v128
	s_waitcnt lgkmcnt(0)
	v_mul_f32_e32 v127, v12, v127
	v_sub_f32_e32 v12, v126, v127
	v_add_f32_e32 v126, v126, v127
	v_cndmask_b32_e64 v126, v4, v126, s[0:1]
	v_cndmask_b32_e32 v12, v12, v126, vcc
	v_mov_b32_e32 v224, v5
	v_mov_b32_e32 v225, v5
	s_nop 1
	v_permlane16_swap_b32_e32 v224, v225
	v_cndmask_b32_e64 v127, v225, v224, s[0:1]
	v_mul_f32_e32 v126, v5, v129
	s_waitcnt lgkmcnt(0)
	v_mul_f32_e32 v127, v13, v127
	v_sub_f32_e32 v13, v126, v127
	v_add_f32_e32 v126, v126, v127
	v_cndmask_b32_e64 v126, v5, v126, s[0:1]
	v_cndmask_b32_e32 v13, v13, v126, vcc
	v_mov_b32_e32 v224, v6
	v_mov_b32_e32 v225, v6
	s_nop 1
	v_permlane16_swap_b32_e32 v224, v225
	v_cndmask_b32_e64 v126, v225, v224, s[0:1]
	s_waitcnt vmcnt(0)
	v_mul_f32_e32 v122, v6, v122
	s_waitcnt lgkmcnt(0)
	v_mul_f32_e32 v126, v14, v126
	v_sub_f32_e32 v14, v122, v126
	v_add_f32_e32 v122, v122, v126
	v_cndmask_b32_e64 v122, v6, v122, s[0:1]
	v_cndmask_b32_e32 v14, v14, v122, vcc
	v_mov_b32_e32 v224, v7
	v_mov_b32_e32 v225, v7
	s_nop 1
	v_permlane16_swap_b32_e32 v224, v225
	v_cndmask_b32_e64 v126, v225, v224, s[0:1]
	v_mul_f32_e32 v122, v7, v123
	s_waitcnt lgkmcnt(0)
	v_mul_f32_e32 v123, v15, v126
	v_sub_f32_e32 v15, v122, v123
	v_add_f32_e32 v122, v122, v123
	v_cndmask_b32_e64 v122, v7, v122, s[0:1]
	v_cndmask_b32_e32 v15, v15, v122, vcc
	v_mov_b32_e32 v224, v8
	v_mov_b32_e32 v225, v8
	s_nop 1
	v_permlane16_swap_b32_e32 v224, v225
	v_cndmask_b32_e64 v123, v225, v224, s[0:1]
	v_mul_f32_e32 v122, v8, v124
	s_waitcnt lgkmcnt(0)
	v_mul_f32_e32 v123, v16, v123
	v_sub_f32_e32 v16, v122, v123
	v_add_f32_e32 v122, v122, v123
	v_cndmask_b32_e64 v122, v8, v122, s[0:1]
	v_cndmask_b32_e32 v16, v16, v122, vcc
	v_mov_b32_e32 v224, v9
	v_mov_b32_e32 v225, v9
	s_nop 1
	v_permlane16_swap_b32_e32 v224, v225
	v_cndmask_b32_e64 v123, v225, v224, s[0:1]
	v_mul_f32_e32 v122, v9, v125
	s_waitcnt lgkmcnt(0)
	v_mul_f32_e32 v123, v17, v123
	v_sub_f32_e32 v17, v122, v123
	v_add_f32_e32 v122, v122, v123
	v_cndmask_b32_e64 v122, v9, v122, s[0:1]
	v_cndmask_b32_e32 v17, v17, v122, vcc

; DI void rope8(float (&v)[8], const float* __restrict__ rope, int s, int fq) {
;     const f32x4 c0 = *(const f32x4*)(rope + s * 16), c1 = *(const f32x4*)(rope + s * 16 + 4), s0 = *(const f32x4*)(rope + s * 16 + 8), s1 = *(const f32x4*)(rope + s * 16 + 12);
;     const float cs[8] = {c0[0], c0[1], c0[2], c0[3], c1[0], c1[1], c1[2], c1[3]}, sn[8] = {s0[0], s0[1], s0[2], s0[3], s1[0], s1[1], s1[2], s1[3]};
; #pragma unroll
;     for (int e = 0; e < 8; ++e) {
;         const float other = __shfl_xor(v[e], 16);
;         const float a = v[e] * cs[e], bq = other * sn[e];
;         v[e] = (fq == 0) ? (a - bq) : ((fq == 1) ? (a + bq) : v[e]);
;     }
; }
.LBB0_399:
	s_andn2_b64 vcc, exec, s[8:9]
	s_cbranch_vccnz .LBB0_449
	v_and_b32_e32 v11, 64, v183
	v_xor_b32_e32 v10, 16, v183
	v_add_u32_e32 v11, 64, v11
	v_cmp_lt_i32_e32 vcc, v10, v11
	v_lshlrev_b32_e32 v114, 6, v124
	s_nop 0
	v_cndmask_b32_e32 v10, v183, v10, vcc
	v_lshlrev_b32_e32 v125, 2, v10
	global_load_dwordx4 v[118:121], v114, s[68:69]
	global_load_dwordx4 v[10:13], v114, s[68:69] offset:32
	global_load_dwordx4 v[14:17], v114, s[68:69] offset:48
	s_nop 0
	global_load_dwordx4 v[114:117], v114, s[68:69] offset:16
	v_mov_b32_e32 v224, v2
	v_mov_b32_e32 v225, v2
	v_cmp_eq_u32_e64 s[0:1], 1, v1
	s_nop 0
	v_permlane16_swap_b32_e32 v224, v225
	v_cndmask_b32_e64 v126, v225, v224, s[0:1]
	v_cmp_lt_i32_e32 vcc, 0, v1
	s_waitcnt vmcnt(3)
	v_mul_f32_e32 v118, v2, v118
	s_waitcnt vmcnt(2) lgkmcnt(0)
	v_mul_f32_e32 v126, v10, v126
	v_sub_f32_e32 v10, v118, v126
	v_add_f32_e32 v118, v118, v126
	v_cndmask_b32_e64 v118, v2, v118, s[0:1]
	v_cndmask_b32_e32 v10, v10, v118, vcc
	v_mov_b32_e32 v224, v3
	v_mov_b32_e32 v225, v3
	s_nop 1
	v_permlane16_swap_b32_e32 v224, v225
	v_cndmask_b32_e64 v126, v225, v224, s[0:1]
	v_mul_f32_e32 v118, v3, v119
	s_waitcnt lgkmcnt(0)
	v_mul_f32_e32 v119, v11, v126
	v_sub_f32_e32 v11, v118, v119
	v_add_f32_e32 v118, v118, v119
	v_cndmask_b32_e64 v118, v3, v118, s[0:1]
	v_cndmask_b32_e32 v11, v11, v118, vcc
	v_mov_b32_e32 v224, v4
	v_mov_b32_e32 v225, v4
	s_nop 1
	v_permlane16_swap_b32_e32 v224, v225
	v_cndmask_b32_e64 v119, v225, v224, s[0:1]
	v_mul_f32_e32 v118, v4, v120
	s_waitcnt lgkmcnt(0)
	v_mul_f32_e32 v119, v12, v119
	v_sub_f32_e32 v12, v118, v119
	v_add_f32_e32 v118, v118, v119
	v_cndmask_b32_e64 v118, v4, v118, s[0:1]
	v_cndmask_b32_e32 v12, v12, v118, vcc
	v_mov_b32_e32 v224, v5
	v_mov_b32_e32 v225, v5
	s_nop 1
	v_permlane16_swap_b32_e32 v224, v225
	v_cndmask_b32_e64 v119, v225, v224, s[0:1]
	v_mul_f32_e32 v118, v5, v121
	s_waitcnt lgkmcnt(0)
	v_mul_f32_e32 v119, v13, v119
	v_sub_f32_e32 v13, v118, v119
	v_add_f32_e32 v118, v118, v119
	v_cndmask_b32_e64 v118, v5, v118, s[0:1]
	v_cndmask_b32_e32 v13, v13, v118, vcc
	v_mov_b32_e32 v224, v6
	v_mov_b32_e32 v225, v6
	s_nop 1
	v_permlane16_swap_b32_e32 v224, v225
	v_cndmask_b32_e64 v118, v225, v224, s[0:1]
	s_waitcnt vmcnt(0)
	v_mul_f32_e32 v114, v6, v114
	s_waitcnt lgkmcnt(0)
	v_mul_f32_e32 v118, v14, v118
	v_sub_f32_e32 v14, v114, v118
	v_add_f32_e32 v114, v114, v118
	v_cndmask_b32_e64 v114, v6, v114, s[0:1]
	v_cndmask_b32_e32 v14, v14, v114, vcc
	v_mov_b32_e32 v224, v7
	v_mov_b32_e32 v225, v7
	s_nop 1
	v_permlane16_swap_b32_e32 v224, v225
	v_cndmask_b32_e64 v118, v225, v224, s[0:1]
	v_mul_f32_e32 v114, v7, v115
	s_waitcnt lgkmcnt(0)
	v_mul_f32_e32 v115, v15, v118
	v_sub_f32_e32 v15, v114, v115
	v_add_f32_e32 v114, v114, v115
	v_cndmask_b32_e64 v114, v7, v114, s[0:1]
	v_cndmask_b32_e32 v15, v15, v114, vcc
	v_mov_b32_e32 v224, v8
	v_mov_b32_e32 v225, v8
	s_nop 1
	v_permlane16_swap_b32_e32 v224, v225
	v_cndmask_b32_e64 v115, v225, v224, s[0:1]
	v_mul_f32_e32 v114, v8, v116
	s_waitcnt lgkmcnt(0)
	v_mul_f32_e32 v115, v16, v115
	v_sub_f32_e32 v16, v114, v115
	v_add_f32_e32 v114, v114, v115
	v_cndmask_b32_e64 v114, v8, v114, s[0:1]
	v_cndmask_b32_e32 v16, v16, v114, vcc
	v_mov_b32_e32 v224, v9
	v_mov_b32_e32 v225, v9
	s_nop 1
	v_permlane16_swap_b32_e32 v224, v225
	v_cndmask_b32_e64 v115, v225, v224, s[0:1]
	v_mul_f32_e32 v114, v9, v117
	s_waitcnt lgkmcnt(0)
	v_mul_f32_e32 v115, v17, v115
	v_sub_f32_e32 v17, v114, v115
	v_add_f32_e32 v114, v114, v115
	v_cndmask_b32_e64 v114, v9, v114, s[0:1]
	v_cndmask_b32_e32 v17, v17, v114, vcc

; DI void rope8(float (&v)[8], const float* __restrict__ rope, int s, int fq) {
;     const f32x4 c0 = *(const f32x4*)(rope + s * 16), c1 = *(const f32x4*)(rope + s * 16 + 4), s0 = *(const f32x4*)(rope + s * 16 + 8), s1 = *(const f32x4*)(rope + s * 16 + 12);
;     const float cs[8] = {c0[0], c0[1], c0[2], c0[3], c1[0], c1[1], c1[2], c1[3]}, sn[8] = {s0[0], s0[1], s0[2], s0[3], s1[0], s1[1], s1[2], s1[3]};
; #pragma unroll
;     for (int e = 0; e < 8; ++e) {
;         const float other = __shfl_xor(v[e], 16);
;         const float a = v[e] * cs[e], bq = other * sn[e];
;         v[e] = (fq == 0) ? (a - bq) : ((fq == 1) ? (a + bq) : v[e]);
;     }
; }
.LBB0_465:
	s_andn2_b64 vcc, exec, s[8:9]
	s_cbranch_vccnz .LBB0_515
	v_and_b32_e32 v11, 64, v183
	v_xor_b32_e32 v10, 16, v183
	v_add_u32_e32 v11, 64, v11
	v_cmp_lt_i32_e32 vcc, v10, v11
	v_lshlrev_b32_e32 v106, 6, v118
	s_nop 0
	v_cndmask_b32_e32 v10, v183, v10, vcc
	v_lshlrev_b32_e32 v119, 2, v10
	global_load_dwordx4 v[110:113], v106, s[68:69]
	global_load_dwordx4 v[10:13], v106, s[68:69] offset:32
	global_load_dwordx4 v[14:17], v106, s[68:69] offset:48
	s_nop 0
	global_load_dwordx4 v[106:109], v106, s[68:69] offset:16
	v_mov_b32_e32 v224, v2
	v_mov_b32_e32 v225, v2
	v_cmp_eq_u32_e64 s[0:1], 1, v1
	s_nop 0
	v_permlane16_swap_b32_e32 v224, v225
	v_cndmask_b32_e64 v120, v225, v224, s[0:1]
	v_cmp_lt_i32_e32 vcc, 0, v1
	s_waitcnt vmcnt(3)
	v_mul_f32_e32 v110, v2, v110
	s_waitcnt vmcnt(2) lgkmcnt(0)
	v_mul_f32_e32 v120, v10, v120
	v_sub_f32_e32 v10, v110, v120
	v_add_f32_e32 v110, v110, v120
	v_cndmask_b32_e64 v110, v2, v110, s[0:1]
	v_cndmask_b32_e32 v10, v10, v110, vcc
	v_mov_b32_e32 v224, v3
	v_mov_b32_e32 v225, v3
	s_nop 1
	v_permlane16_swap_b32_e32 v224, v225
	v_cndmask_b32_e64 v120, v225, v224, s[0:1]
	v_mul_f32_e32 v110, v3, v111
	s_waitcnt lgkmcnt(0)
	v_mul_f32_e32 v111, v11, v120
	v_sub_f32_e32 v11, v110, v111
	v_add_f32_e32 v110, v110, v111
	v_cndmask_b32_e64 v110, v3, v110, s[0:1]
	v_cndmask_b32_e32 v11, v11, v110, vcc
	v_mov_b32_e32 v224, v4
	v_mov_b32_e32 v225, v4
	s_nop 1
	v_permlane16_swap_b32_e32 v224, v225
	v_cndmask_b32_e64 v111, v225, v224, s[0:1]
	v_mul_f32_e32 v110, v4, v112
	s_waitcnt lgkmcnt(0)
	v_mul_f32_e32 v111, v12, v111
	v_sub_f32_e32 v12, v110, v111
	v_add_f32_e32 v110, v110, v111
	v_cndmask_b32_e64 v110, v4, v110, s[0:1]
	v_cndmask_b32_e32 v12, v12, v110, vcc
	v_mov_b32_e32 v224, v5
	v_mov_b32_e32 v225, v5
	s_nop 1
	v_permlane16_swap_b32_e32 v224, v225
	v_cndmask_b32_e64 v111, v225, v224, s[0:1]
	v_mul_f32_e32 v110, v5, v113
	s_waitcnt lgkmcnt(0)
	v_mul_f32_e32 v111, v13, v111
	v_sub_f32_e32 v13, v110, v111
	v_add_f32_e32 v110, v110, v111
	v_cndmask_b32_e64 v110, v5, v110, s[0:1]
	v_cndmask_b32_e32 v13, v13, v110, vcc
	v_mov_b32_e32 v224, v6
	v_mov_b32_e32 v225, v6
	s_nop 1
	v_permlane16_swap_b32_e32 v224, v225
	v_cndmask_b32_e64 v110, v225, v224, s[0:1]
	s_waitcnt vmcnt(0)
	v_mul_f32_e32 v106, v6, v106
	s_waitcnt lgkmcnt(0)
	v_mul_f32_e32 v110, v14, v110
	v_sub_f32_e32 v14, v106, v110
	v_add_f32_e32 v106, v106, v110
	v_cndmask_b32_e64 v106, v6, v106, s[0:1]
	v_cndmask_b32_e32 v14, v14, v106, vcc
	v_mov_b32_e32 v224, v7
	v_mov_b32_e32 v225, v7
	s_nop 1
	v_permlane16_swap_b32_e32 v224, v225
	v_cndmask_b32_e64 v110, v225, v224, s[0:1]
	v_mul_f32_e32 v106, v7, v107
	s_waitcnt lgkmcnt(0)
	v_mul_f32_e32 v107, v15, v110
	v_sub_f32_e32 v15, v106, v107
	v_add_f32_e32 v106, v106, v107
	v_cndmask_b32_e64 v106, v7, v106, s[0:1]
	v_cndmask_b32_e32 v15, v15, v106, vcc
	v_mov_b32_e32 v224, v8
	v_mov_b32_e32 v225, v8
	s_nop 1
	v_permlane16_swap_b32_e32 v224, v225
	v_cndmask_b32_e64 v107, v225, v224, s[0:1]
	v_mul_f32_e32 v106, v8, v108
	s_waitcnt lgkmcnt(0)
	v_mul_f32_e32 v107, v16, v107
	v_sub_f32_e32 v16, v106, v107
	v_add_f32_e32 v106, v106, v107
	v_cndmask_b32_e64 v106, v8, v106, s[0:1]
	v_cndmask_b32_e32 v16, v16, v106, vcc
	v_mov_b32_e32 v224, v9
	v_mov_b32_e32 v225, v9
	s_nop 1
	v_permlane16_swap_b32_e32 v224, v225
	v_cndmask_b32_e64 v107, v225, v224, s[0:1]
	v_mul_f32_e32 v106, v9, v109
	s_waitcnt lgkmcnt(0)
	v_mul_f32_e32 v107, v17, v107
	v_sub_f32_e32 v17, v106, v107
	v_add_f32_e32 v106, v106, v107
	v_cndmask_b32_e64 v106, v9, v106, s[0:1]
	v_cndmask_b32_e32 v17, v17, v106, vcc

; DI void rope8(float (&v)[8], const float* __restrict__ rope, int s, int fq) {
;     const f32x4 c0 = *(const f32x4*)(rope + s * 16), c1 = *(const f32x4*)(rope + s * 16 + 4), s0 = *(const f32x4*)(rope + s * 16 + 8), s1 = *(const f32x4*)(rope + s * 16 + 12);
;     const float cs[8] = {c0[0], c0[1], c0[2], c0[3], c1[0], c1[1], c1[2], c1[3]}, sn[8] = {s0[0], s0[1], s0[2], s0[3], s1[0], s1[1], s1[2], s1[3]};
; #pragma unroll
;     for (int e = 0; e < 8; ++e) {
;         const float other = __shfl_xor(v[e], 16);
;         const float a = v[e] * cs[e], bq = other * sn[e];
;         v[e] = (fq == 0) ? (a - bq) : ((fq == 1) ? (a + bq) : v[e]);
;     }
; }
.LBB0_531:
	s_andn2_b64 vcc, exec, s[8:9]
	s_cbranch_vccnz .LBB0_581
	v_and_b32_e32 v11, 64, v183
	v_xor_b32_e32 v10, 16, v183
	v_add_u32_e32 v11, 64, v11
	v_cmp_lt_i32_e32 vcc, v10, v11
	v_lshlrev_b32_e32 v98, 6, v108
	s_nop 0
	v_cndmask_b32_e32 v10, v183, v10, vcc
	v_lshlrev_b32_e32 v109, 2, v10
	global_load_dwordx4 v[102:105], v98, s[68:69]
	global_load_dwordx4 v[10:13], v98, s[68:69] offset:32
	global_load_dwordx4 v[14:17], v98, s[68:69] offset:48
	s_nop 0
	global_load_dwordx4 v[98:101], v98, s[68:69] offset:16
	v_mov_b32_e32 v224, v2
	v_mov_b32_e32 v225, v2
	v_cmp_eq_u32_e64 s[0:1], 1, v1
	s_nop 0
	v_permlane16_swap_b32_e32 v224, v225
	v_cndmask_b32_e64 v110, v225, v224, s[0:1]
	v_cmp_lt_i32_e32 vcc, 0, v1
	s_waitcnt vmcnt(3)
	v_mul_f32_e32 v102, v2, v102
	s_waitcnt vmcnt(2) lgkmcnt(0)
	v_mul_f32_e32 v110, v10, v110
	v_sub_f32_e32 v10, v102, v110
	v_add_f32_e32 v102, v102, v110
	v_cndmask_b32_e64 v102, v2, v102, s[0:1]
	v_cndmask_b32_e32 v10, v10, v102, vcc
	v_mov_b32_e32 v224, v3
	v_mov_b32_e32 v225, v3
	s_nop 1
	v_permlane16_swap_b32_e32 v224, v225
	v_cndmask_b32_e64 v110, v225, v224, s[0:1]
	v_mul_f32_e32 v102, v3, v103
	s_waitcnt lgkmcnt(0)
	v_mul_f32_e32 v103, v11, v110
	v_sub_f32_e32 v11, v102, v103
	v_add_f32_e32 v102, v102, v103
	v_cndmask_b32_e64 v102, v3, v102, s[0:1]
	v_cndmask_b32_e32 v11, v11, v102, vcc
	v_mov_b32_e32 v224, v4
	v_mov_b32_e32 v225, v4
	s_nop 1
	v_permlane16_swap_b32_e32 v224, v225
	v_cndmask_b32_e64 v103, v225, v224, s[0:1]
	v_mul_f32_e32 v102, v4, v104
	s_waitcnt lgkmcnt(0)
	v_mul_f32_e32 v103, v12, v103
	v_sub_f32_e32 v12, v102, v103
	v_add_f32_e32 v102, v102, v103
	v_cndmask_b32_e64 v102, v4, v102, s[0:1]
	v_cndmask_b32_e32 v12, v12, v102, vcc
	v_mov_b32_e32 v224, v5
	v_mov_b32_e32 v225, v5
	s_nop 1
	v_permlane16_swap_b32_e32 v224, v225
	v_cndmask_b32_e64 v103, v225, v224, s[0:1]
	v_mul_f32_e32 v102, v5, v105
	s_waitcnt lgkmcnt(0)
	v_mul_f32_e32 v103, v13, v103
	v_sub_f32_e32 v13, v102, v103
	v_add_f32_e32 v102, v102, v103
	v_cndmask_b32_e64 v102, v5, v102, s[0:1]
	v_cndmask_b32_e32 v13, v13, v102, vcc
	v_mov_b32_e32 v224, v6
	v_mov_b32_e32 v225, v6
	s_nop 1
	v_permlane16_swap_b32_e32 v224, v225
	v_cndmask_b32_e64 v102, v225, v224, s[0:1]
	s_waitcnt vmcnt(0)
	v_mul_f32_e32 v98, v6, v98
	s_waitcnt lgkmcnt(0)
	v_mul_f32_e32 v102, v14, v102
	v_sub_f32_e32 v14, v98, v102
	v_add_f32_e32 v98, v98, v102
	v_cndmask_b32_e64 v98, v6, v98, s[0:1]
	v_cndmask_b32_e32 v14, v14, v98, vcc
	v_mov_b32_e32 v224, v7
	v_mov_b32_e32 v225, v7
	s_nop 1
	v_permlane16_swap_b32_e32 v224, v225
	v_cndmask_b32_e64 v102, v225, v224, s[0:1]
	v_mul_f32_e32 v98, v7, v99
	s_waitcnt lgkmcnt(0)
	v_mul_f32_e32 v99, v15, v102
	v_sub_f32_e32 v15, v98, v99
	v_add_f32_e32 v98, v98, v99
	v_cndmask_b32_e64 v98, v7, v98, s[0:1]
	v_cndmask_b32_e32 v15, v15, v98, vcc
	v_mov_b32_e32 v224, v8
	v_mov_b32_e32 v225, v8
	s_nop 1
	v_permlane16_swap_b32_e32 v224, v225
	v_cndmask_b32_e64 v99, v225, v224, s[0:1]
	v_mul_f32_e32 v98, v8, v100
	s_waitcnt lgkmcnt(0)
	v_mul_f32_e32 v99, v16, v99
	v_sub_f32_e32 v16, v98, v99
	v_add_f32_e32 v98, v98, v99
	v_cndmask_b32_e64 v98, v8, v98, s[0:1]
	v_cndmask_b32_e32 v16, v16, v98, vcc
	v_mov_b32_e32 v224, v9
	v_mov_b32_e32 v225, v9
	s_nop 1
	v_permlane16_swap_b32_e32 v224, v225
	v_cndmask_b32_e64 v99, v225, v224, s[0:1]
	v_mul_f32_e32 v98, v9, v101
	s_waitcnt lgkmcnt(0)
	v_mul_f32_e32 v99, v17, v99
	v_sub_f32_e32 v17, v98, v99
	v_add_f32_e32 v98, v98, v99
	v_cndmask_b32_e64 v98, v9, v98, s[0:1]
	v_cndmask_b32_e32 v17, v17, v98, vcc

; DI void rope8(float (&v)[8], const float* __restrict__ rope, int s, int fq) {
;     const f32x4 c0 = *(const f32x4*)(rope + s * 16), c1 = *(const f32x4*)(rope + s * 16 + 4), s0 = *(const f32x4*)(rope + s * 16 + 8), s1 = *(const f32x4*)(rope + s * 16 + 12);
;     const float cs[8] = {c0[0], c0[1], c0[2], c0[3], c1[0], c1[1], c1[2], c1[3]}, sn[8] = {s0[0], s0[1], s0[2], s0[3], s1[0], s1[1], s1[2], s1[3]};
; #pragma unroll
;     for (int e = 0; e < 8; ++e) {
;         const float other = __shfl_xor(v[e], 16);
;         const float a = v[e] * cs[e], bq = other * sn[e];
;         v[e] = (fq == 0) ? (a - bq) : ((fq == 1) ? (a + bq) : v[e]);
;     }
; }
.LBB0_597:
	s_andn2_b64 vcc, exec, s[8:9]
	s_cbranch_vccnz .LBB0_647
	v_and_b32_e32 v11, 64, v183
	v_xor_b32_e32 v10, 16, v183
	v_add_u32_e32 v11, 64, v11
	v_cmp_lt_i32_e32 vcc, v10, v11
	v_lshlrev_b32_e32 v90, 6, v100
	s_nop 0
	v_cndmask_b32_e32 v10, v183, v10, vcc
	v_lshlrev_b32_e32 v101, 2, v10
	global_load_dwordx4 v[94:97], v90, s[68:69]
	global_load_dwordx4 v[10:13], v90, s[68:69] offset:32
	global_load_dwordx4 v[14:17], v90, s[68:69] offset:48
	s_nop 0
	global_load_dwordx4 v[90:93], v90, s[68:69] offset:16
	v_mov_b32_e32 v224, v2
	v_mov_b32_e32 v225, v2
	v_cmp_eq_u32_e64 s[0:1], 1, v1
	s_nop 0
	v_permlane16_swap_b32_e32 v224, v225
	v_cndmask_b32_e64 v102, v225, v224, s[0:1]
	v_cmp_lt_i32_e32 vcc, 0, v1
	s_waitcnt vmcnt(3)
	v_mul_f32_e32 v94, v2, v94
	s_waitcnt vmcnt(2) lgkmcnt(0)
	v_mul_f32_e32 v102, v10, v102
	v_sub_f32_e32 v10, v94, v102
	v_add_f32_e32 v94, v94, v102
	v_cndmask_b32_e64 v94, v2, v94, s[0:1]
	v_cndmask_b32_e32 v10, v10, v94, vcc
	v_mov_b32_e32 v224, v3
	v_mov_b32_e32 v225, v3
	s_nop 1
	v_permlane16_swap_b32_e32 v224, v225
	v_cndmask_b32_e64 v102, v225, v224, s[0:1]
	v_mul_f32_e32 v94, v3, v95
	s_waitcnt lgkmcnt(0)
	v_mul_f32_e32 v95, v11, v102
	v_sub_f32_e32 v11, v94, v95
	v_add_f32_e32 v94, v94, v95
	v_cndmask_b32_e64 v94, v3, v94, s[0:1]
	v_cndmask_b32_e32 v11, v11, v94, vcc
	v_mov_b32_e32 v224, v4
	v_mov_b32_e32 v225, v4
	s_nop 1
	v_permlane16_swap_b32_e32 v224, v225
	v_cndmask_b32_e64 v95, v225, v224, s[0:1]
	v_mul_f32_e32 v94, v4, v96
	s_waitcnt lgkmcnt(0)
	v_mul_f32_e32 v95, v12, v95
	v_sub_f32_e32 v12, v94, v95
	v_add_f32_e32 v94, v94, v95
	v_cndmask_b32_e64 v94, v4, v94, s[0:1]
	v_cndmask_b32_e32 v12, v12, v94, vcc
	v_mov_b32_e32 v224, v5
	v_mov_b32_e32 v225, v5
	s_nop 1
	v_permlane16_swap_b32_e32 v224, v225
	v_cndmask_b32_e64 v95, v225, v224, s[0:1]
	v_mul_f32_e32 v94, v5, v97
	s_waitcnt lgkmcnt(0)
	v_mul_f32_e32 v95, v13, v95
	v_sub_f32_e32 v13, v94, v95
	v_add_f32_e32 v94, v94, v95
	v_cndmask_b32_e64 v94, v5, v94, s[0:1]
	v_cndmask_b32_e32 v13, v13, v94, vcc
	v_mov_b32_e32 v224, v6
	v_mov_b32_e32 v225, v6
	s_nop 1
	v_permlane16_swap_b32_e32 v224, v225
	v_cndmask_b32_e64 v94, v225, v224, s[0:1]
	s_waitcnt vmcnt(0)
	v_mul_f32_e32 v90, v6, v90
	s_waitcnt lgkmcnt(0)
	v_mul_f32_e32 v94, v14, v94
	v_sub_f32_e32 v14, v90, v94
	v_add_f32_e32 v90, v90, v94
	v_cndmask_b32_e64 v90, v6, v90, s[0:1]
	v_cndmask_b32_e32 v14, v14, v90, vcc
	v_mov_b32_e32 v224, v7
	v_mov_b32_e32 v225, v7
	s_nop 1
	v_permlane16_swap_b32_e32 v224, v225
	v_cndmask_b32_e64 v94, v225, v224, s[0:1]
	v_mul_f32_e32 v90, v7, v91
	s_waitcnt lgkmcnt(0)
	v_mul_f32_e32 v91, v15, v94
	v_sub_f32_e32 v15, v90, v91
	v_add_f32_e32 v90, v90, v91
	v_cndmask_b32_e64 v90, v7, v90, s[0:1]
	v_cndmask_b32_e32 v15, v15, v90, vcc
	v_mov_b32_e32 v224, v8
	v_mov_b32_e32 v225, v8
	s_nop 1
	v_permlane16_swap_b32_e32 v224, v225
	v_cndmask_b32_e64 v91, v225, v224, s[0:1]
	v_mul_f32_e32 v90, v8, v92
	s_waitcnt lgkmcnt(0)
	v_mul_f32_e32 v91, v16, v91
	v_sub_f32_e32 v16, v90, v91
	v_add_f32_e32 v90, v90, v91
	v_cndmask_b32_e64 v90, v8, v90, s[0:1]
	v_cndmask_b32_e32 v16, v16, v90, vcc
	v_mov_b32_e32 v224, v9
	v_mov_b32_e32 v225, v9
	s_nop 1
	v_permlane16_swap_b32_e32 v224, v225
	v_cndmask_b32_e64 v91, v225, v224, s[0:1]
	v_mul_f32_e32 v90, v9, v93
	s_waitcnt lgkmcnt(0)
	v_mul_f32_e32 v91, v17, v91
	v_sub_f32_e32 v17, v90, v91
	v_add_f32_e32 v90, v90, v91
	v_cndmask_b32_e64 v90, v9, v90, s[0:1]
	v_cndmask_b32_e32 v17, v17, v90, vcc

; DI void rope8(float (&v)[8], const float* __restrict__ rope, int s, int fq) {
;     const f32x4 c0 = *(const f32x4*)(rope + s * 16), c1 = *(const f32x4*)(rope + s * 16 + 4), s0 = *(const f32x4*)(rope + s * 16 + 8), s1 = *(const f32x4*)(rope + s * 16 + 12);
;     const float cs[8] = {c0[0], c0[1], c0[2], c0[3], c1[0], c1[1], c1[2], c1[3]}, sn[8] = {s0[0], s0[1], s0[2], s0[3], s1[0], s1[1], s1[2], s1[3]};
; #pragma unroll
;     for (int e = 0; e < 8; ++e) {
;         const float other = __shfl_xor(v[e], 16);
;         const float a = v[e] * cs[e], bq = other * sn[e];
;         v[e] = (fq == 0) ? (a - bq) : ((fq == 1) ? (a + bq) : v[e]);
;     }
; }
.LBB0_667:
	s_andn2_b64 vcc, exec, s[8:9]
	s_cbranch_vccnz .LBB0_717
	v_and_b32_e32 v11, 64, v183
	v_xor_b32_e32 v10, 16, v183
	v_add_u32_e32 v11, 64, v11
	v_cmp_lt_i32_e32 vcc, v10, v11
	v_lshlrev_b32_e32 v74, 6, v83
	s_nop 0
	v_cndmask_b32_e32 v10, v183, v10, vcc
	v_lshlrev_b32_e32 v86, 2, v10
	global_load_dwordx4 v[78:81], v74, s[68:69]
	global_load_dwordx4 v[10:13], v74, s[68:69] offset:32
	global_load_dwordx4 v[14:17], v74, s[68:69] offset:48
	s_nop 0
	global_load_dwordx4 v[74:77], v74, s[68:69] offset:16
	v_mov_b32_e32 v224, v2
	v_mov_b32_e32 v225, v2
	v_cmp_eq_u32_e64 s[0:1], 1, v1
	s_nop 0
	v_permlane16_swap_b32_e32 v224, v225
	v_cndmask_b32_e64 v87, v225, v224, s[0:1]
	v_cmp_lt_i32_e32 vcc, 0, v1
	s_waitcnt vmcnt(3)
	v_mul_f32_e32 v78, v2, v78
	s_waitcnt vmcnt(2) lgkmcnt(0)
	v_mul_f32_e32 v87, v10, v87
	v_sub_f32_e32 v10, v78, v87
	v_add_f32_e32 v78, v78, v87
	v_cndmask_b32_e64 v78, v2, v78, s[0:1]
	v_cndmask_b32_e32 v10, v10, v78, vcc
	v_mov_b32_e32 v224, v3
	v_mov_b32_e32 v225, v3
	s_nop 1
	v_permlane16_swap_b32_e32 v224, v225
	v_cndmask_b32_e64 v87, v225, v224, s[0:1]
	v_mul_f32_e32 v78, v3, v79
	s_waitcnt lgkmcnt(0)
	v_mul_f32_e32 v79, v11, v87
	v_sub_f32_e32 v11, v78, v79
	v_add_f32_e32 v78, v78, v79
	v_cndmask_b32_e64 v78, v3, v78, s[0:1]
	v_cndmask_b32_e32 v11, v11, v78, vcc
	v_mov_b32_e32 v224, v4
	v_mov_b32_e32 v225, v4
	s_nop 1
	v_permlane16_swap_b32_e32 v224, v225
	v_cndmask_b32_e64 v79, v225, v224, s[0:1]
	v_mul_f32_e32 v78, v4, v80
	s_waitcnt lgkmcnt(0)
	v_mul_f32_e32 v79, v12, v79
	v_sub_f32_e32 v12, v78, v79
	v_add_f32_e32 v78, v78, v79
	v_cndmask_b32_e64 v78, v4, v78, s[0:1]
	v_cndmask_b32_e32 v12, v12, v78, vcc
	v_mov_b32_e32 v224, v5
	v_mov_b32_e32 v225, v5
	s_nop 1
	v_permlane16_swap_b32_e32 v224, v225
	v_cndmask_b32_e64 v79, v225, v224, s[0:1]
	v_mul_f32_e32 v78, v5, v81
	s_waitcnt lgkmcnt(0)
	v_mul_f32_e32 v79, v13, v79
	v_sub_f32_e32 v13, v78, v79
	v_add_f32_e32 v78, v78, v79
	v_cndmask_b32_e64 v78, v5, v78, s[0:1]
	v_cndmask_b32_e32 v13, v13, v78, vcc
	v_mov_b32_e32 v224, v6
	v_mov_b32_e32 v225, v6
	s_nop 1
	v_permlane16_swap_b32_e32 v224, v225
	v_cndmask_b32_e64 v78, v225, v224, s[0:1]
	s_waitcnt vmcnt(0)
	v_mul_f32_e32 v74, v6, v74
	s_waitcnt lgkmcnt(0)
	v_mul_f32_e32 v78, v14, v78
	v_sub_f32_e32 v14, v74, v78
	v_add_f32_e32 v74, v74, v78
	v_cndmask_b32_e64 v74, v6, v74, s[0:1]
	v_cndmask_b32_e32 v14, v14, v74, vcc
	v_mov_b32_e32 v224, v7
	v_mov_b32_e32 v225, v7
	s_nop 1
	v_permlane16_swap_b32_e32 v224, v225
	v_cndmask_b32_e64 v78, v225, v224, s[0:1]
	v_mul_f32_e32 v74, v7, v75
	s_waitcnt lgkmcnt(0)
	v_mul_f32_e32 v75, v15, v78
	v_sub_f32_e32 v15, v74, v75
	v_add_f32_e32 v74, v74, v75
	v_cndmask_b32_e64 v74, v7, v74, s[0:1]
	v_cndmask_b32_e32 v15, v15, v74, vcc
	v_mov_b32_e32 v224, v8
	v_mov_b32_e32 v225, v8
	s_nop 1
	v_permlane16_swap_b32_e32 v224, v225
	v_cndmask_b32_e64 v75, v225, v224, s[0:1]
	v_mul_f32_e32 v74, v8, v76
	s_waitcnt lgkmcnt(0)
	v_mul_f32_e32 v75, v16, v75
	v_sub_f32_e32 v16, v74, v75
	v_add_f32_e32 v74, v74, v75
	v_cndmask_b32_e64 v74, v8, v74, s[0:1]
	v_cndmask_b32_e32 v16, v16, v74, vcc
	v_mov_b32_e32 v224, v9
	v_mov_b32_e32 v225, v9
	s_nop 1
	v_permlane16_swap_b32_e32 v224, v225
	v_cndmask_b32_e64 v75, v225, v224, s[0:1]
	v_mul_f32_e32 v74, v9, v77
	s_waitcnt lgkmcnt(0)
	v_mul_f32_e32 v75, v17, v75
	v_sub_f32_e32 v17, v74, v75
	v_add_f32_e32 v74, v74, v75
	v_cndmask_b32_e64 v74, v9, v74, s[0:1]
	v_cndmask_b32_e32 v17, v17, v74, vcc

; DI void rope8(float (&v)[8], const float* __restrict__ rope, int s, int fq) {
;     const f32x4 c0 = *(const f32x4*)(rope + s * 16), c1 = *(const f32x4*)(rope + s * 16 + 4), s0 = *(const f32x4*)(rope + s * 16 + 8), s1 = *(const f32x4*)(rope + s * 16 + 12);
;     const float cs[8] = {c0[0], c0[1], c0[2], c0[3], c1[0], c1[1], c1[2], c1[3]}, sn[8] = {s0[0], s0[1], s0[2], s0[3], s1[0], s1[1], s1[2], s1[3]};
; #pragma unroll
;     for (int e = 0; e < 8; ++e) {
;         const float other = __shfl_xor(v[e], 16);
;         const float a = v[e] * cs[e], bq = other * sn[e];
;         v[e] = (fq == 0) ? (a - bq) : ((fq == 1) ? (a + bq) : v[e]);
;     }
; }
.LBB0_727:
	s_andn2_b64 vcc, exec, s[8:9]
	s_cbranch_vccnz .LBB0_777
	v_and_b32_e32 v11, 64, v183
	v_xor_b32_e32 v10, 16, v183
	v_add_u32_e32 v11, 64, v11
	v_cmp_lt_i32_e32 vcc, v10, v11
	v_lshlrev_b32_e32 v66, 6, v77
	s_nop 0
	v_cndmask_b32_e32 v10, v183, v10, vcc
	v_lshlrev_b32_e32 v79, 2, v10
	global_load_dwordx4 v[70:73], v66, s[68:69]
	global_load_dwordx4 v[10:13], v66, s[68:69] offset:32
	global_load_dwordx4 v[14:17], v66, s[68:69] offset:48
	s_nop 0
	global_load_dwordx4 v[66:69], v66, s[68:69] offset:16
	v_mov_b32_e32 v224, v2
	v_mov_b32_e32 v225, v2
	v_cmp_eq_u32_e64 s[0:1], 1, v1
	s_nop 0
	v_permlane16_swap_b32_e32 v224, v225
	v_cndmask_b32_e64 v80, v225, v224, s[0:1]
	v_cmp_lt_i32_e32 vcc, 0, v1
	s_waitcnt vmcnt(3)
	v_mul_f32_e32 v70, v2, v70
	s_waitcnt vmcnt(2) lgkmcnt(0)
	v_mul_f32_e32 v80, v10, v80
	v_sub_f32_e32 v10, v70, v80
	v_add_f32_e32 v70, v70, v80
	v_cndmask_b32_e64 v70, v2, v70, s[0:1]
	v_cndmask_b32_e32 v10, v10, v70, vcc
	v_mov_b32_e32 v224, v3
	v_mov_b32_e32 v225, v3
	s_nop 1
	v_permlane16_swap_b32_e32 v224, v225
	v_cndmask_b32_e64 v80, v225, v224, s[0:1]
	v_mul_f32_e32 v70, v3, v71
	s_waitcnt lgkmcnt(0)
	v_mul_f32_e32 v71, v11, v80
	v_sub_f32_e32 v11, v70, v71
	v_add_f32_e32 v70, v70, v71
	v_cndmask_b32_e64 v70, v3, v70, s[0:1]
	v_cndmask_b32_e32 v11, v11, v70, vcc
	v_mov_b32_e32 v224, v4
	v_mov_b32_e32 v225, v4
	s_nop 1
	v_permlane16_swap_b32_e32 v224, v225
	v_cndmask_b32_e64 v71, v225, v224, s[0:1]
	v_mul_f32_e32 v70, v4, v72
	s_waitcnt lgkmcnt(0)
	v_mul_f32_e32 v71, v12, v71
	v_sub_f32_e32 v12, v70, v71
	v_add_f32_e32 v70, v70, v71
	v_cndmask_b32_e64 v70, v4, v70, s[0:1]
	v_cndmask_b32_e32 v12, v12, v70, vcc
	v_mov_b32_e32 v224, v5
	v_mov_b32_e32 v225, v5
	s_nop 1
	v_permlane16_swap_b32_e32 v224, v225
	v_cndmask_b32_e64 v71, v225, v224, s[0:1]
	v_mul_f32_e32 v70, v5, v73
	s_waitcnt lgkmcnt(0)
	v_mul_f32_e32 v71, v13, v71
	v_sub_f32_e32 v13, v70, v71
	v_add_f32_e32 v70, v70, v71
	v_cndmask_b32_e64 v70, v5, v70, s[0:1]
	v_cndmask_b32_e32 v13, v13, v70, vcc
	v_mov_b32_e32 v224, v6
	v_mov_b32_e32 v225, v6
	s_nop 1
	v_permlane16_swap_b32_e32 v224, v225
	v_cndmask_b32_e64 v70, v225, v224, s[0:1]
	s_waitcnt vmcnt(0)
	v_mul_f32_e32 v66, v6, v66
	s_waitcnt lgkmcnt(0)
	v_mul_f32_e32 v70, v14, v70
	v_sub_f32_e32 v14, v66, v70
	v_add_f32_e32 v66, v66, v70
	v_cndmask_b32_e64 v66, v6, v66, s[0:1]
	v_cndmask_b32_e32 v14, v14, v66, vcc
	v_mov_b32_e32 v224, v7
	v_mov_b32_e32 v225, v7
	s_nop 1
	v_permlane16_swap_b32_e32 v224, v225
	v_cndmask_b32_e64 v70, v225, v224, s[0:1]
	v_mul_f32_e32 v66, v7, v67
	s_waitcnt lgkmcnt(0)
	v_mul_f32_e32 v67, v15, v70
	v_sub_f32_e32 v15, v66, v67
	v_add_f32_e32 v66, v66, v67
	v_cndmask_b32_e64 v66, v7, v66, s[0:1]
	v_cndmask_b32_e32 v15, v15, v66, vcc
	v_mov_b32_e32 v224, v8
	v_mov_b32_e32 v225, v8
	s_nop 1
	v_permlane16_swap_b32_e32 v224, v225
	v_cndmask_b32_e64 v67, v225, v224, s[0:1]
	v_mul_f32_e32 v66, v8, v68
	s_waitcnt lgkmcnt(0)
	v_mul_f32_e32 v67, v16, v67
	v_sub_f32_e32 v16, v66, v67
	v_add_f32_e32 v66, v66, v67
	v_cndmask_b32_e64 v66, v8, v66, s[0:1]
	v_cndmask_b32_e32 v16, v16, v66, vcc
	v_mov_b32_e32 v224, v9
	v_mov_b32_e32 v225, v9
	s_nop 1
	v_permlane16_swap_b32_e32 v224, v225
	v_cndmask_b32_e64 v67, v225, v224, s[0:1]
	v_mul_f32_e32 v66, v9, v69
	s_waitcnt lgkmcnt(0)
	v_mul_f32_e32 v67, v17, v67
	v_sub_f32_e32 v17, v66, v67
	v_add_f32_e32 v66, v66, v67
	v_cndmask_b32_e64 v66, v9, v66, s[0:1]
	v_cndmask_b32_e32 v17, v17, v66, vcc

; DI void rope8(float (&v)[8], const float* __restrict__ rope, int s, int fq) {
;     const f32x4 c0 = *(const f32x4*)(rope + s * 16), c1 = *(const f32x4*)(rope + s * 16 + 4), s0 = *(const f32x4*)(rope + s * 16 + 8), s1 = *(const f32x4*)(rope + s * 16 + 12);
;     const float cs[8] = {c0[0], c0[1], c0[2], c0[3], c1[0], c1[1], c1[2], c1[3]}, sn[8] = {s0[0], s0[1], s0[2], s0[3], s1[0], s1[1], s1[2], s1[3]};
; #pragma unroll
;     for (int e = 0; e < 8; ++e) {
;         const float other = __shfl_xor(v[e], 16);
;         const float a = v[e] * cs[e], bq = other * sn[e];
;         v[e] = (fq == 0) ? (a - bq) : ((fq == 1) ? (a + bq) : v[e]);
;     }
; }
.LBB0_787:
	s_andn2_b64 vcc, exec, s[8:9]
	s_cbranch_vccnz .LBB0_837
	v_and_b32_e32 v11, 64, v183
	v_xor_b32_e32 v10, 16, v183
	v_add_u32_e32 v11, 64, v11
	v_cmp_lt_i32_e32 vcc, v10, v11
	v_lshlrev_b32_e32 v58, 6, v67
	s_nop 0
	v_cndmask_b32_e32 v10, v183, v10, vcc
	v_lshlrev_b32_e32 v68, 2, v10
	global_load_dwordx4 v[62:65], v58, s[68:69]
	global_load_dwordx4 v[10:13], v58, s[68:69] offset:32
	global_load_dwordx4 v[14:17], v58, s[68:69] offset:48
	s_nop 0
	global_load_dwordx4 v[58:61], v58, s[68:69] offset:16
	v_mov_b32_e32 v224, v2
	v_mov_b32_e32 v225, v2
	v_cmp_eq_u32_e64 s[0:1], 1, v1
	s_nop 0
	v_permlane16_swap_b32_e32 v224, v225
	v_cndmask_b32_e64 v69, v225, v224, s[0:1]
	v_cmp_lt_i32_e32 vcc, 0, v1
	s_waitcnt vmcnt(3)
	v_mul_f32_e32 v62, v2, v62
	s_waitcnt vmcnt(2) lgkmcnt(0)
	v_mul_f32_e32 v69, v10, v69
	v_sub_f32_e32 v10, v62, v69
	v_add_f32_e32 v62, v62, v69
	v_cndmask_b32_e64 v62, v2, v62, s[0:1]
	v_cndmask_b32_e32 v10, v10, v62, vcc
	v_mov_b32_e32 v224, v3
	v_mov_b32_e32 v225, v3
	s_nop 1
	v_permlane16_swap_b32_e32 v224, v225
	v_cndmask_b32_e64 v69, v225, v224, s[0:1]
	v_mul_f32_e32 v62, v3, v63
	s_waitcnt lgkmcnt(0)
	v_mul_f32_e32 v63, v11, v69
	v_sub_f32_e32 v11, v62, v63
	v_add_f32_e32 v62, v62, v63
	v_cndmask_b32_e64 v62, v3, v62, s[0:1]
	v_cndmask_b32_e32 v11, v11, v62, vcc
	v_mov_b32_e32 v224, v4
	v_mov_b32_e32 v225, v4
	s_nop 1
	v_permlane16_swap_b32_e32 v224, v225
	v_cndmask_b32_e64 v63, v225, v224, s[0:1]
	v_mul_f32_e32 v62, v4, v64
	s_waitcnt lgkmcnt(0)
	v_mul_f32_e32 v63, v12, v63
	v_sub_f32_e32 v12, v62, v63
	v_add_f32_e32 v62, v62, v63
	v_cndmask_b32_e64 v62, v4, v62, s[0:1]
	v_cndmask_b32_e32 v12, v12, v62, vcc
	v_mov_b32_e32 v224, v5
	v_mov_b32_e32 v225, v5
	s_nop 1
	v_permlane16_swap_b32_e32 v224, v225
	v_cndmask_b32_e64 v63, v225, v224, s[0:1]
	v_mul_f32_e32 v62, v5, v65
	s_waitcnt lgkmcnt(0)
	v_mul_f32_e32 v63, v13, v63
	v_sub_f32_e32 v13, v62, v63
	v_add_f32_e32 v62, v62, v63
	v_cndmask_b32_e64 v62, v5, v62, s[0:1]
	v_cndmask_b32_e32 v13, v13, v62, vcc
	v_mov_b32_e32 v224, v6
	v_mov_b32_e32 v225, v6
	s_nop 1
	v_permlane16_swap_b32_e32 v224, v225
	v_cndmask_b32_e64 v62, v225, v224, s[0:1]
	s_waitcnt vmcnt(0)
	v_mul_f32_e32 v58, v6, v58
	s_waitcnt lgkmcnt(0)
	v_mul_f32_e32 v62, v14, v62
	v_sub_f32_e32 v14, v58, v62
	v_add_f32_e32 v58, v58, v62
	v_cndmask_b32_e64 v58, v6, v58, s[0:1]
	v_cndmask_b32_e32 v14, v14, v58, vcc
	v_mov_b32_e32 v224, v7
	v_mov_b32_e32 v225, v7
	s_nop 1
	v_permlane16_swap_b32_e32 v224, v225
	v_cndmask_b32_e64 v62, v225, v224, s[0:1]
	v_mul_f32_e32 v58, v7, v59
	s_waitcnt lgkmcnt(0)
	v_mul_f32_e32 v59, v15, v62
	v_sub_f32_e32 v15, v58, v59
	v_add_f32_e32 v58, v58, v59
	v_cndmask_b32_e64 v58, v7, v58, s[0:1]
	v_cndmask_b32_e32 v15, v15, v58, vcc
	v_mov_b32_e32 v224, v8
	v_mov_b32_e32 v225, v8
	s_nop 1
	v_permlane16_swap_b32_e32 v224, v225
	v_cndmask_b32_e64 v59, v225, v224, s[0:1]
	v_mul_f32_e32 v58, v8, v60
	s_waitcnt lgkmcnt(0)
	v_mul_f32_e32 v59, v16, v59
	v_sub_f32_e32 v16, v58, v59
	v_add_f32_e32 v58, v58, v59
	v_cndmask_b32_e64 v58, v8, v58, s[0:1]
	v_cndmask_b32_e32 v16, v16, v58, vcc
	v_mov_b32_e32 v224, v9
	v_mov_b32_e32 v225, v9
	s_nop 1
	v_permlane16_swap_b32_e32 v224, v225
	v_cndmask_b32_e64 v59, v225, v224, s[0:1]
	v_mul_f32_e32 v58, v9, v61
	s_waitcnt lgkmcnt(0)
	v_mul_f32_e32 v59, v17, v59
	v_sub_f32_e32 v17, v58, v59
	v_add_f32_e32 v58, v58, v59
	v_cndmask_b32_e64 v58, v9, v58, s[0:1]
	v_cndmask_b32_e32 v17, v17, v58, vcc

; DI void rope8(float (&v)[8], const float* __restrict__ rope, int s, int fq) {
;     const f32x4 c0 = *(const f32x4*)(rope + s * 16), c1 = *(const f32x4*)(rope + s * 16 + 4), s0 = *(const f32x4*)(rope + s * 16 + 8), s1 = *(const f32x4*)(rope + s * 16 + 12);
;     const float cs[8] = {c0[0], c0[1], c0[2], c0[3], c1[0], c1[1], c1[2], c1[3]}, sn[8] = {s0[0], s0[1], s0[2], s0[3], s1[0], s1[1], s1[2], s1[3]};
; #pragma unroll
;     for (int e = 0; e < 8; ++e) {
;         const float other = __shfl_xor(v[e], 16);
;         const float a = v[e] * cs[e], bq = other * sn[e];
;         v[e] = (fq == 0) ? (a - bq) : ((fq == 1) ? (a + bq) : v[e]);
;     }
; }
.LBB0_847:
	s_andn2_b64 vcc, exec, s[8:9]
	s_cbranch_vccnz .LBB0_897
	v_and_b32_e32 v11, 64, v183
	v_xor_b32_e32 v10, 16, v183
	v_add_u32_e32 v11, 64, v11
	v_cmp_lt_i32_e32 vcc, v10, v11
	v_lshlrev_b32_e32 v50, 6, v59
	s_nop 0
	v_cndmask_b32_e32 v10, v183, v10, vcc
	v_lshlrev_b32_e32 v60, 2, v10
	global_load_dwordx4 v[54:57], v50, s[68:69]
	global_load_dwordx4 v[10:13], v50, s[68:69] offset:32
	global_load_dwordx4 v[14:17], v50, s[68:69] offset:48
	s_nop 0
	global_load_dwordx4 v[50:53], v50, s[68:69] offset:16
	v_mov_b32_e32 v224, v2
	v_mov_b32_e32 v225, v2
	v_cmp_eq_u32_e64 s[0:1], 1, v1
	s_nop 0
	v_permlane16_swap_b32_e32 v224, v225
	v_cndmask_b32_e64 v61, v225, v224, s[0:1]
	v_cmp_lt_i32_e32 vcc, 0, v1
	s_waitcnt vmcnt(3)
	v_mul_f32_e32 v54, v2, v54
	s_waitcnt vmcnt(2) lgkmcnt(0)
	v_mul_f32_e32 v61, v10, v61
	v_sub_f32_e32 v10, v54, v61
	v_add_f32_e32 v54, v54, v61
	v_cndmask_b32_e64 v54, v2, v54, s[0:1]
	v_cndmask_b32_e32 v10, v10, v54, vcc
	v_mov_b32_e32 v224, v3
	v_mov_b32_e32 v225, v3
	s_nop 1
	v_permlane16_swap_b32_e32 v224, v225
	v_cndmask_b32_e64 v61, v225, v224, s[0:1]
	v_mul_f32_e32 v54, v3, v55
	s_waitcnt lgkmcnt(0)
	v_mul_f32_e32 v55, v11, v61
	v_sub_f32_e32 v11, v54, v55
	v_add_f32_e32 v54, v54, v55
	v_cndmask_b32_e64 v54, v3, v54, s[0:1]
	v_cndmask_b32_e32 v11, v11, v54, vcc
	v_mov_b32_e32 v224, v4
	v_mov_b32_e32 v225, v4
	s_nop 1
	v_permlane16_swap_b32_e32 v224, v225
	v_cndmask_b32_e64 v55, v225, v224, s[0:1]
	v_mul_f32_e32 v54, v4, v56
	s_waitcnt lgkmcnt(0)
	v_mul_f32_e32 v55, v12, v55
	v_sub_f32_e32 v12, v54, v55
	v_add_f32_e32 v54, v54, v55
	v_cndmask_b32_e64 v54, v4, v54, s[0:1]
	v_cndmask_b32_e32 v12, v12, v54, vcc
	v_mov_b32_e32 v224, v5
	v_mov_b32_e32 v225, v5
	s_nop 1
	v_permlane16_swap_b32_e32 v224, v225
	v_cndmask_b32_e64 v55, v225, v224, s[0:1]
	v_mul_f32_e32 v54, v5, v57
	s_waitcnt lgkmcnt(0)
	v_mul_f32_e32 v55, v13, v55
	v_sub_f32_e32 v13, v54, v55
	v_add_f32_e32 v54, v54, v55
	v_cndmask_b32_e64 v54, v5, v54, s[0:1]
	v_cndmask_b32_e32 v13, v13, v54, vcc
	v_mov_b32_e32 v224, v6
	v_mov_b32_e32 v225, v6
	s_nop 1
	v_permlane16_swap_b32_e32 v224, v225
	v_cndmask_b32_e64 v54, v225, v224, s[0:1]
	s_waitcnt vmcnt(0)
	v_mul_f32_e32 v50, v6, v50
	s_waitcnt lgkmcnt(0)
	v_mul_f32_e32 v54, v14, v54
	v_sub_f32_e32 v14, v50, v54
	v_add_f32_e32 v50, v50, v54
	v_cndmask_b32_e64 v50, v6, v50, s[0:1]
	v_cndmask_b32_e32 v14, v14, v50, vcc
	v_mov_b32_e32 v224, v7
	v_mov_b32_e32 v225, v7
	s_nop 1
	v_permlane16_swap_b32_e32 v224, v225
	v_cndmask_b32_e64 v54, v225, v224, s[0:1]
	v_mul_f32_e32 v50, v7, v51
	s_waitcnt lgkmcnt(0)
	v_mul_f32_e32 v51, v15, v54
	v_sub_f32_e32 v15, v50, v51
	v_add_f32_e32 v50, v50, v51
	v_cndmask_b32_e64 v50, v7, v50, s[0:1]
	v_cndmask_b32_e32 v15, v15, v50, vcc
	v_mov_b32_e32 v224, v8
	v_mov_b32_e32 v225, v8
	s_nop 1
	v_permlane16_swap_b32_e32 v224, v225
	v_cndmask_b32_e64 v51, v225, v224, s[0:1]
	v_mul_f32_e32 v50, v8, v52
	s_waitcnt lgkmcnt(0)
	v_mul_f32_e32 v51, v16, v51
	v_sub_f32_e32 v16, v50, v51
	v_add_f32_e32 v50, v50, v51
	v_cndmask_b32_e64 v50, v8, v50, s[0:1]
	v_cndmask_b32_e32 v16, v16, v50, vcc
	v_mov_b32_e32 v224, v9
	v_mov_b32_e32 v225, v9
	s_nop 1
	v_permlane16_swap_b32_e32 v224, v225
	v_cndmask_b32_e64 v51, v225, v224, s[0:1]
	v_mul_f32_e32 v50, v9, v53
	s_waitcnt lgkmcnt(0)
	v_mul_f32_e32 v51, v17, v51
	v_sub_f32_e32 v17, v50, v51
	v_add_f32_e32 v50, v50, v51
	v_cndmask_b32_e64 v50, v9, v50, s[0:1]
	v_cndmask_b32_e32 v17, v17, v50, vcc

; DI void rope8(float (&v)[8], const float* __restrict__ rope, int s, int fq) {
;     const f32x4 c0 = *(const f32x4*)(rope + s * 16), c1 = *(const f32x4*)(rope + s * 16 + 4), s0 = *(const f32x4*)(rope + s * 16 + 8), s1 = *(const f32x4*)(rope + s * 16 + 12);
;     const float cs[8] = {c0[0], c0[1], c0[2], c0[3], c1[0], c1[1], c1[2], c1[3]}, sn[8] = {s0[0], s0[1], s0[2], s0[3], s1[0], s1[1], s1[2], s1[3]};
; #pragma unroll
;     for (int e = 0; e < 8; ++e) {
;         const float other = __shfl_xor(v[e], 16);
;         const float a = v[e] * cs[e], bq = other * sn[e];
;         v[e] = (fq == 0) ? (a - bq) : ((fq == 1) ? (a + bq) : v[e]);
;     }
; }
.LBB0_907:
	s_andn2_b64 vcc, exec, s[8:9]
	s_cbranch_vccnz .LBB0_957
	v_and_b32_e32 v11, 64, v183
	v_xor_b32_e32 v10, 16, v183
	v_add_u32_e32 v11, 64, v11
	v_cmp_lt_i32_e32 vcc, v10, v11
	v_lshlrev_b32_e32 v42, 6, v51
	s_nop 0
	v_cndmask_b32_e32 v10, v183, v10, vcc
	v_lshlrev_b32_e32 v52, 2, v10
	global_load_dwordx4 v[46:49], v42, s[68:69]
	global_load_dwordx4 v[10:13], v42, s[68:69] offset:32
	global_load_dwordx4 v[14:17], v42, s[68:69] offset:48
	s_nop 0
	global_load_dwordx4 v[42:45], v42, s[68:69] offset:16
	v_mov_b32_e32 v224, v2
	v_mov_b32_e32 v225, v2
	v_cmp_eq_u32_e64 s[0:1], 1, v1
	s_nop 0
	v_permlane16_swap_b32_e32 v224, v225
	v_cndmask_b32_e64 v53, v225, v224, s[0:1]
	v_cmp_lt_i32_e32 vcc, 0, v1
	s_waitcnt vmcnt(3)
	v_mul_f32_e32 v46, v2, v46
	s_waitcnt vmcnt(2) lgkmcnt(0)
	v_mul_f32_e32 v53, v10, v53
	v_sub_f32_e32 v10, v46, v53
	v_add_f32_e32 v46, v46, v53
	v_cndmask_b32_e64 v46, v2, v46, s[0:1]
	v_cndmask_b32_e32 v10, v10, v46, vcc
	v_mov_b32_e32 v224, v3
	v_mov_b32_e32 v225, v3
	s_nop 1
	v_permlane16_swap_b32_e32 v224, v225
	v_cndmask_b32_e64 v53, v225, v224, s[0:1]
	v_mul_f32_e32 v46, v3, v47
	s_waitcnt lgkmcnt(0)
	v_mul_f32_e32 v47, v11, v53
	v_sub_f32_e32 v11, v46, v47
	v_add_f32_e32 v46, v46, v47
	v_cndmask_b32_e64 v46, v3, v46, s[0:1]
	v_cndmask_b32_e32 v11, v11, v46, vcc
	v_mov_b32_e32 v224, v4
	v_mov_b32_e32 v225, v4
	s_nop 1
	v_permlane16_swap_b32_e32 v224, v225
	v_cndmask_b32_e64 v47, v225, v224, s[0:1]
	v_mul_f32_e32 v46, v4, v48
	s_waitcnt lgkmcnt(0)
	v_mul_f32_e32 v47, v12, v47
	v_sub_f32_e32 v12, v46, v47
	v_add_f32_e32 v46, v46, v47
	v_cndmask_b32_e64 v46, v4, v46, s[0:1]
	v_cndmask_b32_e32 v12, v12, v46, vcc
	v_mov_b32_e32 v224, v5
	v_mov_b32_e32 v225, v5
	s_nop 1
	v_permlane16_swap_b32_e32 v224, v225
	v_cndmask_b32_e64 v47, v225, v224, s[0:1]
	v_mul_f32_e32 v46, v5, v49
	s_waitcnt lgkmcnt(0)
	v_mul_f32_e32 v47, v13, v47
	v_sub_f32_e32 v13, v46, v47
	v_add_f32_e32 v46, v46, v47
	v_cndmask_b32_e64 v46, v5, v46, s[0:1]
	v_cndmask_b32_e32 v13, v13, v46, vcc
	v_mov_b32_e32 v224, v6
	v_mov_b32_e32 v225, v6
	s_nop 1
	v_permlane16_swap_b32_e32 v224, v225
	v_cndmask_b32_e64 v46, v225, v224, s[0:1]
	s_waitcnt vmcnt(0)
	v_mul_f32_e32 v42, v6, v42
	s_waitcnt lgkmcnt(0)
	v_mul_f32_e32 v46, v14, v46
	v_sub_f32_e32 v14, v42, v46
	v_add_f32_e32 v42, v42, v46
	v_cndmask_b32_e64 v42, v6, v42, s[0:1]
	v_cndmask_b32_e32 v14, v14, v42, vcc
	v_mov_b32_e32 v224, v7
	v_mov_b32_e32 v225, v7
	s_nop 1
	v_permlane16_swap_b32_e32 v224, v225
	v_cndmask_b32_e64 v46, v225, v224, s[0:1]
	v_mul_f32_e32 v42, v7, v43
	s_waitcnt lgkmcnt(0)
	v_mul_f32_e32 v43, v15, v46
	v_sub_f32_e32 v15, v42, v43
	v_add_f32_e32 v42, v42, v43
	v_cndmask_b32_e64 v42, v7, v42, s[0:1]
	v_cndmask_b32_e32 v15, v15, v42, vcc
	v_mov_b32_e32 v224, v8
	v_mov_b32_e32 v225, v8
	s_nop 1
	v_permlane16_swap_b32_e32 v224, v225
	v_cndmask_b32_e64 v43, v225, v224, s[0:1]
	v_mul_f32_e32 v42, v8, v44
	s_waitcnt lgkmcnt(0)
	v_mul_f32_e32 v43, v16, v43
	v_sub_f32_e32 v16, v42, v43
	v_add_f32_e32 v42, v42, v43
	v_cndmask_b32_e64 v42, v8, v42, s[0:1]
	v_cndmask_b32_e32 v16, v16, v42, vcc
	v_mov_b32_e32 v224, v9
	v_mov_b32_e32 v225, v9
	s_nop 1
	v_permlane16_swap_b32_e32 v224, v225
	v_cndmask_b32_e64 v43, v225, v224, s[0:1]
	v_mul_f32_e32 v42, v9, v45
	s_waitcnt lgkmcnt(0)
	v_mul_f32_e32 v43, v17, v43
	v_sub_f32_e32 v17, v42, v43
	v_add_f32_e32 v42, v42, v43
	v_cndmask_b32_e64 v42, v9, v42, s[0:1]
	v_cndmask_b32_e32 v17, v17, v42, vcc

; DI void rope8(float (&v)[8], const float* __restrict__ rope, int s, int fq) {
;     const f32x4 c0 = *(const f32x4*)(rope + s * 16), c1 = *(const f32x4*)(rope + s * 16 + 4), s0 = *(const f32x4*)(rope + s * 16 + 8), s1 = *(const f32x4*)(rope + s * 16 + 12);
;     const float cs[8] = {c0[0], c0[1], c0[2], c0[3], c1[0], c1[1], c1[2], c1[3]}, sn[8] = {s0[0], s0[1], s0[2], s0[3], s1[0], s1[1], s1[2], s1[3]};
; #pragma unroll
;     for (int e = 0; e < 8; ++e) {
;         const float other = __shfl_xor(v[e], 16);
;         const float a = v[e] * cs[e], bq = other * sn[e];
;         v[e] = (fq == 0) ? (a - bq) : ((fq == 1) ? (a + bq) : v[e]);
;     }
; }
.LBB0_967:
	s_andn2_b64 vcc, exec, s[8:9]
	s_cbranch_vccnz .LBB0_1017
	v_and_b32_e32 v11, 64, v183
	v_xor_b32_e32 v10, 16, v183
	v_add_u32_e32 v11, 64, v11
	v_cmp_lt_i32_e32 vcc, v10, v11
	v_lshlrev_b32_e32 v34, 6, v45
	s_nop 0
	v_cndmask_b32_e32 v10, v183, v10, vcc
	v_lshlrev_b32_e32 v46, 2, v10
	global_load_dwordx4 v[38:41], v34, s[68:69]
	global_load_dwordx4 v[10:13], v34, s[68:69] offset:32
	global_load_dwordx4 v[14:17], v34, s[68:69] offset:48
	s_nop 0
	global_load_dwordx4 v[34:37], v34, s[68:69] offset:16
	v_mov_b32_e32 v224, v2
	v_mov_b32_e32 v225, v2
	v_cmp_eq_u32_e64 s[0:1], 1, v1
	s_nop 0
	v_permlane16_swap_b32_e32 v224, v225
	v_cndmask_b32_e64 v47, v225, v224, s[0:1]
	v_cmp_lt_i32_e32 vcc, 0, v1
	s_waitcnt vmcnt(3)
	v_mul_f32_e32 v38, v2, v38
	s_waitcnt vmcnt(2) lgkmcnt(0)
	v_mul_f32_e32 v47, v10, v47
	v_sub_f32_e32 v10, v38, v47
	v_add_f32_e32 v38, v38, v47
	v_cndmask_b32_e64 v38, v2, v38, s[0:1]
	v_cndmask_b32_e32 v10, v10, v38, vcc
	v_mov_b32_e32 v224, v3
	v_mov_b32_e32 v225, v3
	s_nop 1
	v_permlane16_swap_b32_e32 v224, v225
	v_cndmask_b32_e64 v47, v225, v224, s[0:1]
	v_mul_f32_e32 v38, v3, v39
	s_waitcnt lgkmcnt(0)
	v_mul_f32_e32 v39, v11, v47
	v_sub_f32_e32 v11, v38, v39
	v_add_f32_e32 v38, v38, v39
	v_cndmask_b32_e64 v38, v3, v38, s[0:1]
	v_cndmask_b32_e32 v11, v11, v38, vcc
	v_mov_b32_e32 v224, v4
	v_mov_b32_e32 v225, v4
	s_nop 1
	v_permlane16_swap_b32_e32 v224, v225
	v_cndmask_b32_e64 v39, v225, v224, s[0:1]
	v_mul_f32_e32 v38, v4, v40
	s_waitcnt lgkmcnt(0)
	v_mul_f32_e32 v39, v12, v39
	v_sub_f32_e32 v12, v38, v39
	v_add_f32_e32 v38, v38, v39
	v_cndmask_b32_e64 v38, v4, v38, s[0:1]
	v_cndmask_b32_e32 v12, v12, v38, vcc
	v_mov_b32_e32 v224, v5
	v_mov_b32_e32 v225, v5
	s_nop 1
	v_permlane16_swap_b32_e32 v224, v225
	v_cndmask_b32_e64 v39, v225, v224, s[0:1]
	v_mul_f32_e32 v38, v5, v41
	s_waitcnt lgkmcnt(0)
	v_mul_f32_e32 v39, v13, v39
	v_sub_f32_e32 v13, v38, v39
	v_add_f32_e32 v38, v38, v39
	v_cndmask_b32_e64 v38, v5, v38, s[0:1]
	v_cndmask_b32_e32 v13, v13, v38, vcc
	v_mov_b32_e32 v224, v6
	v_mov_b32_e32 v225, v6
	s_nop 1
	v_permlane16_swap_b32_e32 v224, v225
	v_cndmask_b32_e64 v38, v225, v224, s[0:1]
	s_waitcnt vmcnt(0)
	v_mul_f32_e32 v34, v6, v34
	s_waitcnt lgkmcnt(0)
	v_mul_f32_e32 v38, v14, v38
	v_sub_f32_e32 v14, v34, v38
	v_add_f32_e32 v34, v34, v38
	v_cndmask_b32_e64 v34, v6, v34, s[0:1]
	v_cndmask_b32_e32 v14, v14, v34, vcc
	v_mov_b32_e32 v224, v7
	v_mov_b32_e32 v225, v7
	s_nop 1
	v_permlane16_swap_b32_e32 v224, v225
	v_cndmask_b32_e64 v38, v225, v224, s[0:1]
	v_mul_f32_e32 v34, v7, v35
	s_waitcnt lgkmcnt(0)
	v_mul_f32_e32 v35, v15, v38
	v_sub_f32_e32 v15, v34, v35
	v_add_f32_e32 v34, v34, v35
	v_cndmask_b32_e64 v34, v7, v34, s[0:1]
	v_cndmask_b32_e32 v15, v15, v34, vcc
	v_mov_b32_e32 v224, v8
	v_mov_b32_e32 v225, v8
	s_nop 1
	v_permlane16_swap_b32_e32 v224, v225
	v_cndmask_b32_e64 v35, v225, v224, s[0:1]
	v_mul_f32_e32 v34, v8, v36
	s_waitcnt lgkmcnt(0)
	v_mul_f32_e32 v35, v16, v35
	v_sub_f32_e32 v16, v34, v35
	v_add_f32_e32 v34, v34, v35
	v_cndmask_b32_e64 v34, v8, v34, s[0:1]
	v_cndmask_b32_e32 v16, v16, v34, vcc
	v_mov_b32_e32 v224, v9
	v_mov_b32_e32 v225, v9
	s_nop 1
	v_permlane16_swap_b32_e32 v224, v225
	v_cndmask_b32_e64 v35, v225, v224, s[0:1]
	v_mul_f32_e32 v34, v9, v37
	s_waitcnt lgkmcnt(0)
	v_mul_f32_e32 v35, v17, v35
	v_sub_f32_e32 v17, v34, v35
	v_add_f32_e32 v34, v34, v35
	v_cndmask_b32_e64 v34, v9, v34, s[0:1]
	v_cndmask_b32_e32 v17, v17, v34, vcc

; DI void rope8(float (&v)[8], const float* __restrict__ rope, int s, int fq) {
;     const f32x4 c0 = *(const f32x4*)(rope + s * 16), c1 = *(const f32x4*)(rope + s * 16 + 4), s0 = *(const f32x4*)(rope + s * 16 + 8), s1 = *(const f32x4*)(rope + s * 16 + 12);
;     const float cs[8] = {c0[0], c0[1], c0[2], c0[3], c1[0], c1[1], c1[2], c1[3]}, sn[8] = {s0[0], s0[1], s0[2], s0[3], s1[0], s1[1], s1[2], s1[3]};
; #pragma unroll
;     for (int e = 0; e < 8; ++e) {
;         const float other = __shfl_xor(v[e], 16);
;         const float a = v[e] * cs[e], bq = other * sn[e];
;         v[e] = (fq == 0) ? (a - bq) : ((fq == 1) ? (a + bq) : v[e]);
;     }
; }
.LBB0_1027:
	s_andn2_b64 vcc, exec, s[8:9]
	s_cbranch_vccnz .LBB0_1077
	v_and_b32_e32 v11, 64, v183
	v_xor_b32_e32 v10, 16, v183
	v_add_u32_e32 v11, 64, v11
	v_cmp_lt_i32_e32 vcc, v10, v11
	v_lshlrev_b32_e32 v26, 6, v35
	s_nop 0
	v_cndmask_b32_e32 v10, v183, v10, vcc
	v_lshlrev_b32_e32 v36, 2, v10
	global_load_dwordx4 v[30:33], v26, s[68:69]
	global_load_dwordx4 v[10:13], v26, s[68:69] offset:32
	global_load_dwordx4 v[14:17], v26, s[68:69] offset:48
	s_nop 0
	global_load_dwordx4 v[26:29], v26, s[68:69] offset:16
	v_mov_b32_e32 v224, v2
	v_mov_b32_e32 v225, v2
	v_cmp_eq_u32_e64 s[0:1], 1, v1
	s_nop 0
	v_permlane16_swap_b32_e32 v224, v225
	v_cndmask_b32_e64 v37, v225, v224, s[0:1]
	v_cmp_lt_i32_e32 vcc, 0, v1
	s_waitcnt vmcnt(3)
	v_mul_f32_e32 v30, v2, v30
	s_waitcnt vmcnt(2) lgkmcnt(0)
	v_mul_f32_e32 v37, v10, v37
	v_sub_f32_e32 v10, v30, v37
	v_add_f32_e32 v30, v30, v37
	v_cndmask_b32_e64 v30, v2, v30, s[0:1]
	v_cndmask_b32_e32 v10, v10, v30, vcc
	v_mov_b32_e32 v224, v3
	v_mov_b32_e32 v225, v3
	s_nop 1
	v_permlane16_swap_b32_e32 v224, v225
	v_cndmask_b32_e64 v37, v225, v224, s[0:1]
	v_mul_f32_e32 v30, v3, v31
	s_waitcnt lgkmcnt(0)
	v_mul_f32_e32 v31, v11, v37
	v_sub_f32_e32 v11, v30, v31
	v_add_f32_e32 v30, v30, v31
	v_cndmask_b32_e64 v30, v3, v30, s[0:1]
	v_cndmask_b32_e32 v11, v11, v30, vcc
	v_mov_b32_e32 v224, v4
	v_mov_b32_e32 v225, v4
	s_nop 1
	v_permlane16_swap_b32_e32 v224, v225
	v_cndmask_b32_e64 v31, v225, v224, s[0:1]
	v_mul_f32_e32 v30, v4, v32
	s_waitcnt lgkmcnt(0)
	v_mul_f32_e32 v31, v12, v31
	v_sub_f32_e32 v12, v30, v31
	v_add_f32_e32 v30, v30, v31
	v_cndmask_b32_e64 v30, v4, v30, s[0:1]
	v_cndmask_b32_e32 v12, v12, v30, vcc
	v_mov_b32_e32 v224, v5
	v_mov_b32_e32 v225, v5
	s_nop 1
	v_permlane16_swap_b32_e32 v224, v225
	v_cndmask_b32_e64 v31, v225, v224, s[0:1]
	v_mul_f32_e32 v30, v5, v33
	s_waitcnt lgkmcnt(0)
	v_mul_f32_e32 v31, v13, v31
	v_sub_f32_e32 v13, v30, v31
	v_add_f32_e32 v30, v30, v31
	v_cndmask_b32_e64 v30, v5, v30, s[0:1]
	v_cndmask_b32_e32 v13, v13, v30, vcc
	v_mov_b32_e32 v224, v6
	v_mov_b32_e32 v225, v6
	s_nop 1
	v_permlane16_swap_b32_e32 v224, v225
	v_cndmask_b32_e64 v30, v225, v224, s[0:1]
	s_waitcnt vmcnt(0)
	v_mul_f32_e32 v26, v6, v26
	s_waitcnt lgkmcnt(0)
	v_mul_f32_e32 v30, v14, v30
	v_sub_f32_e32 v14, v26, v30
	v_add_f32_e32 v26, v26, v30
	v_cndmask_b32_e64 v26, v6, v26, s[0:1]
	v_cndmask_b32_e32 v14, v14, v26, vcc
	v_mov_b32_e32 v224, v7
	v_mov_b32_e32 v225, v7
	s_nop 1
	v_permlane16_swap_b32_e32 v224, v225
	v_cndmask_b32_e64 v30, v225, v224, s[0:1]
	v_mul_f32_e32 v26, v7, v27
	s_waitcnt lgkmcnt(0)
	v_mul_f32_e32 v27, v15, v30
	v_sub_f32_e32 v15, v26, v27
	v_add_f32_e32 v26, v26, v27
	v_cndmask_b32_e64 v26, v7, v26, s[0:1]
	v_cndmask_b32_e32 v15, v15, v26, vcc
	v_mov_b32_e32 v224, v8
	v_mov_b32_e32 v225, v8
	s_nop 1
	v_permlane16_swap_b32_e32 v224, v225
	v_cndmask_b32_e64 v27, v225, v224, s[0:1]
	v_mul_f32_e32 v26, v8, v28
	s_waitcnt lgkmcnt(0)
	v_mul_f32_e32 v27, v16, v27
	v_sub_f32_e32 v16, v26, v27
	v_add_f32_e32 v26, v26, v27
	v_cndmask_b32_e64 v26, v8, v26, s[0:1]
	v_cndmask_b32_e32 v16, v16, v26, vcc
	v_mov_b32_e32 v224, v9
	v_mov_b32_e32 v225, v9
	s_nop 1
	v_permlane16_swap_b32_e32 v224, v225
	v_cndmask_b32_e64 v27, v225, v224, s[0:1]
	v_mul_f32_e32 v26, v9, v29
	s_waitcnt lgkmcnt(0)
	v_mul_f32_e32 v27, v17, v27
	v_sub_f32_e32 v17, v26, v27
	v_add_f32_e32 v26, v26, v27
	v_cndmask_b32_e64 v26, v9, v26, s[0:1]
	v_cndmask_b32_e32 v17, v17, v26, vcc

; DI void rope8(float (&v)[8], const float* __restrict__ rope, int s, int fq) {
;     const f32x4 c0 = *(const f32x4*)(rope + s * 16), c1 = *(const f32x4*)(rope + s * 16 + 4), s0 = *(const f32x4*)(rope + s * 16 + 8), s1 = *(const f32x4*)(rope + s * 16 + 12);
;     const float cs[8] = {c0[0], c0[1], c0[2], c0[3], c1[0], c1[1], c1[2], c1[3]}, sn[8] = {s0[0], s0[1], s0[2], s0[3], s1[0], s1[1], s1[2], s1[3]};
; #pragma unroll
;     for (int e = 0; e < 8; ++e) {
;         const float other = __shfl_xor(v[e], 16);
;         const float a = v[e] * cs[e], bq = other * sn[e];
;         v[e] = (fq == 0) ? (a - bq) : ((fq == 1) ? (a + bq) : v[e]);
;     }
; }
.LBB0_1087:
	s_andn2_b64 vcc, exec, s[6:7]
	s_cbranch_vccnz .LBB0_1137
	v_and_b32_e32 v11, 64, v183
	v_xor_b32_e32 v10, 16, v183
	v_add_u32_e32 v11, 64, v11
	v_cmp_lt_i32_e32 vcc, v10, v11
	v_lshlrev_b32_e32 v18, 6, v27
	s_nop 0
	v_cndmask_b32_e32 v10, v183, v10, vcc
	v_lshlrev_b32_e32 v28, 2, v10
	global_load_dwordx4 v[22:25], v18, s[68:69]
	global_load_dwordx4 v[10:13], v18, s[68:69] offset:32
	global_load_dwordx4 v[14:17], v18, s[68:69] offset:48
	s_nop 0
	global_load_dwordx4 v[18:21], v18, s[68:69] offset:16
	v_mov_b32_e32 v224, v2
	v_mov_b32_e32 v225, v2
	v_cmp_eq_u32_e64 s[0:1], 1, v1
	s_nop 0
	v_permlane16_swap_b32_e32 v224, v225
	v_cndmask_b32_e64 v29, v225, v224, s[0:1]
	v_cmp_lt_i32_e32 vcc, 0, v1
	s_waitcnt vmcnt(3)
	v_mul_f32_e32 v22, v2, v22
	s_waitcnt vmcnt(2) lgkmcnt(0)
	v_mul_f32_e32 v29, v10, v29
	v_sub_f32_e32 v10, v22, v29
	v_add_f32_e32 v22, v22, v29
	v_cndmask_b32_e64 v22, v2, v22, s[0:1]
	v_cndmask_b32_e32 v10, v10, v22, vcc
	v_mov_b32_e32 v224, v3
	v_mov_b32_e32 v225, v3
	s_nop 1
	v_permlane16_swap_b32_e32 v224, v225
	v_cndmask_b32_e64 v29, v225, v224, s[0:1]
	v_mul_f32_e32 v22, v3, v23
	s_waitcnt lgkmcnt(0)
	v_mul_f32_e32 v23, v11, v29
	v_sub_f32_e32 v11, v22, v23
	v_add_f32_e32 v22, v22, v23
	v_cndmask_b32_e64 v22, v3, v22, s[0:1]
	v_cndmask_b32_e32 v11, v11, v22, vcc
	v_mov_b32_e32 v224, v4
	v_mov_b32_e32 v225, v4
	s_nop 1
	v_permlane16_swap_b32_e32 v224, v225
	v_cndmask_b32_e64 v23, v225, v224, s[0:1]
	v_mul_f32_e32 v22, v4, v24
	s_waitcnt lgkmcnt(0)
	v_mul_f32_e32 v23, v12, v23
	v_sub_f32_e32 v12, v22, v23
	v_add_f32_e32 v22, v22, v23
	v_cndmask_b32_e64 v22, v4, v22, s[0:1]
	v_cndmask_b32_e32 v12, v12, v22, vcc
	v_mov_b32_e32 v224, v5
	v_mov_b32_e32 v225, v5
	s_nop 1
	v_permlane16_swap_b32_e32 v224, v225
	v_cndmask_b32_e64 v23, v225, v224, s[0:1]
	v_mul_f32_e32 v22, v5, v25
	s_waitcnt lgkmcnt(0)
	v_mul_f32_e32 v23, v13, v23
	v_sub_f32_e32 v13, v22, v23
	v_add_f32_e32 v22, v22, v23
	v_cndmask_b32_e64 v22, v5, v22, s[0:1]
	v_cndmask_b32_e32 v13, v13, v22, vcc
	v_mov_b32_e32 v224, v6
	v_mov_b32_e32 v225, v6
	s_nop 1
	v_permlane16_swap_b32_e32 v224, v225
	v_cndmask_b32_e64 v22, v225, v224, s[0:1]
	s_waitcnt vmcnt(0)
	v_mul_f32_e32 v18, v6, v18
	s_waitcnt lgkmcnt(0)
	v_mul_f32_e32 v22, v14, v22
	v_sub_f32_e32 v14, v18, v22
	v_add_f32_e32 v18, v18, v22
	v_cndmask_b32_e64 v18, v6, v18, s[0:1]
	v_cndmask_b32_e32 v14, v14, v18, vcc
	v_mov_b32_e32 v224, v7
	v_mov_b32_e32 v225, v7
	s_nop 1
	v_permlane16_swap_b32_e32 v224, v225
	v_cndmask_b32_e64 v22, v225, v224, s[0:1]
	v_mul_f32_e32 v18, v7, v19
	s_waitcnt lgkmcnt(0)
	v_mul_f32_e32 v19, v15, v22
	v_sub_f32_e32 v15, v18, v19
	v_add_f32_e32 v18, v18, v19
	v_cndmask_b32_e64 v18, v7, v18, s[0:1]
	v_cndmask_b32_e32 v15, v15, v18, vcc
	v_mov_b32_e32 v224, v8
	v_mov_b32_e32 v225, v8
	s_nop 1
	v_permlane16_swap_b32_e32 v224, v225
	v_cndmask_b32_e64 v19, v225, v224, s[0:1]
	v_mul_f32_e32 v18, v8, v20
	s_waitcnt lgkmcnt(0)
	v_mul_f32_e32 v19, v16, v19
	v_sub_f32_e32 v16, v18, v19
	v_add_f32_e32 v18, v18, v19
	v_cndmask_b32_e64 v18, v8, v18, s[0:1]
	v_cndmask_b32_e32 v16, v16, v18, vcc
	v_mov_b32_e32 v224, v9
	v_mov_b32_e32 v225, v9
	s_nop 1
	v_permlane16_swap_b32_e32 v224, v225
	v_cndmask_b32_e64 v19, v225, v224, s[0:1]
	v_mul_f32_e32 v18, v9, v21
	s_waitcnt lgkmcnt(0)
	v_mul_f32_e32 v19, v17, v19
	v_sub_f32_e32 v17, v18, v19
	v_add_f32_e32 v18, v18, v19
	v_cndmask_b32_e64 v18, v9, v18, s[0:1]
	v_cndmask_b32_e32 v17, v17, v18, vcc

; DI void rope8(float (&v)[8], const float* __restrict__ rope, int s, int fq) {
;     const f32x4 c0 = *(const f32x4*)(rope + s * 16), c1 = *(const f32x4*)(rope + s * 16 + 4), s0 = *(const f32x4*)(rope + s * 16 + 8), s1 = *(const f32x4*)(rope + s * 16 + 12);
;     const float cs[8] = {c0[0], c0[1], c0[2], c0[3], c1[0], c1[1], c1[2], c1[3]}, sn[8] = {s0[0], s0[1], s0[2], s0[3], s1[0], s1[1], s1[2], s1[3]};
; #pragma unroll
;     for (int e = 0; e < 8; ++e) {
;         const float other = __shfl_xor(v[e], 16);
;         const float a = v[e] * cs[e], bq = other * sn[e];
;         v[e] = (fq == 0) ? (a - bq) : ((fq == 1) ? (a + bq) : v[e]);
;     }
; }
.LBB0_1145:
	s_andn2_b64 vcc, exec, s[6:7]
	s_cbranch_vccnz .LBB0_1195
	v_and_b32_e32 v11, 64, v183
	v_xor_b32_e32 v10, 16, v183
	v_add_u32_e32 v11, 64, v11
	v_cmp_lt_i32_e32 vcc, v10, v11
	v_lshlrev_b32_e32 v82, 6, v92
	s_nop 0
	v_cndmask_b32_e32 v10, v183, v10, vcc
	v_lshlrev_b32_e32 v93, 2, v10
	global_load_dwordx4 v[86:89], v82, s[68:69]
	global_load_dwordx4 v[10:13], v82, s[68:69] offset:32
	global_load_dwordx4 v[14:17], v82, s[68:69] offset:48
	s_nop 0
	global_load_dwordx4 v[82:85], v82, s[68:69] offset:16
	v_mov_b32_e32 v224, v2
	v_mov_b32_e32 v225, v2
	v_cmp_eq_u32_e64 s[0:1], 1, v1
	s_nop 0
	v_permlane16_swap_b32_e32 v224, v225
	v_cndmask_b32_e64 v94, v225, v224, s[0:1]
	v_cmp_lt_i32_e32 vcc, 0, v1
	s_waitcnt vmcnt(3)
	v_mul_f32_e32 v86, v2, v86
	s_waitcnt vmcnt(2) lgkmcnt(0)
	v_mul_f32_e32 v94, v10, v94
	v_sub_f32_e32 v10, v86, v94
	v_add_f32_e32 v86, v86, v94
	v_cndmask_b32_e64 v86, v2, v86, s[0:1]
	v_cndmask_b32_e32 v10, v10, v86, vcc
	v_mov_b32_e32 v224, v3
	v_mov_b32_e32 v225, v3
	s_nop 1
	v_permlane16_swap_b32_e32 v224, v225
	v_cndmask_b32_e64 v94, v225, v224, s[0:1]
	v_mul_f32_e32 v86, v3, v87
	s_waitcnt lgkmcnt(0)
	v_mul_f32_e32 v87, v11, v94
	v_sub_f32_e32 v11, v86, v87
	v_add_f32_e32 v86, v86, v87
	v_cndmask_b32_e64 v86, v3, v86, s[0:1]
	v_cndmask_b32_e32 v11, v11, v86, vcc
	v_mov_b32_e32 v224, v4
	v_mov_b32_e32 v225, v4
	s_nop 1
	v_permlane16_swap_b32_e32 v224, v225
	v_cndmask_b32_e64 v87, v225, v224, s[0:1]
	v_mul_f32_e32 v86, v4, v88
	s_waitcnt lgkmcnt(0)
	v_mul_f32_e32 v87, v12, v87
	v_sub_f32_e32 v12, v86, v87
	v_add_f32_e32 v86, v86, v87
	v_cndmask_b32_e64 v86, v4, v86, s[0:1]
	v_cndmask_b32_e32 v12, v12, v86, vcc
	v_mov_b32_e32 v224, v5
	v_mov_b32_e32 v225, v5
	s_nop 1
	v_permlane16_swap_b32_e32 v224, v225
	v_cndmask_b32_e64 v87, v225, v224, s[0:1]
	v_mul_f32_e32 v86, v5, v89
	s_waitcnt lgkmcnt(0)
	v_mul_f32_e32 v87, v13, v87
	v_sub_f32_e32 v13, v86, v87
	v_add_f32_e32 v86, v86, v87
	v_cndmask_b32_e64 v86, v5, v86, s[0:1]
	v_cndmask_b32_e32 v13, v13, v86, vcc
	v_mov_b32_e32 v224, v6
	v_mov_b32_e32 v225, v6
	s_nop 1
	v_permlane16_swap_b32_e32 v224, v225
	v_cndmask_b32_e64 v86, v225, v224, s[0:1]
	s_waitcnt vmcnt(0)
	v_mul_f32_e32 v82, v6, v82
	s_waitcnt lgkmcnt(0)
	v_mul_f32_e32 v86, v14, v86
	v_sub_f32_e32 v14, v82, v86
	v_add_f32_e32 v82, v82, v86
	v_cndmask_b32_e64 v82, v6, v82, s[0:1]
	v_cndmask_b32_e32 v14, v14, v82, vcc
	v_mov_b32_e32 v224, v7
	v_mov_b32_e32 v225, v7
	s_nop 1
	v_permlane16_swap_b32_e32 v224, v225
	v_cndmask_b32_e64 v86, v225, v224, s[0:1]
	v_mul_f32_e32 v82, v7, v83
	s_waitcnt lgkmcnt(0)
	v_mul_f32_e32 v83, v15, v86
	v_sub_f32_e32 v15, v82, v83
	v_add_f32_e32 v82, v82, v83
	v_cndmask_b32_e64 v82, v7, v82, s[0:1]
	v_cndmask_b32_e32 v15, v15, v82, vcc
	v_mov_b32_e32 v224, v8
	v_mov_b32_e32 v225, v8
	s_nop 1
	v_permlane16_swap_b32_e32 v224, v225
	v_cndmask_b32_e64 v83, v225, v224, s[0:1]
	v_mul_f32_e32 v82, v8, v84
	s_waitcnt lgkmcnt(0)
	v_mul_f32_e32 v83, v16, v83
	v_sub_f32_e32 v16, v82, v83
	v_add_f32_e32 v82, v82, v83
	v_cndmask_b32_e64 v82, v8, v82, s[0:1]
	v_cndmask_b32_e32 v16, v16, v82, vcc
	v_mov_b32_e32 v224, v9
	v_mov_b32_e32 v225, v9
	s_nop 1
	v_permlane16_swap_b32_e32 v224, v225
	v_cndmask_b32_e64 v83, v225, v224, s[0:1]
	v_mul_f32_e32 v82, v9, v85
	s_waitcnt lgkmcnt(0)
	v_mul_f32_e32 v83, v17, v83
	v_sub_f32_e32 v17, v82, v83
	v_add_f32_e32 v82, v82, v83
	v_cndmask_b32_e64 v82, v9, v82, s[0:1]
	v_cndmask_b32_e32 v17, v17, v82, vcc

; DI void rope8(float (&v)[8], const float* __restrict__ rope, int s, int fq) {
;     const f32x4 c0 = *(const f32x4*)(rope + s * 16), c1 = *(const f32x4*)(rope + s * 16 + 4), s0 = *(const f32x4*)(rope + s * 16 + 8), s1 = *(const f32x4*)(rope + s * 16 + 12);
;     const float cs[8] = {c0[0], c0[1], c0[2], c0[3], c1[0], c1[1], c1[2], c1[3]}, sn[8] = {s0[0], s0[1], s0[2], s0[3], s1[0], s1[1], s1[2], s1[3]};
; #pragma unroll
;     for (int e = 0; e < 8; ++e) {
;         const float other = __shfl_xor(v[e], 16);
;         const float a = v[e] * cs[e], bq = other * sn[e];
;         v[e] = (fq == 0) ? (a - bq) : ((fq == 1) ? (a + bq) : v[e]);
;     }
; }
.LBB0_1561:
	s_andn2_b64 vcc, exec, s[6:7]
	s_cbranch_vccnz .LBB0_1611
	v_and_b32_e32 v11, 64, v188
	v_xor_b32_e32 v10, 16, v188
	v_add_u32_e32 v11, 64, v11
	v_cmp_lt_i32_e32 vcc, v10, v11
	v_lshlrev_b32_e32 v11, 6, v158
	global_load_dwordx4 v[146:149], v11, s[68:69]
	global_load_dwordx4 v[142:145], v11, s[68:69] offset:32
	global_load_dwordx4 v[14:17], v11, s[68:69] offset:48
	global_load_dwordx4 v[138:141], v11, s[68:69] offset:16
	v_cndmask_b32_e32 v10, v188, v10, vcc
	v_lshlrev_b32_e32 v190, 2, v10
	v_mov_b32_e32 v224, v2
	v_mov_b32_e32 v225, v2
	v_cmp_eq_u32_e64 s[0:1], 1, v177
	s_nop 0
	v_permlane16_swap_b32_e32 v224, v225
	v_cndmask_b32_e64 v12, v225, v224, s[0:1]
	v_cmp_lt_i32_e32 vcc, 0, v177
	s_waitcnt vmcnt(3)
	v_mul_f32_e32 v11, v2, v146
	s_waitcnt vmcnt(2) lgkmcnt(0)
	v_mul_f32_e32 v12, v142, v12
	v_sub_f32_e32 v10, v11, v12
	v_add_f32_e32 v11, v11, v12
	v_cndmask_b32_e64 v11, v2, v11, s[0:1]
	v_cndmask_b32_e32 v10, v10, v11, vcc
	v_mov_b32_e32 v224, v3
	v_mov_b32_e32 v225, v3
	s_nop 1
	v_permlane16_swap_b32_e32 v224, v225
	v_cndmask_b32_e64 v11, v225, v224, s[0:1]
	v_mul_f32_e32 v12, v3, v147
	s_waitcnt lgkmcnt(0)
	v_mul_f32_e32 v13, v143, v11
	v_sub_f32_e32 v11, v12, v13
	v_add_f32_e32 v12, v12, v13
	v_cndmask_b32_e64 v12, v3, v12, s[0:1]
	v_cndmask_b32_e32 v11, v11, v12, vcc
	v_mov_b32_e32 v224, v4
	v_mov_b32_e32 v225, v4
	s_nop 1
	v_permlane16_swap_b32_e32 v224, v225
	v_cndmask_b32_e64 v12, v225, v224, s[0:1]
	v_mul_f32_e32 v13, v4, v148
	s_waitcnt lgkmcnt(0)
	v_mul_f32_e32 v142, v144, v12
	v_sub_f32_e32 v12, v13, v142
	v_add_f32_e32 v13, v13, v142
	v_cndmask_b32_e64 v13, v4, v13, s[0:1]
	v_cndmask_b32_e32 v12, v12, v13, vcc
	v_mov_b32_e32 v224, v5
	v_mov_b32_e32 v225, v5
	s_nop 1
	v_permlane16_swap_b32_e32 v224, v225
	v_cndmask_b32_e64 v13, v225, v224, s[0:1]
	v_mul_f32_e32 v142, v5, v149
	s_waitcnt lgkmcnt(0)
	v_mul_f32_e32 v143, v145, v13
	v_sub_f32_e32 v13, v142, v143
	v_add_f32_e32 v142, v142, v143
	v_cndmask_b32_e64 v142, v5, v142, s[0:1]
	v_cndmask_b32_e32 v13, v13, v142, vcc
	v_mov_b32_e32 v224, v6
	v_mov_b32_e32 v225, v6
	s_nop 1
	v_permlane16_swap_b32_e32 v224, v225
	v_cndmask_b32_e64 v142, v225, v224, s[0:1]
	s_waitcnt vmcnt(0)
	v_mul_f32_e32 v138, v6, v138
	s_waitcnt lgkmcnt(0)
	v_mul_f32_e32 v142, v14, v142
	v_sub_f32_e32 v14, v138, v142
	v_add_f32_e32 v138, v138, v142
	v_cndmask_b32_e64 v138, v6, v138, s[0:1]
	v_cndmask_b32_e32 v14, v14, v138, vcc
	v_mov_b32_e32 v224, v7
	v_mov_b32_e32 v225, v7
	s_nop 1
	v_permlane16_swap_b32_e32 v224, v225
	v_cndmask_b32_e64 v142, v225, v224, s[0:1]
	v_mul_f32_e32 v138, v7, v139
	s_waitcnt lgkmcnt(0)
	v_mul_f32_e32 v139, v15, v142
	v_sub_f32_e32 v15, v138, v139
	v_add_f32_e32 v138, v138, v139
	v_cndmask_b32_e64 v138, v7, v138, s[0:1]
	v_cndmask_b32_e32 v15, v15, v138, vcc
	v_mov_b32_e32 v224, v8
	v_mov_b32_e32 v225, v8
	s_nop 1
	v_permlane16_swap_b32_e32 v224, v225
	v_cndmask_b32_e64 v139, v225, v224, s[0:1]
	v_mul_f32_e32 v138, v8, v140
	s_waitcnt lgkmcnt(0)
	v_mul_f32_e32 v139, v16, v139
	v_sub_f32_e32 v16, v138, v139
	v_add_f32_e32 v138, v138, v139
	v_cndmask_b32_e64 v138, v8, v138, s[0:1]
	v_cndmask_b32_e32 v16, v16, v138, vcc
	v_mov_b32_e32 v224, v9
	v_mov_b32_e32 v225, v9
	s_nop 1
	v_permlane16_swap_b32_e32 v224, v225
	v_cndmask_b32_e64 v139, v225, v224, s[0:1]
	v_mul_f32_e32 v138, v9, v141
	s_waitcnt lgkmcnt(0)
	v_mul_f32_e32 v139, v17, v139
	v_sub_f32_e32 v17, v138, v139
	v_add_f32_e32 v138, v138, v139
	v_cndmask_b32_e64 v138, v9, v138, s[0:1]
	v_cndmask_b32_e32 v17, v17, v138, vcc

; DI void rope8(float (&v)[8], const float* __restrict__ rope, int s, int fq) {
;     const f32x4 c0 = *(const f32x4*)(rope + s * 16), c1 = *(const f32x4*)(rope + s * 16 + 4), s0 = *(const f32x4*)(rope + s * 16 + 8), s1 = *(const f32x4*)(rope + s * 16 + 12);
;     const float cs[8] = {c0[0], c0[1], c0[2], c0[3], c1[0], c1[1], c1[2], c1[3]}, sn[8] = {s0[0], s0[1], s0[2], s0[3], s1[0], s1[1], s1[2], s1[3]};
; #pragma unroll
;     for (int e = 0; e < 8; ++e) {
;         const float other = __shfl_xor(v[e], 16);
;         const float a = v[e] * cs[e], bq = other * sn[e];
;         v[e] = (fq == 0) ? (a - bq) : ((fq == 1) ? (a + bq) : v[e]);
;     }
; }
.LBB0_1626:
	s_andn2_b64 vcc, exec, s[8:9]
	s_cbranch_vccnz .LBB0_1676
	v_and_b32_e32 v11, 64, v188
	v_xor_b32_e32 v10, 16, v188
	v_add_u32_e32 v11, 64, v11
	v_cmp_lt_i32_e32 vcc, v10, v11
	v_lshlrev_b32_e32 v11, 6, v144
	global_load_dwordx4 v[138:141], v11, s[68:69]
	global_load_dwordx4 v[134:137], v11, s[68:69] offset:32
	global_load_dwordx4 v[14:17], v11, s[68:69] offset:48
	global_load_dwordx4 v[130:133], v11, s[68:69] offset:16
	v_cndmask_b32_e32 v10, v188, v10, vcc
	v_lshlrev_b32_e32 v145, 2, v10
	v_mov_b32_e32 v224, v2
	v_mov_b32_e32 v225, v2
	v_cmp_eq_u32_e64 s[0:1], 1, v177
	s_nop 0
	v_permlane16_swap_b32_e32 v224, v225
	v_cndmask_b32_e64 v12, v225, v224, s[0:1]
	v_cmp_lt_i32_e32 vcc, 0, v177
	s_waitcnt vmcnt(3)
	v_mul_f32_e32 v11, v2, v138
	s_waitcnt vmcnt(2) lgkmcnt(0)
	v_mul_f32_e32 v12, v134, v12
	v_sub_f32_e32 v10, v11, v12
	v_add_f32_e32 v11, v11, v12
	v_cndmask_b32_e64 v11, v2, v11, s[0:1]
	v_cndmask_b32_e32 v10, v10, v11, vcc
	v_mov_b32_e32 v224, v3
	v_mov_b32_e32 v225, v3
	s_nop 1
	v_permlane16_swap_b32_e32 v224, v225
	v_cndmask_b32_e64 v11, v225, v224, s[0:1]
	v_mul_f32_e32 v12, v3, v139
	s_waitcnt lgkmcnt(0)
	v_mul_f32_e32 v13, v135, v11
	v_sub_f32_e32 v11, v12, v13
	v_add_f32_e32 v12, v12, v13
	v_cndmask_b32_e64 v12, v3, v12, s[0:1]
	v_cndmask_b32_e32 v11, v11, v12, vcc
	v_mov_b32_e32 v224, v4
	v_mov_b32_e32 v225, v4
	s_nop 1
	v_permlane16_swap_b32_e32 v224, v225
	v_cndmask_b32_e64 v12, v225, v224, s[0:1]
	v_mul_f32_e32 v13, v4, v140
	s_waitcnt lgkmcnt(0)
	v_mul_f32_e32 v134, v136, v12
	v_sub_f32_e32 v12, v13, v134
	v_add_f32_e32 v13, v13, v134
	v_cndmask_b32_e64 v13, v4, v13, s[0:1]
	v_cndmask_b32_e32 v12, v12, v13, vcc
	v_mov_b32_e32 v224, v5
	v_mov_b32_e32 v225, v5
	s_nop 1
	v_permlane16_swap_b32_e32 v224, v225
	v_cndmask_b32_e64 v13, v225, v224, s[0:1]
	v_mul_f32_e32 v134, v5, v141
	s_waitcnt lgkmcnt(0)
	v_mul_f32_e32 v135, v137, v13
	v_sub_f32_e32 v13, v134, v135
	v_add_f32_e32 v134, v134, v135
	v_cndmask_b32_e64 v134, v5, v134, s[0:1]
	v_cndmask_b32_e32 v13, v13, v134, vcc
	v_mov_b32_e32 v224, v6
	v_mov_b32_e32 v225, v6
	s_nop 1
	v_permlane16_swap_b32_e32 v224, v225
	v_cndmask_b32_e64 v134, v225, v224, s[0:1]
	s_waitcnt vmcnt(0)
	v_mul_f32_e32 v130, v6, v130
	s_waitcnt lgkmcnt(0)
	v_mul_f32_e32 v134, v14, v134
	v_sub_f32_e32 v14, v130, v134
	v_add_f32_e32 v130, v130, v134
	v_cndmask_b32_e64 v130, v6, v130, s[0:1]
	v_cndmask_b32_e32 v14, v14, v130, vcc
	v_mov_b32_e32 v224, v7
	v_mov_b32_e32 v225, v7
	s_nop 1
	v_permlane16_swap_b32_e32 v224, v225
	v_cndmask_b32_e64 v134, v225, v224, s[0:1]
	v_mul_f32_e32 v130, v7, v131
	s_waitcnt lgkmcnt(0)
	v_mul_f32_e32 v131, v15, v134
	v_sub_f32_e32 v15, v130, v131
	v_add_f32_e32 v130, v130, v131
	v_cndmask_b32_e64 v130, v7, v130, s[0:1]
	v_cndmask_b32_e32 v15, v15, v130, vcc
	v_mov_b32_e32 v224, v8
	v_mov_b32_e32 v225, v8
	s_nop 1
	v_permlane16_swap_b32_e32 v224, v225
	v_cndmask_b32_e64 v131, v225, v224, s[0:1]
	v_mul_f32_e32 v130, v8, v132
	s_waitcnt lgkmcnt(0)
	v_mul_f32_e32 v131, v16, v131
	v_sub_f32_e32 v16, v130, v131
	v_add_f32_e32 v130, v130, v131
	v_cndmask_b32_e64 v130, v8, v130, s[0:1]
	v_cndmask_b32_e32 v16, v16, v130, vcc
	v_mov_b32_e32 v224, v9
	v_mov_b32_e32 v225, v9
	s_nop 1
	v_permlane16_swap_b32_e32 v224, v225
	v_cndmask_b32_e64 v131, v225, v224, s[0:1]
	v_mul_f32_e32 v130, v9, v133
	s_waitcnt lgkmcnt(0)
	v_mul_f32_e32 v131, v17, v131
	v_sub_f32_e32 v17, v130, v131
	v_add_f32_e32 v130, v130, v131
	v_cndmask_b32_e64 v130, v9, v130, s[0:1]
	v_cndmask_b32_e32 v17, v17, v130, vcc

; DI void rope8(float (&v)[8], const float* __restrict__ rope, int s, int fq) {
;     const f32x4 c0 = *(const f32x4*)(rope + s * 16), c1 = *(const f32x4*)(rope + s * 16 + 4), s0 = *(const f32x4*)(rope + s * 16 + 8), s1 = *(const f32x4*)(rope + s * 16 + 12);
;     const float cs[8] = {c0[0], c0[1], c0[2], c0[3], c1[0], c1[1], c1[2], c1[3]}, sn[8] = {s0[0], s0[1], s0[2], s0[3], s1[0], s1[1], s1[2], s1[3]};
; #pragma unroll
;     for (int e = 0; e < 8; ++e) {
;         const float other = __shfl_xor(v[e], 16);
;         const float a = v[e] * cs[e], bq = other * sn[e];
;         v[e] = (fq == 0) ? (a - bq) : ((fq == 1) ? (a + bq) : v[e]);
;     }
.LBB0_1691:
	s_andn2_b64 vcc, exec, s[8:9]
	s_cbranch_vccnz .LBB0_1741
	v_and_b32_e32 v11, 64, v188
	v_xor_b32_e32 v10, 16, v188
	v_add_u32_e32 v11, 64, v11
	v_cmp_lt_i32_e32 vcc, v10, v11
	v_lshlrev_b32_e32 v11, 6, v136
	global_load_dwordx4 v[130:133], v11, s[68:69]
	global_load_dwordx4 v[126:129], v11, s[68:69] offset:32
	global_load_dwordx4 v[14:17], v11, s[68:69] offset:48
	global_load_dwordx4 v[122:125], v11, s[68:69] offset:16
	v_cndmask_b32_e32 v10, v188, v10, vcc
	v_lshlrev_b32_e32 v137, 2, v10
	v_mov_b32_e32 v224, v2
	v_mov_b32_e32 v225, v2
	v_cmp_eq_u32_e64 s[0:1], 1, v177
	s_nop 0
	v_permlane16_swap_b32_e32 v224, v225
	v_cndmask_b32_e64 v12, v225, v224, s[0:1]
	v_cmp_lt_i32_e32 vcc, 0, v177
	s_waitcnt vmcnt(3)
	v_mul_f32_e32 v11, v2, v130
	s_waitcnt vmcnt(2) lgkmcnt(0)
	v_mul_f32_e32 v12, v126, v12
	v_sub_f32_e32 v10, v11, v12
	v_add_f32_e32 v11, v11, v12
	v_cndmask_b32_e64 v11, v2, v11, s[0:1]
	v_cndmask_b32_e32 v10, v10, v11, vcc
	v_mov_b32_e32 v224, v3
	v_mov_b32_e32 v225, v3
	s_nop 1
	v_permlane16_swap_b32_e32 v224, v225
	v_cndmask_b32_e64 v11, v225, v224, s[0:1]
	v_mul_f32_e32 v12, v3, v131
	s_waitcnt lgkmcnt(0)
	v_mul_f32_e32 v13, v127, v11
	v_sub_f32_e32 v11, v12, v13
	v_add_f32_e32 v12, v12, v13
	v_cndmask_b32_e64 v12, v3, v12, s[0:1]
	v_cndmask_b32_e32 v11, v11, v12, vcc
	v_mov_b32_e32 v224, v4
	v_mov_b32_e32 v225, v4
	s_nop 1
	v_permlane16_swap_b32_e32 v224, v225
	v_cndmask_b32_e64 v12, v225, v224, s[0:1]
	v_mul_f32_e32 v13, v4, v132
	s_waitcnt lgkmcnt(0)
	v_mul_f32_e32 v126, v128, v12
	v_sub_f32_e32 v12, v13, v126
	v_add_f32_e32 v13, v13, v126
	v_cndmask_b32_e64 v13, v4, v13, s[0:1]
	v_cndmask_b32_e32 v12, v12, v13, vcc
	v_mov_b32_e32 v224, v5
	v_mov_b32_e32 v225, v5
	s_nop 1
	v_permlane16_swap_b32_e32 v224, v225
	v_cndmask_b32_e64 v13, v225, v224, s[0:1]
	v_mul_f32_e32 v126, v5, v133
	s_waitcnt lgkmcnt(0)
	v_mul_f32_e32 v127, v129, v13
	v_sub_f32_e32 v13, v126, v127
	v_add_f32_e32 v126, v126, v127
	v_cndmask_b32_e64 v126, v5, v126, s[0:1]
	v_cndmask_b32_e32 v13, v13, v126, vcc
	v_mov_b32_e32 v224, v6
	v_mov_b32_e32 v225, v6
	s_nop 1
	v_permlane16_swap_b32_e32 v224, v225
	v_cndmask_b32_e64 v126, v225, v224, s[0:1]
	s_waitcnt vmcnt(0)
	v_mul_f32_e32 v122, v6, v122
	s_waitcnt lgkmcnt(0)
	v_mul_f32_e32 v126, v14, v126
	v_sub_f32_e32 v14, v122, v126
	v_add_f32_e32 v122, v122, v126
	v_cndmask_b32_e64 v122, v6, v122, s[0:1]
	v_cndmask_b32_e32 v14, v14, v122, vcc
	v_mov_b32_e32 v224, v7
	v_mov_b32_e32 v225, v7
	s_nop 1
	v_permlane16_swap_b32_e32 v224, v225
	v_cndmask_b32_e64 v126, v225, v224, s[0:1]
	v_mul_f32_e32 v122, v7, v123
	s_waitcnt lgkmcnt(0)
	v_mul_f32_e32 v123, v15, v126
	v_sub_f32_e32 v15, v122, v123
	v_add_f32_e32 v122, v122, v123
	v_cndmask_b32_e64 v122, v7, v122, s[0:1]
	v_cndmask_b32_e32 v15, v15, v122, vcc
	v_mov_b32_e32 v224, v8
	v_mov_b32_e32 v225, v8
	s_nop 1
	v_permlane16_swap_b32_e32 v224, v225
	v_cndmask_b32_e64 v123, v225, v224, s[0:1]
	v_mul_f32_e32 v122, v8, v124
	s_waitcnt lgkmcnt(0)
	v_mul_f32_e32 v123, v16, v123
	v_sub_f32_e32 v16, v122, v123
	v_add_f32_e32 v122, v122, v123
	v_cndmask_b32_e64 v122, v8, v122, s[0:1]
	v_cndmask_b32_e32 v16, v16, v122, vcc
	v_mov_b32_e32 v224, v9
	v_mov_b32_e32 v225, v9
	s_nop 1
	v_permlane16_swap_b32_e32 v224, v225
	v_cndmask_b32_e64 v123, v225, v224, s[0:1]
	v_mul_f32_e32 v122, v9, v125
	s_waitcnt lgkmcnt(0)
	v_mul_f32_e32 v123, v17, v123
	v_sub_f32_e32 v17, v122, v123
	v_add_f32_e32 v122, v122, v123
	v_cndmask_b32_e64 v122, v9, v122, s[0:1]
	v_cndmask_b32_e32 v17, v17, v122, vcc

; DI void rope8(float (&v)[8], const float* __restrict__ rope, int s, int fq) {
;     const f32x4 c0 = *(const f32x4*)(rope + s * 16), c1 = *(const f32x4*)(rope + s * 16 + 4), s0 = *(const f32x4*)(rope + s * 16 + 8), s1 = *(const f32x4*)(rope + s * 16 + 12);
;     const float cs[8] = {c0[0], c0[1], c0[2], c0[3], c1[0], c1[1], c1[2], c1[3]}, sn[8] = {s0[0], s0[1], s0[2], s0[3], s1[0], s1[1], s1[2], s1[3]};
; #pragma unroll
;     for (int e = 0; e < 8; ++e) {
;         const float other = __shfl_xor(v[e], 16);
;         const float a = v[e] * cs[e], bq = other * sn[e];
;         v[e] = (fq == 0) ? (a - bq) : ((fq == 1) ? (a + bq) : v[e]);
;     }
.LBB0_1756:
	s_andn2_b64 vcc, exec, s[8:9]
	s_cbranch_vccnz .LBB0_1806
	v_and_b32_e32 v11, 64, v188
	v_xor_b32_e32 v10, 16, v188
	v_add_u32_e32 v11, 64, v11
	v_cmp_lt_i32_e32 vcc, v10, v11
	v_lshlrev_b32_e32 v11, 6, v128
	global_load_dwordx4 v[122:125], v11, s[68:69]
	global_load_dwordx4 v[118:121], v11, s[68:69] offset:32
	global_load_dwordx4 v[14:17], v11, s[68:69] offset:48
	global_load_dwordx4 v[114:117], v11, s[68:69] offset:16
	v_cndmask_b32_e32 v10, v188, v10, vcc
	v_lshlrev_b32_e32 v129, 2, v10
	v_mov_b32_e32 v224, v2
	v_mov_b32_e32 v225, v2
	v_cmp_eq_u32_e64 s[0:1], 1, v177
	s_nop 0
	v_permlane16_swap_b32_e32 v224, v225
	v_cndmask_b32_e64 v12, v225, v224, s[0:1]
	v_cmp_lt_i32_e32 vcc, 0, v177
	s_waitcnt vmcnt(3)
	v_mul_f32_e32 v11, v2, v122
	s_waitcnt vmcnt(2) lgkmcnt(0)
	v_mul_f32_e32 v12, v118, v12
	v_sub_f32_e32 v10, v11, v12
	v_add_f32_e32 v11, v11, v12
	v_cndmask_b32_e64 v11, v2, v11, s[0:1]
	v_cndmask_b32_e32 v10, v10, v11, vcc
	v_mov_b32_e32 v224, v3
	v_mov_b32_e32 v225, v3
	s_nop 1
	v_permlane16_swap_b32_e32 v224, v225
	v_cndmask_b32_e64 v11, v225, v224, s[0:1]
	v_mul_f32_e32 v12, v3, v123
	s_waitcnt lgkmcnt(0)
	v_mul_f32_e32 v13, v119, v11
	v_sub_f32_e32 v11, v12, v13
	v_add_f32_e32 v12, v12, v13
	v_cndmask_b32_e64 v12, v3, v12, s[0:1]
	v_cndmask_b32_e32 v11, v11, v12, vcc
	v_mov_b32_e32 v224, v4
	v_mov_b32_e32 v225, v4
	s_nop 1
	v_permlane16_swap_b32_e32 v224, v225
	v_cndmask_b32_e64 v12, v225, v224, s[0:1]
	v_mul_f32_e32 v13, v4, v124
	s_waitcnt lgkmcnt(0)
	v_mul_f32_e32 v118, v120, v12
	v_sub_f32_e32 v12, v13, v118
	v_add_f32_e32 v13, v13, v118
	v_cndmask_b32_e64 v13, v4, v13, s[0:1]
	v_cndmask_b32_e32 v12, v12, v13, vcc
	v_mov_b32_e32 v224, v5
	v_mov_b32_e32 v225, v5
	s_nop 1
	v_permlane16_swap_b32_e32 v224, v225
	v_cndmask_b32_e64 v13, v225, v224, s[0:1]
	v_mul_f32_e32 v118, v5, v125
	s_waitcnt lgkmcnt(0)
	v_mul_f32_e32 v119, v121, v13
	v_sub_f32_e32 v13, v118, v119
	v_add_f32_e32 v118, v118, v119
	v_cndmask_b32_e64 v118, v5, v118, s[0:1]
	v_cndmask_b32_e32 v13, v13, v118, vcc
	v_mov_b32_e32 v224, v6
	v_mov_b32_e32 v225, v6
	s_nop 1
	v_permlane16_swap_b32_e32 v224, v225
	v_cndmask_b32_e64 v118, v225, v224, s[0:1]
	s_waitcnt vmcnt(0)
	v_mul_f32_e32 v114, v6, v114
	s_waitcnt lgkmcnt(0)
	v_mul_f32_e32 v118, v14, v118
	v_sub_f32_e32 v14, v114, v118
	v_add_f32_e32 v114, v114, v118
	v_cndmask_b32_e64 v114, v6, v114, s[0:1]
	v_cndmask_b32_e32 v14, v14, v114, vcc
	v_mov_b32_e32 v224, v7
	v_mov_b32_e32 v225, v7
	s_nop 1
	v_permlane16_swap_b32_e32 v224, v225
	v_cndmask_b32_e64 v118, v225, v224, s[0:1]
	v_mul_f32_e32 v114, v7, v115
	s_waitcnt lgkmcnt(0)
	v_mul_f32_e32 v115, v15, v118
	v_sub_f32_e32 v15, v114, v115
	v_add_f32_e32 v114, v114, v115
	v_cndmask_b32_e64 v114, v7, v114, s[0:1]
	v_cndmask_b32_e32 v15, v15, v114, vcc
	v_mov_b32_e32 v224, v8
	v_mov_b32_e32 v225, v8
	s_nop 1
	v_permlane16_swap_b32_e32 v224, v225
	v_cndmask_b32_e64 v115, v225, v224, s[0:1]
	v_mul_f32_e32 v114, v8, v116
	s_waitcnt lgkmcnt(0)
	v_mul_f32_e32 v115, v16, v115
	v_sub_f32_e32 v16, v114, v115
	v_add_f32_e32 v114, v114, v115
	v_cndmask_b32_e64 v114, v8, v114, s[0:1]
	v_cndmask_b32_e32 v16, v16, v114, vcc
	v_mov_b32_e32 v224, v9
	v_mov_b32_e32 v225, v9
	s_nop 1
	v_permlane16_swap_b32_e32 v224, v225
	v_cndmask_b32_e64 v115, v225, v224, s[0:1]
	v_mul_f32_e32 v114, v9, v117
	s_waitcnt lgkmcnt(0)
	v_mul_f32_e32 v115, v17, v115
	v_sub_f32_e32 v17, v114, v115
	v_add_f32_e32 v114, v114, v115
	v_cndmask_b32_e64 v114, v9, v114, s[0:1]
	v_cndmask_b32_e32 v17, v17, v114, vcc

; DI void rope8(float (&v)[8], const float* __restrict__ rope, int s, int fq) {
;     const f32x4 c0 = *(const f32x4*)(rope + s * 16), c1 = *(const f32x4*)(rope + s * 16 + 4), s0 = *(const f32x4*)(rope + s * 16 + 8), s1 = *(const f32x4*)(rope + s * 16 + 12);
;     const float cs[8] = {c0[0], c0[1], c0[2], c0[3], c1[0], c1[1], c1[2], c1[3]}, sn[8] = {s0[0], s0[1], s0[2], s0[3], s1[0], s1[1], s1[2], s1[3]};
; #pragma unroll
;     for (int e = 0; e < 8; ++e) {
;         const float other = __shfl_xor(v[e], 16);
;         const float a = v[e] * cs[e], bq = other * sn[e];
;         v[e] = (fq == 0) ? (a - bq) : ((fq == 1) ? (a + bq) : v[e]);
;     }
.LBB0_1821:
	s_andn2_b64 vcc, exec, s[8:9]
	s_cbranch_vccnz .LBB0_1871
	v_and_b32_e32 v11, 64, v188
	v_xor_b32_e32 v10, 16, v188
	v_add_u32_e32 v11, 64, v11
	v_cmp_lt_i32_e32 vcc, v10, v11
	v_lshlrev_b32_e32 v11, 6, v122
	global_load_dwordx4 v[114:117], v11, s[68:69]
	global_load_dwordx4 v[110:113], v11, s[68:69] offset:32
	global_load_dwordx4 v[14:17], v11, s[68:69] offset:48
	global_load_dwordx4 v[106:109], v11, s[68:69] offset:16
	v_cndmask_b32_e32 v10, v188, v10, vcc
	v_lshlrev_b32_e32 v123, 2, v10
	v_mov_b32_e32 v224, v2
	v_mov_b32_e32 v225, v2
	v_cmp_eq_u32_e64 s[0:1], 1, v177
	s_nop 0
	v_permlane16_swap_b32_e32 v224, v225
	v_cndmask_b32_e64 v12, v225, v224, s[0:1]
	v_cmp_lt_i32_e32 vcc, 0, v177
	s_waitcnt vmcnt(3)
	v_mul_f32_e32 v11, v2, v114
	s_waitcnt vmcnt(2) lgkmcnt(0)
	v_mul_f32_e32 v12, v110, v12
	v_sub_f32_e32 v10, v11, v12
	v_add_f32_e32 v11, v11, v12
	v_cndmask_b32_e64 v11, v2, v11, s[0:1]
	v_cndmask_b32_e32 v10, v10, v11, vcc
	v_mov_b32_e32 v224, v3
	v_mov_b32_e32 v225, v3
	s_nop 1
	v_permlane16_swap_b32_e32 v224, v225
	v_cndmask_b32_e64 v11, v225, v224, s[0:1]
	v_mul_f32_e32 v12, v3, v115
	s_waitcnt lgkmcnt(0)
	v_mul_f32_e32 v13, v111, v11
	v_sub_f32_e32 v11, v12, v13
	v_add_f32_e32 v12, v12, v13
	v_cndmask_b32_e64 v12, v3, v12, s[0:1]
	v_cndmask_b32_e32 v11, v11, v12, vcc
	v_mov_b32_e32 v224, v4
	v_mov_b32_e32 v225, v4
	s_nop 1
	v_permlane16_swap_b32_e32 v224, v225
	v_cndmask_b32_e64 v12, v225, v224, s[0:1]
	v_mul_f32_e32 v13, v4, v116
	s_waitcnt lgkmcnt(0)
	v_mul_f32_e32 v110, v112, v12
	v_sub_f32_e32 v12, v13, v110
	v_add_f32_e32 v13, v13, v110
	v_cndmask_b32_e64 v13, v4, v13, s[0:1]
	v_cndmask_b32_e32 v12, v12, v13, vcc
	v_mov_b32_e32 v224, v5
	v_mov_b32_e32 v225, v5
	s_nop 1
	v_permlane16_swap_b32_e32 v224, v225
	v_cndmask_b32_e64 v13, v225, v224, s[0:1]
	v_mul_f32_e32 v110, v5, v117
	s_waitcnt lgkmcnt(0)
	v_mul_f32_e32 v111, v113, v13
	v_sub_f32_e32 v13, v110, v111
	v_add_f32_e32 v110, v110, v111
	v_cndmask_b32_e64 v110, v5, v110, s[0:1]
	v_cndmask_b32_e32 v13, v13, v110, vcc
	v_mov_b32_e32 v224, v6
	v_mov_b32_e32 v225, v6
	s_nop 1
	v_permlane16_swap_b32_e32 v224, v225
	v_cndmask_b32_e64 v110, v225, v224, s[0:1]
	s_waitcnt vmcnt(0)
	v_mul_f32_e32 v106, v6, v106
	s_waitcnt lgkmcnt(0)
	v_mul_f32_e32 v110, v14, v110
	v_sub_f32_e32 v14, v106, v110
	v_add_f32_e32 v106, v106, v110
	v_cndmask_b32_e64 v106, v6, v106, s[0:1]
	v_cndmask_b32_e32 v14, v14, v106, vcc
	v_mov_b32_e32 v224, v7
	v_mov_b32_e32 v225, v7
	s_nop 1
	v_permlane16_swap_b32_e32 v224, v225
	v_cndmask_b32_e64 v110, v225, v224, s[0:1]
	v_mul_f32_e32 v106, v7, v107
	s_waitcnt lgkmcnt(0)
	v_mul_f32_e32 v107, v15, v110
	v_sub_f32_e32 v15, v106, v107
	v_add_f32_e32 v106, v106, v107
	v_cndmask_b32_e64 v106, v7, v106, s[0:1]
	v_cndmask_b32_e32 v15, v15, v106, vcc
	v_mov_b32_e32 v224, v8
	v_mov_b32_e32 v225, v8
	s_nop 1
	v_permlane16_swap_b32_e32 v224, v225
	v_cndmask_b32_e64 v107, v225, v224, s[0:1]
	v_mul_f32_e32 v106, v8, v108
	s_waitcnt lgkmcnt(0)
	v_mul_f32_e32 v107, v16, v107
	v_sub_f32_e32 v16, v106, v107
	v_add_f32_e32 v106, v106, v107
	v_cndmask_b32_e64 v106, v8, v106, s[0:1]
	v_cndmask_b32_e32 v16, v16, v106, vcc
	v_mov_b32_e32 v224, v9
	v_mov_b32_e32 v225, v9
	s_nop 1
	v_permlane16_swap_b32_e32 v224, v225
	v_cndmask_b32_e64 v107, v225, v224, s[0:1]
	v_mul_f32_e32 v106, v9, v109
	s_waitcnt lgkmcnt(0)
	v_mul_f32_e32 v107, v17, v107
	v_sub_f32_e32 v17, v106, v107
	v_add_f32_e32 v106, v106, v107
	v_cndmask_b32_e64 v106, v9, v106, s[0:1]
	v_cndmask_b32_e32 v17, v17, v106, vcc

; DI void rope8(float (&v)[8], const float* __restrict__ rope, int s, int fq) {
;     const f32x4 c0 = *(const f32x4*)(rope + s * 16), c1 = *(const f32x4*)(rope + s * 16 + 4), s0 = *(const f32x4*)(rope + s * 16 + 8), s1 = *(const f32x4*)(rope + s * 16 + 12);
;     const float cs[8] = {c0[0], c0[1], c0[2], c0[3], c1[0], c1[1], c1[2], c1[3]}, sn[8] = {s0[0], s0[1], s0[2], s0[3], s1[0], s1[1], s1[2], s1[3]};
; #pragma unroll
;     for (int e = 0; e < 8; ++e) {
;         const float other = __shfl_xor(v[e], 16);
;         const float a = v[e] * cs[e], bq = other * sn[e];
;         v[e] = (fq == 0) ? (a - bq) : ((fq == 1) ? (a + bq) : v[e]);
;     }
.LBB0_1886:
	s_andn2_b64 vcc, exec, s[8:9]
	s_cbranch_vccnz .LBB0_1936
	v_and_b32_e32 v11, 64, v188
	v_xor_b32_e32 v10, 16, v188
	v_add_u32_e32 v11, 64, v11
	v_cmp_lt_i32_e32 vcc, v10, v11
	v_lshlrev_b32_e32 v11, 6, v112
	global_load_dwordx4 v[106:109], v11, s[68:69]
	global_load_dwordx4 v[102:105], v11, s[68:69] offset:32
	global_load_dwordx4 v[14:17], v11, s[68:69] offset:48
	global_load_dwordx4 v[98:101], v11, s[68:69] offset:16
	v_cndmask_b32_e32 v10, v188, v10, vcc
	v_lshlrev_b32_e32 v113, 2, v10
	v_mov_b32_e32 v224, v2
	v_mov_b32_e32 v225, v2
	v_cmp_eq_u32_e64 s[0:1], 1, v177
	s_nop 0
	v_permlane16_swap_b32_e32 v224, v225
	v_cndmask_b32_e64 v12, v225, v224, s[0:1]
	v_cmp_lt_i32_e32 vcc, 0, v177
	s_waitcnt vmcnt(3)
	v_mul_f32_e32 v11, v2, v106
	s_waitcnt vmcnt(2) lgkmcnt(0)
	v_mul_f32_e32 v12, v102, v12
	v_sub_f32_e32 v10, v11, v12
	v_add_f32_e32 v11, v11, v12
	v_cndmask_b32_e64 v11, v2, v11, s[0:1]
	v_cndmask_b32_e32 v10, v10, v11, vcc
	v_mov_b32_e32 v224, v3
	v_mov_b32_e32 v225, v3
	s_nop 1
	v_permlane16_swap_b32_e32 v224, v225
	v_cndmask_b32_e64 v11, v225, v224, s[0:1]
	v_mul_f32_e32 v12, v3, v107
	s_waitcnt lgkmcnt(0)
	v_mul_f32_e32 v13, v103, v11
	v_sub_f32_e32 v11, v12, v13
	v_add_f32_e32 v12, v12, v13
	v_cndmask_b32_e64 v12, v3, v12, s[0:1]
	v_cndmask_b32_e32 v11, v11, v12, vcc
	v_mov_b32_e32 v224, v4
	v_mov_b32_e32 v225, v4
	s_nop 1
	v_permlane16_swap_b32_e32 v224, v225
	v_cndmask_b32_e64 v12, v225, v224, s[0:1]
	v_mul_f32_e32 v13, v4, v108
	s_waitcnt lgkmcnt(0)
	v_mul_f32_e32 v102, v104, v12
	v_sub_f32_e32 v12, v13, v102
	v_add_f32_e32 v13, v13, v102
	v_cndmask_b32_e64 v13, v4, v13, s[0:1]
	v_cndmask_b32_e32 v12, v12, v13, vcc
	v_mov_b32_e32 v224, v5
	v_mov_b32_e32 v225, v5
	s_nop 1
	v_permlane16_swap_b32_e32 v224, v225
	v_cndmask_b32_e64 v13, v225, v224, s[0:1]
	v_mul_f32_e32 v102, v5, v109
	s_waitcnt lgkmcnt(0)
	v_mul_f32_e32 v103, v105, v13
	v_sub_f32_e32 v13, v102, v103
	v_add_f32_e32 v102, v102, v103
	v_cndmask_b32_e64 v102, v5, v102, s[0:1]
	v_cndmask_b32_e32 v13, v13, v102, vcc
	v_mov_b32_e32 v224, v6
	v_mov_b32_e32 v225, v6
	s_nop 1
	v_permlane16_swap_b32_e32 v224, v225
	v_cndmask_b32_e64 v102, v225, v224, s[0:1]
	s_waitcnt vmcnt(0)
	v_mul_f32_e32 v98, v6, v98
	s_waitcnt lgkmcnt(0)
	v_mul_f32_e32 v102, v14, v102
	v_sub_f32_e32 v14, v98, v102
	v_add_f32_e32 v98, v98, v102
	v_cndmask_b32_e64 v98, v6, v98, s[0:1]
	v_cndmask_b32_e32 v14, v14, v98, vcc
	v_mov_b32_e32 v224, v7
	v_mov_b32_e32 v225, v7
	s_nop 1
	v_permlane16_swap_b32_e32 v224, v225
	v_cndmask_b32_e64 v102, v225, v224, s[0:1]
	v_mul_f32_e32 v98, v7, v99
	s_waitcnt lgkmcnt(0)
	v_mul_f32_e32 v99, v15, v102
	v_sub_f32_e32 v15, v98, v99
	v_add_f32_e32 v98, v98, v99
	v_cndmask_b32_e64 v98, v7, v98, s[0:1]
	v_cndmask_b32_e32 v15, v15, v98, vcc
	v_mov_b32_e32 v224, v8
	v_mov_b32_e32 v225, v8
	s_nop 1
	v_permlane16_swap_b32_e32 v224, v225
	v_cndmask_b32_e64 v99, v225, v224, s[0:1]
	v_mul_f32_e32 v98, v8, v100
	s_waitcnt lgkmcnt(0)
	v_mul_f32_e32 v99, v16, v99
	v_sub_f32_e32 v16, v98, v99
	v_add_f32_e32 v98, v98, v99
	v_cndmask_b32_e64 v98, v8, v98, s[0:1]
	v_cndmask_b32_e32 v16, v16, v98, vcc
	v_mov_b32_e32 v224, v9
	v_mov_b32_e32 v225, v9
	s_nop 1
	v_permlane16_swap_b32_e32 v224, v225
	v_cndmask_b32_e64 v99, v225, v224, s[0:1]
	v_mul_f32_e32 v98, v9, v101
	s_waitcnt lgkmcnt(0)
	v_mul_f32_e32 v99, v17, v99
	v_sub_f32_e32 v17, v98, v99
	v_add_f32_e32 v98, v98, v99
	v_cndmask_b32_e64 v98, v9, v98, s[0:1]
	v_cndmask_b32_e32 v17, v17, v98, vcc

; DI void rope8(float (&v)[8], const float* __restrict__ rope, int s, int fq) {
;     const f32x4 c0 = *(const f32x4*)(rope + s * 16), c1 = *(const f32x4*)(rope + s * 16 + 4), s0 = *(const f32x4*)(rope + s * 16 + 8), s1 = *(const f32x4*)(rope + s * 16 + 12);
;     const float cs[8] = {c0[0], c0[1], c0[2], c0[3], c1[0], c1[1], c1[2], c1[3]}, sn[8] = {s0[0], s0[1], s0[2], s0[3], s1[0], s1[1], s1[2], s1[3]};
; #pragma unroll
;     for (int e = 0; e < 8; ++e) {
;         const float other = __shfl_xor(v[e], 16);
;         const float a = v[e] * cs[e], bq = other * sn[e];
;         v[e] = (fq == 0) ? (a - bq) : ((fq == 1) ? (a + bq) : v[e]);
;     }
.LBB0_1951:
	s_andn2_b64 vcc, exec, s[8:9]
	s_cbranch_vccnz .LBB0_2001
	v_and_b32_e32 v11, 64, v188
	v_xor_b32_e32 v10, 16, v188
	v_add_u32_e32 v11, 64, v11
	v_cmp_lt_i32_e32 vcc, v10, v11
	v_lshlrev_b32_e32 v11, 6, v104
	global_load_dwordx4 v[98:101], v11, s[68:69]
	global_load_dwordx4 v[94:97], v11, s[68:69] offset:32
	global_load_dwordx4 v[14:17], v11, s[68:69] offset:48
	global_load_dwordx4 v[90:93], v11, s[68:69] offset:16
	v_cndmask_b32_e32 v10, v188, v10, vcc
	v_lshlrev_b32_e32 v105, 2, v10
	v_mov_b32_e32 v224, v2
	v_mov_b32_e32 v225, v2
	v_cmp_eq_u32_e64 s[0:1], 1, v177
	s_nop 0
	v_permlane16_swap_b32_e32 v224, v225
	v_cndmask_b32_e64 v12, v225, v224, s[0:1]
	v_cmp_lt_i32_e32 vcc, 0, v177
	s_waitcnt vmcnt(3)
	v_mul_f32_e32 v11, v2, v98
	s_waitcnt vmcnt(2) lgkmcnt(0)
	v_mul_f32_e32 v12, v94, v12
	v_sub_f32_e32 v10, v11, v12
	v_add_f32_e32 v11, v11, v12
	v_cndmask_b32_e64 v11, v2, v11, s[0:1]
	v_cndmask_b32_e32 v10, v10, v11, vcc
	v_mov_b32_e32 v224, v3
	v_mov_b32_e32 v225, v3
	s_nop 1
	v_permlane16_swap_b32_e32 v224, v225
	v_cndmask_b32_e64 v11, v225, v224, s[0:1]
	v_mul_f32_e32 v12, v3, v99
	s_waitcnt lgkmcnt(0)
	v_mul_f32_e32 v13, v95, v11
	v_sub_f32_e32 v11, v12, v13
	v_add_f32_e32 v12, v12, v13
	v_cndmask_b32_e64 v12, v3, v12, s[0:1]
	v_cndmask_b32_e32 v11, v11, v12, vcc
	v_mov_b32_e32 v224, v4
	v_mov_b32_e32 v225, v4
	s_nop 1
	v_permlane16_swap_b32_e32 v224, v225
	v_cndmask_b32_e64 v12, v225, v224, s[0:1]
	v_mul_f32_e32 v13, v4, v100
	s_waitcnt lgkmcnt(0)
	v_mul_f32_e32 v94, v96, v12
	v_sub_f32_e32 v12, v13, v94
	v_add_f32_e32 v13, v13, v94
	v_cndmask_b32_e64 v13, v4, v13, s[0:1]
	v_cndmask_b32_e32 v12, v12, v13, vcc
	v_mov_b32_e32 v224, v5
	v_mov_b32_e32 v225, v5
	s_nop 1
	v_permlane16_swap_b32_e32 v224, v225
	v_cndmask_b32_e64 v13, v225, v224, s[0:1]
	v_mul_f32_e32 v94, v5, v101
	s_waitcnt lgkmcnt(0)
	v_mul_f32_e32 v95, v97, v13
	v_sub_f32_e32 v13, v94, v95
	v_add_f32_e32 v94, v94, v95
	v_cndmask_b32_e64 v94, v5, v94, s[0:1]
	v_cndmask_b32_e32 v13, v13, v94, vcc
	v_mov_b32_e32 v224, v6
	v_mov_b32_e32 v225, v6
	s_nop 1
	v_permlane16_swap_b32_e32 v224, v225
	v_cndmask_b32_e64 v94, v225, v224, s[0:1]
	s_waitcnt vmcnt(0)
	v_mul_f32_e32 v90, v6, v90
	s_waitcnt lgkmcnt(0)
	v_mul_f32_e32 v94, v14, v94
	v_sub_f32_e32 v14, v90, v94
	v_add_f32_e32 v90, v90, v94
	v_cndmask_b32_e64 v90, v6, v90, s[0:1]
	v_cndmask_b32_e32 v14, v14, v90, vcc
	v_mov_b32_e32 v224, v7
	v_mov_b32_e32 v225, v7
	s_nop 1
	v_permlane16_swap_b32_e32 v224, v225
	v_cndmask_b32_e64 v94, v225, v224, s[0:1]
	v_mul_f32_e32 v90, v7, v91
	s_waitcnt lgkmcnt(0)
	v_mul_f32_e32 v91, v15, v94
	v_sub_f32_e32 v15, v90, v91
	v_add_f32_e32 v90, v90, v91
	v_cndmask_b32_e64 v90, v7, v90, s[0:1]
	v_cndmask_b32_e32 v15, v15, v90, vcc
	v_mov_b32_e32 v224, v8
	v_mov_b32_e32 v225, v8
	s_nop 1
	v_permlane16_swap_b32_e32 v224, v225
	v_cndmask_b32_e64 v91, v225, v224, s[0:1]
	v_mul_f32_e32 v90, v8, v92
	s_waitcnt lgkmcnt(0)
	v_mul_f32_e32 v91, v16, v91
	v_sub_f32_e32 v16, v90, v91
	v_add_f32_e32 v90, v90, v91
	v_cndmask_b32_e64 v90, v8, v90, s[0:1]
	v_cndmask_b32_e32 v16, v16, v90, vcc
	v_mov_b32_e32 v224, v9
	v_mov_b32_e32 v225, v9
	s_nop 1
	v_permlane16_swap_b32_e32 v224, v225
	v_cndmask_b32_e64 v91, v225, v224, s[0:1]
	v_mul_f32_e32 v90, v9, v93
	s_waitcnt lgkmcnt(0)
	v_mul_f32_e32 v91, v17, v91
	v_sub_f32_e32 v17, v90, v91
	v_add_f32_e32 v90, v90, v91
	v_cndmask_b32_e64 v90, v9, v90, s[0:1]
	v_cndmask_b32_e32 v17, v17, v90, vcc

; DI void rope8(float (&v)[8], const float* __restrict__ rope, int s, int fq) {
;     const f32x4 c0 = *(const f32x4*)(rope + s * 16), c1 = *(const f32x4*)(rope + s * 16 + 4), s0 = *(const f32x4*)(rope + s * 16 + 8), s1 = *(const f32x4*)(rope + s * 16 + 12);
;     const float cs[8] = {c0[0], c0[1], c0[2], c0[3], c1[0], c1[1], c1[2], c1[3]}, sn[8] = {s0[0], s0[1], s0[2], s0[3], s1[0], s1[1], s1[2], s1[3]};
; #pragma unroll
;     for (int e = 0; e < 8; ++e) {
;         const float other = __shfl_xor(v[e], 16);
;         const float a = v[e] * cs[e], bq = other * sn[e];
;         v[e] = (fq == 0) ? (a - bq) : ((fq == 1) ? (a + bq) : v[e]);
;     }
.LBB0_2016:
	s_andn2_b64 vcc, exec, s[6:7]
	s_cbranch_vccnz .LBB0_2066
	v_and_b32_e32 v11, 64, v188
	v_xor_b32_e32 v10, 16, v188
	v_add_u32_e32 v11, 64, v11
	v_cmp_lt_i32_e32 vcc, v10, v11
	v_lshlrev_b32_e32 v11, 6, v96
	global_load_dwordx4 v[90:93], v11, s[68:69]
	global_load_dwordx4 v[86:89], v11, s[68:69] offset:32
	global_load_dwordx4 v[14:17], v11, s[68:69] offset:48
	global_load_dwordx4 v[82:85], v11, s[68:69] offset:16
	v_cndmask_b32_e32 v10, v188, v10, vcc
	v_lshlrev_b32_e32 v97, 2, v10
	v_mov_b32_e32 v224, v2
	v_mov_b32_e32 v225, v2
	v_cmp_eq_u32_e64 s[0:1], 1, v177
	s_nop 0
	v_permlane16_swap_b32_e32 v224, v225
	v_cndmask_b32_e64 v12, v225, v224, s[0:1]
	v_cmp_lt_i32_e32 vcc, 0, v177
	s_waitcnt vmcnt(3)
	v_mul_f32_e32 v11, v2, v90
	s_waitcnt vmcnt(2) lgkmcnt(0)
	v_mul_f32_e32 v12, v86, v12
	v_sub_f32_e32 v10, v11, v12
	v_add_f32_e32 v11, v11, v12
	v_cndmask_b32_e64 v11, v2, v11, s[0:1]
	v_cndmask_b32_e32 v10, v10, v11, vcc
	v_mov_b32_e32 v224, v3
	v_mov_b32_e32 v225, v3
	s_nop 1
	v_permlane16_swap_b32_e32 v224, v225
	v_cndmask_b32_e64 v11, v225, v224, s[0:1]
	v_mul_f32_e32 v12, v3, v91
	s_waitcnt lgkmcnt(0)
	v_mul_f32_e32 v13, v87, v11
	v_sub_f32_e32 v11, v12, v13
	v_add_f32_e32 v12, v12, v13
	v_cndmask_b32_e64 v12, v3, v12, s[0:1]
	v_cndmask_b32_e32 v11, v11, v12, vcc
	v_mov_b32_e32 v224, v4
	v_mov_b32_e32 v225, v4
	s_nop 1
	v_permlane16_swap_b32_e32 v224, v225
	v_cndmask_b32_e64 v12, v225, v224, s[0:1]
	v_mul_f32_e32 v13, v4, v92
	s_waitcnt lgkmcnt(0)
	v_mul_f32_e32 v86, v88, v12
	v_sub_f32_e32 v12, v13, v86
	v_add_f32_e32 v13, v13, v86
	v_cndmask_b32_e64 v13, v4, v13, s[0:1]
	v_cndmask_b32_e32 v12, v12, v13, vcc
	v_mov_b32_e32 v224, v5
	v_mov_b32_e32 v225, v5
	s_nop 1
	v_permlane16_swap_b32_e32 v224, v225
	v_cndmask_b32_e64 v13, v225, v224, s[0:1]
	v_mul_f32_e32 v86, v5, v93
	s_waitcnt lgkmcnt(0)
	v_mul_f32_e32 v87, v89, v13
	v_sub_f32_e32 v13, v86, v87
	v_add_f32_e32 v86, v86, v87
	v_cndmask_b32_e64 v86, v5, v86, s[0:1]
	v_cndmask_b32_e32 v13, v13, v86, vcc
	v_mov_b32_e32 v224, v6
	v_mov_b32_e32 v225, v6
	s_nop 1
	v_permlane16_swap_b32_e32 v224, v225
	v_cndmask_b32_e64 v86, v225, v224, s[0:1]
	s_waitcnt vmcnt(0)
	v_mul_f32_e32 v82, v6, v82
	s_waitcnt lgkmcnt(0)
	v_mul_f32_e32 v86, v14, v86
	v_sub_f32_e32 v14, v82, v86
	v_add_f32_e32 v82, v82, v86
	v_cndmask_b32_e64 v82, v6, v82, s[0:1]
	v_cndmask_b32_e32 v14, v14, v82, vcc
	v_mov_b32_e32 v224, v7
	v_mov_b32_e32 v225, v7
	s_nop 1
	v_permlane16_swap_b32_e32 v224, v225
	v_cndmask_b32_e64 v86, v225, v224, s[0:1]
	v_mul_f32_e32 v82, v7, v83
	s_waitcnt lgkmcnt(0)
	v_mul_f32_e32 v83, v15, v86
	v_sub_f32_e32 v15, v82, v83
	v_add_f32_e32 v82, v82, v83
	v_cndmask_b32_e64 v82, v7, v82, s[0:1]
	v_cndmask_b32_e32 v15, v15, v82, vcc
	v_mov_b32_e32 v224, v8
	v_mov_b32_e32 v225, v8
	s_nop 1
	v_permlane16_swap_b32_e32 v224, v225
	v_cndmask_b32_e64 v83, v225, v224, s[0:1]
	v_mul_f32_e32 v82, v8, v84
	s_waitcnt lgkmcnt(0)
	v_mul_f32_e32 v83, v16, v83
	v_sub_f32_e32 v16, v82, v83
	v_add_f32_e32 v82, v82, v83
	v_cndmask_b32_e64 v82, v8, v82, s[0:1]
	v_cndmask_b32_e32 v16, v16, v82, vcc
	v_mov_b32_e32 v224, v9
	v_mov_b32_e32 v225, v9
	s_nop 1
	v_permlane16_swap_b32_e32 v224, v225
	v_cndmask_b32_e64 v83, v225, v224, s[0:1]
	v_mul_f32_e32 v82, v9, v85
	s_waitcnt lgkmcnt(0)
	v_mul_f32_e32 v83, v17, v83
	v_sub_f32_e32 v17, v82, v83
	v_add_f32_e32 v82, v82, v83
	v_cndmask_b32_e64 v82, v9, v82, s[0:1]
	v_cndmask_b32_e32 v17, v17, v82, vcc

; DI void rope8(float (&v)[8], const float* __restrict__ rope, int s, int fq) {
;     const f32x4 c0 = *(const f32x4*)(rope + s * 16), c1 = *(const f32x4*)(rope + s * 16 + 4), s0 = *(const f32x4*)(rope + s * 16 + 8), s1 = *(const f32x4*)(rope + s * 16 + 12);
;     const float cs[8] = {c0[0], c0[1], c0[2], c0[3], c1[0], c1[1], c1[2], c1[3]}, sn[8] = {s0[0], s0[1], s0[2], s0[3], s1[0], s1[1], s1[2], s1[3]};
; #pragma unroll
;     for (int e = 0; e < 8; ++e) {
;         const float other = __shfl_xor(v[e], 16);
;         const float a = v[e] * cs[e], bq = other * sn[e];
;         v[e] = (fq == 0) ? (a - bq) : ((fq == 1) ? (a + bq) : v[e]);
;     }
.LBB0_2082:
	s_andn2_b64 vcc, exec, s[10:11]
	s_cbranch_vccnz .LBB0_2132
	v_and_b32_e32 v11, 64, v188
	v_xor_b32_e32 v10, 16, v188
	v_add_u32_e32 v11, 64, v11
	v_cmp_lt_i32_e32 vcc, v10, v11
	v_lshlrev_b32_e32 v74, 6, v83
	s_nop 0
	v_cndmask_b32_e32 v10, v188, v10, vcc
	v_lshlrev_b32_e32 v86, 2, v10
	global_load_dwordx4 v[78:81], v74, s[68:69]
	global_load_dwordx4 v[10:13], v74, s[68:69] offset:32
	global_load_dwordx4 v[14:17], v74, s[68:69] offset:48
	s_nop 0
	global_load_dwordx4 v[74:77], v74, s[68:69] offset:16
	v_mov_b32_e32 v224, v2
	v_mov_b32_e32 v225, v2
	v_cmp_eq_u32_e64 s[10:11], 1, v177
	s_nop 0
	v_permlane16_swap_b32_e32 v224, v225
	v_cndmask_b32_e64 v87, v225, v224, s[10:11]
	v_cmp_lt_i32_e32 vcc, 0, v177
	s_waitcnt vmcnt(3)
	v_mul_f32_e32 v78, v2, v78
	s_waitcnt vmcnt(2) lgkmcnt(0)
	v_mul_f32_e32 v87, v10, v87
	v_sub_f32_e32 v10, v78, v87
	v_add_f32_e32 v78, v78, v87
	v_cndmask_b32_e64 v78, v2, v78, s[10:11]
	v_cndmask_b32_e32 v10, v10, v78, vcc
	v_mov_b32_e32 v224, v3
	v_mov_b32_e32 v225, v3
	s_nop 1
	v_permlane16_swap_b32_e32 v224, v225
	v_cndmask_b32_e64 v87, v225, v224, s[10:11]
	v_mul_f32_e32 v78, v3, v79
	s_waitcnt lgkmcnt(0)
	v_mul_f32_e32 v79, v11, v87
	v_sub_f32_e32 v11, v78, v79
	v_add_f32_e32 v78, v78, v79
	v_cndmask_b32_e64 v78, v3, v78, s[10:11]
	v_cndmask_b32_e32 v11, v11, v78, vcc
	v_mov_b32_e32 v224, v4
	v_mov_b32_e32 v225, v4
	s_nop 1
	v_permlane16_swap_b32_e32 v224, v225
	v_cndmask_b32_e64 v79, v225, v224, s[10:11]
	v_mul_f32_e32 v78, v4, v80
	s_waitcnt lgkmcnt(0)
	v_mul_f32_e32 v79, v12, v79
	v_sub_f32_e32 v12, v78, v79
	v_add_f32_e32 v78, v78, v79
	v_cndmask_b32_e64 v78, v4, v78, s[10:11]
	v_cndmask_b32_e32 v12, v12, v78, vcc
	v_mov_b32_e32 v224, v5
	v_mov_b32_e32 v225, v5
	s_nop 1
	v_permlane16_swap_b32_e32 v224, v225
	v_cndmask_b32_e64 v79, v225, v224, s[10:11]
	v_mul_f32_e32 v78, v5, v81
	s_waitcnt lgkmcnt(0)
	v_mul_f32_e32 v79, v13, v79
	v_sub_f32_e32 v13, v78, v79
	v_add_f32_e32 v78, v78, v79
	v_cndmask_b32_e64 v78, v5, v78, s[10:11]
	v_cndmask_b32_e32 v13, v13, v78, vcc
	v_mov_b32_e32 v224, v6
	v_mov_b32_e32 v225, v6
	s_nop 1
	v_permlane16_swap_b32_e32 v224, v225
	v_cndmask_b32_e64 v78, v225, v224, s[10:11]
	s_waitcnt vmcnt(0)
	v_mul_f32_e32 v74, v6, v74
	s_waitcnt lgkmcnt(0)
	v_mul_f32_e32 v78, v14, v78
	v_sub_f32_e32 v14, v74, v78
	v_add_f32_e32 v74, v74, v78
	v_cndmask_b32_e64 v74, v6, v74, s[10:11]
	v_cndmask_b32_e32 v14, v14, v74, vcc
	v_mov_b32_e32 v224, v7
	v_mov_b32_e32 v225, v7
	s_nop 1
	v_permlane16_swap_b32_e32 v224, v225
	v_cndmask_b32_e64 v78, v225, v224, s[10:11]
	v_mul_f32_e32 v74, v7, v75
	s_waitcnt lgkmcnt(0)
	v_mul_f32_e32 v75, v15, v78
	v_sub_f32_e32 v15, v74, v75
	v_add_f32_e32 v74, v74, v75
	v_cndmask_b32_e64 v74, v7, v74, s[10:11]
	v_cndmask_b32_e32 v15, v15, v74, vcc
	v_mov_b32_e32 v224, v8
	v_mov_b32_e32 v225, v8
	s_nop 1
	v_permlane16_swap_b32_e32 v224, v225
	v_cndmask_b32_e64 v75, v225, v224, s[10:11]
	v_mul_f32_e32 v74, v8, v76
	s_waitcnt lgkmcnt(0)
	v_mul_f32_e32 v75, v16, v75
	v_sub_f32_e32 v16, v74, v75
	v_add_f32_e32 v74, v74, v75
	v_cndmask_b32_e64 v74, v8, v74, s[10:11]
	v_cndmask_b32_e32 v16, v16, v74, vcc
	v_mov_b32_e32 v224, v9
	v_mov_b32_e32 v225, v9
	s_nop 1
	v_permlane16_swap_b32_e32 v224, v225
	v_cndmask_b32_e64 v75, v225, v224, s[10:11]
	v_mul_f32_e32 v74, v9, v77
	s_waitcnt lgkmcnt(0)
	v_mul_f32_e32 v75, v17, v75
	v_sub_f32_e32 v17, v74, v75
	v_add_f32_e32 v74, v74, v75
	v_cndmask_b32_e64 v74, v9, v74, s[10:11]
	v_cndmask_b32_e32 v17, v17, v74, vcc

; DI void rope8(float (&v)[8], const float* __restrict__ rope, int s, int fq) {
;     const f32x4 c0 = *(const f32x4*)(rope + s * 16), c1 = *(const f32x4*)(rope + s * 16 + 4), s0 = *(const f32x4*)(rope + s * 16 + 8), s1 = *(const f32x4*)(rope + s * 16 + 12);
;     const float cs[8] = {c0[0], c0[1], c0[2], c0[3], c1[0], c1[1], c1[2], c1[3]}, sn[8] = {s0[0], s0[1], s0[2], s0[3], s1[0], s1[1], s1[2], s1[3]};
; #pragma unroll
;     for (int e = 0; e < 8; ++e) {
;         const float other = __shfl_xor(v[e], 16);
;         const float a = v[e] * cs[e], bq = other * sn[e];
;         v[e] = (fq == 0) ? (a - bq) : ((fq == 1) ? (a + bq) : v[e]);
;     }
.LBB0_2138:
	s_andn2_b64 vcc, exec, s[10:11]
	s_cbranch_vccnz .LBB0_2188
	v_and_b32_e32 v11, 64, v188
	v_xor_b32_e32 v10, 16, v188
	v_add_u32_e32 v11, 64, v11
	v_cmp_lt_i32_e32 vcc, v10, v11
	v_lshlrev_b32_e32 v66, 6, v77
	s_nop 0
	v_cndmask_b32_e32 v10, v188, v10, vcc
	v_lshlrev_b32_e32 v79, 2, v10
	global_load_dwordx4 v[70:73], v66, s[68:69]
	global_load_dwordx4 v[10:13], v66, s[68:69] offset:32
	global_load_dwordx4 v[14:17], v66, s[68:69] offset:48
	s_nop 0
	global_load_dwordx4 v[66:69], v66, s[68:69] offset:16
	v_mov_b32_e32 v224, v2
	v_mov_b32_e32 v225, v2
	v_cmp_eq_u32_e64 s[0:1], 1, v177
	s_nop 0
	v_permlane16_swap_b32_e32 v224, v225
	v_cndmask_b32_e64 v80, v225, v224, s[0:1]
	v_cmp_lt_i32_e32 vcc, 0, v177
	s_waitcnt vmcnt(3)
	v_mul_f32_e32 v70, v2, v70
	s_waitcnt vmcnt(2) lgkmcnt(0)
	v_mul_f32_e32 v80, v10, v80
	v_sub_f32_e32 v10, v70, v80
	v_add_f32_e32 v70, v70, v80
	v_cndmask_b32_e64 v70, v2, v70, s[0:1]
	v_cndmask_b32_e32 v10, v10, v70, vcc
	v_mov_b32_e32 v224, v3
	v_mov_b32_e32 v225, v3
	s_nop 1
	v_permlane16_swap_b32_e32 v224, v225
	v_cndmask_b32_e64 v80, v225, v224, s[0:1]
	v_mul_f32_e32 v70, v3, v71
	s_waitcnt lgkmcnt(0)
	v_mul_f32_e32 v71, v11, v80
	v_sub_f32_e32 v11, v70, v71
	v_add_f32_e32 v70, v70, v71
	v_cndmask_b32_e64 v70, v3, v70, s[0:1]
	v_cndmask_b32_e32 v11, v11, v70, vcc
	v_mov_b32_e32 v224, v4
	v_mov_b32_e32 v225, v4
	s_nop 1
	v_permlane16_swap_b32_e32 v224, v225
	v_cndmask_b32_e64 v71, v225, v224, s[0:1]
	v_mul_f32_e32 v70, v4, v72
	s_waitcnt lgkmcnt(0)
	v_mul_f32_e32 v71, v12, v71
	v_sub_f32_e32 v12, v70, v71
	v_add_f32_e32 v70, v70, v71
	v_cndmask_b32_e64 v70, v4, v70, s[0:1]
	v_cndmask_b32_e32 v12, v12, v70, vcc
	v_mov_b32_e32 v224, v5
	v_mov_b32_e32 v225, v5
	s_nop 1
	v_permlane16_swap_b32_e32 v224, v225
	v_cndmask_b32_e64 v71, v225, v224, s[0:1]
	v_mul_f32_e32 v70, v5, v73
	s_waitcnt lgkmcnt(0)
	v_mul_f32_e32 v71, v13, v71
	v_sub_f32_e32 v13, v70, v71
	v_add_f32_e32 v70, v70, v71
	v_cndmask_b32_e64 v70, v5, v70, s[0:1]
	v_cndmask_b32_e32 v13, v13, v70, vcc
	v_mov_b32_e32 v224, v6
	v_mov_b32_e32 v225, v6
	s_nop 1
	v_permlane16_swap_b32_e32 v224, v225
	v_cndmask_b32_e64 v70, v225, v224, s[0:1]
	s_waitcnt vmcnt(0)
	v_mul_f32_e32 v66, v6, v66
	s_waitcnt lgkmcnt(0)
	v_mul_f32_e32 v70, v14, v70
	v_sub_f32_e32 v14, v66, v70
	v_add_f32_e32 v66, v66, v70
	v_cndmask_b32_e64 v66, v6, v66, s[0:1]
	v_cndmask_b32_e32 v14, v14, v66, vcc
	v_mov_b32_e32 v224, v7
	v_mov_b32_e32 v225, v7
	s_nop 1
	v_permlane16_swap_b32_e32 v224, v225
	v_cndmask_b32_e64 v70, v225, v224, s[0:1]
	v_mul_f32_e32 v66, v7, v67
	s_waitcnt lgkmcnt(0)
	v_mul_f32_e32 v67, v15, v70
	v_sub_f32_e32 v15, v66, v67
	v_add_f32_e32 v66, v66, v67
	v_cndmask_b32_e64 v66, v7, v66, s[0:1]
	v_cndmask_b32_e32 v15, v15, v66, vcc
	v_mov_b32_e32 v224, v8
	v_mov_b32_e32 v225, v8
	s_nop 1
	v_permlane16_swap_b32_e32 v224, v225
	v_cndmask_b32_e64 v67, v225, v224, s[0:1]
	v_mul_f32_e32 v66, v8, v68
	s_waitcnt lgkmcnt(0)
	v_mul_f32_e32 v67, v16, v67
	v_sub_f32_e32 v16, v66, v67
	v_add_f32_e32 v66, v66, v67
	v_cndmask_b32_e64 v66, v8, v66, s[0:1]
	v_cndmask_b32_e32 v16, v16, v66, vcc
	v_mov_b32_e32 v224, v9
	v_mov_b32_e32 v225, v9
	s_nop 1
	v_permlane16_swap_b32_e32 v224, v225
	v_cndmask_b32_e64 v67, v225, v224, s[0:1]
	v_mul_f32_e32 v66, v9, v69
	s_waitcnt lgkmcnt(0)
	v_mul_f32_e32 v67, v17, v67
	v_sub_f32_e32 v17, v66, v67
	v_add_f32_e32 v66, v66, v67
	v_cndmask_b32_e64 v66, v9, v66, s[0:1]
	v_cndmask_b32_e32 v17, v17, v66, vcc

; DI void rope8(float (&v)[8], const float* __restrict__ rope, int s, int fq) {
;     const f32x4 c0 = *(const f32x4*)(rope + s * 16), c1 = *(const f32x4*)(rope + s * 16 + 4), s0 = *(const f32x4*)(rope + s * 16 + 8), s1 = *(const f32x4*)(rope + s * 16 + 12);
;     const float cs[8] = {c0[0], c0[1], c0[2], c0[3], c1[0], c1[1], c1[2], c1[3]}, sn[8] = {s0[0], s0[1], s0[2], s0[3], s1[0], s1[1], s1[2], s1[3]};
; #pragma unroll
;     for (int e = 0; e < 8; ++e) {
;         const float other = __shfl_xor(v[e], 16);
;         const float a = v[e] * cs[e], bq = other * sn[e];
;         v[e] = (fq == 0) ? (a - bq) : ((fq == 1) ? (a + bq) : v[e]);
;     }
.LBB0_2194:
	s_andn2_b64 vcc, exec, s[10:11]
	s_cbranch_vccnz .LBB0_2244
	v_and_b32_e32 v11, 64, v188
	v_xor_b32_e32 v10, 16, v188
	v_add_u32_e32 v11, 64, v11
	v_cmp_lt_i32_e32 vcc, v10, v11
	v_lshlrev_b32_e32 v58, 6, v67
	s_nop 0
	v_cndmask_b32_e32 v10, v188, v10, vcc
	v_lshlrev_b32_e32 v68, 2, v10
	global_load_dwordx4 v[62:65], v58, s[68:69]
	global_load_dwordx4 v[10:13], v58, s[68:69] offset:32
	global_load_dwordx4 v[14:17], v58, s[68:69] offset:48
	s_nop 0
	global_load_dwordx4 v[58:61], v58, s[68:69] offset:16
	v_mov_b32_e32 v224, v2
	v_mov_b32_e32 v225, v2
	v_cmp_eq_u32_e64 s[0:1], 1, v177
	s_nop 0
	v_permlane16_swap_b32_e32 v224, v225
	v_cndmask_b32_e64 v69, v225, v224, s[0:1]
	v_cmp_lt_i32_e32 vcc, 0, v177
	s_waitcnt vmcnt(3)
	v_mul_f32_e32 v62, v2, v62
	s_waitcnt vmcnt(2) lgkmcnt(0)
	v_mul_f32_e32 v69, v10, v69
	v_sub_f32_e32 v10, v62, v69
	v_add_f32_e32 v62, v62, v69
	v_cndmask_b32_e64 v62, v2, v62, s[0:1]
	v_cndmask_b32_e32 v10, v10, v62, vcc
	v_mov_b32_e32 v224, v3
	v_mov_b32_e32 v225, v3
	s_nop 1
	v_permlane16_swap_b32_e32 v224, v225
	v_cndmask_b32_e64 v69, v225, v224, s[0:1]
	v_mul_f32_e32 v62, v3, v63
	s_waitcnt lgkmcnt(0)
	v_mul_f32_e32 v63, v11, v69
	v_sub_f32_e32 v11, v62, v63
	v_add_f32_e32 v62, v62, v63
	v_cndmask_b32_e64 v62, v3, v62, s[0:1]
	v_cndmask_b32_e32 v11, v11, v62, vcc
	v_mov_b32_e32 v224, v4
	v_mov_b32_e32 v225, v4
	s_nop 1
	v_permlane16_swap_b32_e32 v224, v225
	v_cndmask_b32_e64 v63, v225, v224, s[0:1]
	v_mul_f32_e32 v62, v4, v64
	s_waitcnt lgkmcnt(0)
	v_mul_f32_e32 v63, v12, v63
	v_sub_f32_e32 v12, v62, v63
	v_add_f32_e32 v62, v62, v63
	v_cndmask_b32_e64 v62, v4, v62, s[0:1]
	v_cndmask_b32_e32 v12, v12, v62, vcc
	v_mov_b32_e32 v224, v5
	v_mov_b32_e32 v225, v5
	s_nop 1
	v_permlane16_swap_b32_e32 v224, v225
	v_cndmask_b32_e64 v63, v225, v224, s[0:1]
	v_mul_f32_e32 v62, v5, v65
	s_waitcnt lgkmcnt(0)
	v_mul_f32_e32 v63, v13, v63
	v_sub_f32_e32 v13, v62, v63
	v_add_f32_e32 v62, v62, v63
	v_cndmask_b32_e64 v62, v5, v62, s[0:1]
	v_cndmask_b32_e32 v13, v13, v62, vcc
	v_mov_b32_e32 v224, v6
	v_mov_b32_e32 v225, v6
	s_nop 1
	v_permlane16_swap_b32_e32 v224, v225
	v_cndmask_b32_e64 v62, v225, v224, s[0:1]
	s_waitcnt vmcnt(0)
	v_mul_f32_e32 v58, v6, v58
	s_waitcnt lgkmcnt(0)
	v_mul_f32_e32 v62, v14, v62
	v_sub_f32_e32 v14, v58, v62
	v_add_f32_e32 v58, v58, v62
	v_cndmask_b32_e64 v58, v6, v58, s[0:1]
	v_cndmask_b32_e32 v14, v14, v58, vcc
	v_mov_b32_e32 v224, v7
	v_mov_b32_e32 v225, v7
	s_nop 1
	v_permlane16_swap_b32_e32 v224, v225
	v_cndmask_b32_e64 v62, v225, v224, s[0:1]
	v_mul_f32_e32 v58, v7, v59
	s_waitcnt lgkmcnt(0)
	v_mul_f32_e32 v59, v15, v62
	v_sub_f32_e32 v15, v58, v59
	v_add_f32_e32 v58, v58, v59
	v_cndmask_b32_e64 v58, v7, v58, s[0:1]
	v_cndmask_b32_e32 v15, v15, v58, vcc
	v_mov_b32_e32 v224, v8
	v_mov_b32_e32 v225, v8
	s_nop 1
	v_permlane16_swap_b32_e32 v224, v225
	v_cndmask_b32_e64 v59, v225, v224, s[0:1]
	v_mul_f32_e32 v58, v8, v60
	s_waitcnt lgkmcnt(0)
	v_mul_f32_e32 v59, v16, v59
	v_sub_f32_e32 v16, v58, v59
	v_add_f32_e32 v58, v58, v59
	v_cndmask_b32_e64 v58, v8, v58, s[0:1]
	v_cndmask_b32_e32 v16, v16, v58, vcc
	v_mov_b32_e32 v224, v9
	v_mov_b32_e32 v225, v9
	s_nop 1
	v_permlane16_swap_b32_e32 v224, v225
	v_cndmask_b32_e64 v59, v225, v224, s[0:1]
	v_mul_f32_e32 v58, v9, v61
	s_waitcnt lgkmcnt(0)
	v_mul_f32_e32 v59, v17, v59
	v_sub_f32_e32 v17, v58, v59
	v_add_f32_e32 v58, v58, v59
	v_cndmask_b32_e64 v58, v9, v58, s[0:1]
	v_cndmask_b32_e32 v17, v17, v58, vcc

; DI void rope8(float (&v)[8], const float* __restrict__ rope, int s, int fq) {
;     const f32x4 c0 = *(const f32x4*)(rope + s * 16), c1 = *(const f32x4*)(rope + s * 16 + 4), s0 = *(const f32x4*)(rope + s * 16 + 8), s1 = *(const f32x4*)(rope + s * 16 + 12);
;     const float cs[8] = {c0[0], c0[1], c0[2], c0[3], c1[0], c1[1], c1[2], c1[3]}, sn[8] = {s0[0], s0[1], s0[2], s0[3], s1[0], s1[1], s1[2], s1[3]};
; #pragma unroll
;     for (int e = 0; e < 8; ++e) {
;         const float other = __shfl_xor(v[e], 16);
;         const float a = v[e] * cs[e], bq = other * sn[e];
;         v[e] = (fq == 0) ? (a - bq) : ((fq == 1) ? (a + bq) : v[e]);
;     }
.LBB0_2250:
	s_andn2_b64 vcc, exec, s[10:11]
	s_cbranch_vccnz .LBB0_2300
	v_and_b32_e32 v11, 64, v188
	v_xor_b32_e32 v10, 16, v188
	v_add_u32_e32 v11, 64, v11
	v_cmp_lt_i32_e32 vcc, v10, v11
	v_lshlrev_b32_e32 v50, 6, v59
	s_nop 0
	v_cndmask_b32_e32 v10, v188, v10, vcc
	v_lshlrev_b32_e32 v60, 2, v10
	global_load_dwordx4 v[54:57], v50, s[68:69]
	global_load_dwordx4 v[10:13], v50, s[68:69] offset:32
	global_load_dwordx4 v[14:17], v50, s[68:69] offset:48
	s_nop 0
	global_load_dwordx4 v[50:53], v50, s[68:69] offset:16
	v_mov_b32_e32 v224, v2
	v_mov_b32_e32 v225, v2
	v_cmp_eq_u32_e64 s[0:1], 1, v177
	s_nop 0
	v_permlane16_swap_b32_e32 v224, v225
	v_cndmask_b32_e64 v61, v225, v224, s[0:1]
	v_cmp_lt_i32_e32 vcc, 0, v177
	s_waitcnt vmcnt(3)
	v_mul_f32_e32 v54, v2, v54
	s_waitcnt vmcnt(2) lgkmcnt(0)
	v_mul_f32_e32 v61, v10, v61
	v_sub_f32_e32 v10, v54, v61
	v_add_f32_e32 v54, v54, v61
	v_cndmask_b32_e64 v54, v2, v54, s[0:1]
	v_cndmask_b32_e32 v10, v10, v54, vcc
	v_mov_b32_e32 v224, v3
	v_mov_b32_e32 v225, v3
	s_nop 1
	v_permlane16_swap_b32_e32 v224, v225
	v_cndmask_b32_e64 v61, v225, v224, s[0:1]
	v_mul_f32_e32 v54, v3, v55
	s_waitcnt lgkmcnt(0)
	v_mul_f32_e32 v55, v11, v61
	v_sub_f32_e32 v11, v54, v55
	v_add_f32_e32 v54, v54, v55
	v_cndmask_b32_e64 v54, v3, v54, s[0:1]
	v_cndmask_b32_e32 v11, v11, v54, vcc
	v_mov_b32_e32 v224, v4
	v_mov_b32_e32 v225, v4
	s_nop 1
	v_permlane16_swap_b32_e32 v224, v225
	v_cndmask_b32_e64 v55, v225, v224, s[0:1]
	v_mul_f32_e32 v54, v4, v56
	s_waitcnt lgkmcnt(0)
	v_mul_f32_e32 v55, v12, v55
	v_sub_f32_e32 v12, v54, v55
	v_add_f32_e32 v54, v54, v55
	v_cndmask_b32_e64 v54, v4, v54, s[0:1]
	v_cndmask_b32_e32 v12, v12, v54, vcc
	v_mov_b32_e32 v224, v5
	v_mov_b32_e32 v225, v5
	s_nop 1
	v_permlane16_swap_b32_e32 v224, v225
	v_cndmask_b32_e64 v55, v225, v224, s[0:1]
	v_mul_f32_e32 v54, v5, v57
	s_waitcnt lgkmcnt(0)
	v_mul_f32_e32 v55, v13, v55
	v_sub_f32_e32 v13, v54, v55
	v_add_f32_e32 v54, v54, v55
	v_cndmask_b32_e64 v54, v5, v54, s[0:1]
	v_cndmask_b32_e32 v13, v13, v54, vcc
	v_mov_b32_e32 v224, v6
	v_mov_b32_e32 v225, v6
	s_nop 1
	v_permlane16_swap_b32_e32 v224, v225
	v_cndmask_b32_e64 v54, v225, v224, s[0:1]
	s_waitcnt vmcnt(0)
	v_mul_f32_e32 v50, v6, v50
	s_waitcnt lgkmcnt(0)
	v_mul_f32_e32 v54, v14, v54
	v_sub_f32_e32 v14, v50, v54
	v_add_f32_e32 v50, v50, v54
	v_cndmask_b32_e64 v50, v6, v50, s[0:1]
	v_cndmask_b32_e32 v14, v14, v50, vcc
	v_mov_b32_e32 v224, v7
	v_mov_b32_e32 v225, v7
	s_nop 1
	v_permlane16_swap_b32_e32 v224, v225
	v_cndmask_b32_e64 v54, v225, v224, s[0:1]
	v_mul_f32_e32 v50, v7, v51
	s_waitcnt lgkmcnt(0)
	v_mul_f32_e32 v51, v15, v54
	v_sub_f32_e32 v15, v50, v51
	v_add_f32_e32 v50, v50, v51
	v_cndmask_b32_e64 v50, v7, v50, s[0:1]
	v_cndmask_b32_e32 v15, v15, v50, vcc
	v_mov_b32_e32 v224, v8
	v_mov_b32_e32 v225, v8
	s_nop 1
	v_permlane16_swap_b32_e32 v224, v225
	v_cndmask_b32_e64 v51, v225, v224, s[0:1]
	v_mul_f32_e32 v50, v8, v52
	s_waitcnt lgkmcnt(0)
	v_mul_f32_e32 v51, v16, v51
	v_sub_f32_e32 v16, v50, v51
	v_add_f32_e32 v50, v50, v51
	v_cndmask_b32_e64 v50, v8, v50, s[0:1]
	v_cndmask_b32_e32 v16, v16, v50, vcc
	v_mov_b32_e32 v224, v9
	v_mov_b32_e32 v225, v9
	s_nop 1
	v_permlane16_swap_b32_e32 v224, v225
	v_cndmask_b32_e64 v51, v225, v224, s[0:1]
	v_mul_f32_e32 v50, v9, v53
	s_waitcnt lgkmcnt(0)
	v_mul_f32_e32 v51, v17, v51
	v_sub_f32_e32 v17, v50, v51
	v_add_f32_e32 v50, v50, v51
	v_cndmask_b32_e64 v50, v9, v50, s[0:1]
	v_cndmask_b32_e32 v17, v17, v50, vcc

; DI void rope8(float (&v)[8], const float* __restrict__ rope, int s, int fq) {
;     const f32x4 c0 = *(const f32x4*)(rope + s * 16), c1 = *(const f32x4*)(rope + s * 16 + 4), s0 = *(const f32x4*)(rope + s * 16 + 8), s1 = *(const f32x4*)(rope + s * 16 + 12);
;     const float cs[8] = {c0[0], c0[1], c0[2], c0[3], c1[0], c1[1], c1[2], c1[3]}, sn[8] = {s0[0], s0[1], s0[2], s0[3], s1[0], s1[1], s1[2], s1[3]};
; #pragma unroll
;     for (int e = 0; e < 8; ++e) {
;         const float other = __shfl_xor(v[e], 16);
;         const float a = v[e] * cs[e], bq = other * sn[e];
;         v[e] = (fq == 0) ? (a - bq) : ((fq == 1) ? (a + bq) : v[e]);
;     }
.LBB0_2306:
	s_andn2_b64 vcc, exec, s[10:11]
	s_cbranch_vccnz .LBB0_2356
	v_and_b32_e32 v11, 64, v188
	v_xor_b32_e32 v10, 16, v188
	v_add_u32_e32 v11, 64, v11
	v_cmp_lt_i32_e32 vcc, v10, v11
	v_lshlrev_b32_e32 v42, 6, v51
	s_nop 0
	v_cndmask_b32_e32 v10, v188, v10, vcc
	v_lshlrev_b32_e32 v52, 2, v10
	global_load_dwordx4 v[46:49], v42, s[68:69]
	global_load_dwordx4 v[10:13], v42, s[68:69] offset:32
	global_load_dwordx4 v[14:17], v42, s[68:69] offset:48
	s_nop 0
	global_load_dwordx4 v[42:45], v42, s[68:69] offset:16
	v_mov_b32_e32 v224, v2
	v_mov_b32_e32 v225, v2
	v_cmp_eq_u32_e64 s[0:1], 1, v177
	s_nop 0
	v_permlane16_swap_b32_e32 v224, v225
	v_cndmask_b32_e64 v53, v225, v224, s[0:1]
	v_cmp_lt_i32_e32 vcc, 0, v177
	s_waitcnt vmcnt(3)
	v_mul_f32_e32 v46, v2, v46
	s_waitcnt vmcnt(2) lgkmcnt(0)
	v_mul_f32_e32 v53, v10, v53
	v_sub_f32_e32 v10, v46, v53
	v_add_f32_e32 v46, v46, v53
	v_cndmask_b32_e64 v46, v2, v46, s[0:1]
	v_cndmask_b32_e32 v10, v10, v46, vcc
	v_mov_b32_e32 v224, v3
	v_mov_b32_e32 v225, v3
	s_nop 1
	v_permlane16_swap_b32_e32 v224, v225
	v_cndmask_b32_e64 v53, v225, v224, s[0:1]
	v_mul_f32_e32 v46, v3, v47
	s_waitcnt lgkmcnt(0)
	v_mul_f32_e32 v47, v11, v53
	v_sub_f32_e32 v11, v46, v47
	v_add_f32_e32 v46, v46, v47
	v_cndmask_b32_e64 v46, v3, v46, s[0:1]
	v_cndmask_b32_e32 v11, v11, v46, vcc
	v_mov_b32_e32 v224, v4
	v_mov_b32_e32 v225, v4
	s_nop 1
	v_permlane16_swap_b32_e32 v224, v225
	v_cndmask_b32_e64 v47, v225, v224, s[0:1]
	v_mul_f32_e32 v46, v4, v48
	s_waitcnt lgkmcnt(0)
	v_mul_f32_e32 v47, v12, v47
	v_sub_f32_e32 v12, v46, v47
	v_add_f32_e32 v46, v46, v47
	v_cndmask_b32_e64 v46, v4, v46, s[0:1]
	v_cndmask_b32_e32 v12, v12, v46, vcc
	v_mov_b32_e32 v224, v5
	v_mov_b32_e32 v225, v5
	s_nop 1
	v_permlane16_swap_b32_e32 v224, v225
	v_cndmask_b32_e64 v47, v225, v224, s[0:1]
	v_mul_f32_e32 v46, v5, v49
	s_waitcnt lgkmcnt(0)
	v_mul_f32_e32 v47, v13, v47
	v_sub_f32_e32 v13, v46, v47
	v_add_f32_e32 v46, v46, v47
	v_cndmask_b32_e64 v46, v5, v46, s[0:1]
	v_cndmask_b32_e32 v13, v13, v46, vcc
	v_mov_b32_e32 v224, v6
	v_mov_b32_e32 v225, v6
	s_nop 1
	v_permlane16_swap_b32_e32 v224, v225
	v_cndmask_b32_e64 v46, v225, v224, s[0:1]
	s_waitcnt vmcnt(0)
	v_mul_f32_e32 v42, v6, v42
	s_waitcnt lgkmcnt(0)
	v_mul_f32_e32 v46, v14, v46
	v_sub_f32_e32 v14, v42, v46
	v_add_f32_e32 v42, v42, v46
	v_cndmask_b32_e64 v42, v6, v42, s[0:1]
	v_cndmask_b32_e32 v14, v14, v42, vcc
	v_mov_b32_e32 v224, v7
	v_mov_b32_e32 v225, v7
	s_nop 1
	v_permlane16_swap_b32_e32 v224, v225
	v_cndmask_b32_e64 v46, v225, v224, s[0:1]
	v_mul_f32_e32 v42, v7, v43
	s_waitcnt lgkmcnt(0)
	v_mul_f32_e32 v43, v15, v46
	v_sub_f32_e32 v15, v42, v43
	v_add_f32_e32 v42, v42, v43
	v_cndmask_b32_e64 v42, v7, v42, s[0:1]
	v_cndmask_b32_e32 v15, v15, v42, vcc
	v_mov_b32_e32 v224, v8
	v_mov_b32_e32 v225, v8
	s_nop 1
	v_permlane16_swap_b32_e32 v224, v225
	v_cndmask_b32_e64 v43, v225, v224, s[0:1]
	v_mul_f32_e32 v42, v8, v44
	s_waitcnt lgkmcnt(0)
	v_mul_f32_e32 v43, v16, v43
	v_sub_f32_e32 v16, v42, v43
	v_add_f32_e32 v42, v42, v43
	v_cndmask_b32_e64 v42, v8, v42, s[0:1]
	v_cndmask_b32_e32 v16, v16, v42, vcc
	v_mov_b32_e32 v224, v9
	v_mov_b32_e32 v225, v9
	s_nop 1
	v_permlane16_swap_b32_e32 v224, v225
	v_cndmask_b32_e64 v43, v225, v224, s[0:1]
	v_mul_f32_e32 v42, v9, v45
	s_waitcnt lgkmcnt(0)
	v_mul_f32_e32 v43, v17, v43
	v_sub_f32_e32 v17, v42, v43
	v_add_f32_e32 v42, v42, v43
	v_cndmask_b32_e64 v42, v9, v42, s[0:1]
	v_cndmask_b32_e32 v17, v17, v42, vcc

; DI void rope8(float (&v)[8], const float* __restrict__ rope, int s, int fq) {
;     const f32x4 c0 = *(const f32x4*)(rope + s * 16), c1 = *(const f32x4*)(rope + s * 16 + 4), s0 = *(const f32x4*)(rope + s * 16 + 8), s1 = *(const f32x4*)(rope + s * 16 + 12);
;     const float cs[8] = {c0[0], c0[1], c0[2], c0[3], c1[0], c1[1], c1[2], c1[3]}, sn[8] = {s0[0], s0[1], s0[2], s0[3], s1[0], s1[1], s1[2], s1[3]};
; #pragma unroll
;     for (int e = 0; e < 8; ++e) {
;         const float other = __shfl_xor(v[e], 16);
;         const float a = v[e] * cs[e], bq = other * sn[e];
;         v[e] = (fq == 0) ? (a - bq) : ((fq == 1) ? (a + bq) : v[e]);
;     }
.LBB0_2362:
	s_andn2_b64 vcc, exec, s[10:11]
	s_cbranch_vccnz .LBB0_2412
	v_and_b32_e32 v11, 64, v188
	v_xor_b32_e32 v10, 16, v188
	v_add_u32_e32 v11, 64, v11
	v_cmp_lt_i32_e32 vcc, v10, v11
	v_lshlrev_b32_e32 v34, 6, v45
	s_nop 0
	v_cndmask_b32_e32 v10, v188, v10, vcc
	v_lshlrev_b32_e32 v46, 2, v10
	global_load_dwordx4 v[38:41], v34, s[68:69]
	global_load_dwordx4 v[10:13], v34, s[68:69] offset:32
	global_load_dwordx4 v[14:17], v34, s[68:69] offset:48
	s_nop 0
	global_load_dwordx4 v[34:37], v34, s[68:69] offset:16
	v_mov_b32_e32 v224, v2
	v_mov_b32_e32 v225, v2
	v_cmp_eq_u32_e64 s[0:1], 1, v177
	s_nop 0
	v_permlane16_swap_b32_e32 v224, v225
	v_cndmask_b32_e64 v47, v225, v224, s[0:1]
	v_cmp_lt_i32_e32 vcc, 0, v177
	s_waitcnt vmcnt(3)
	v_mul_f32_e32 v38, v2, v38
	s_waitcnt vmcnt(2) lgkmcnt(0)
	v_mul_f32_e32 v47, v10, v47
	v_sub_f32_e32 v10, v38, v47
	v_add_f32_e32 v38, v38, v47
	v_cndmask_b32_e64 v38, v2, v38, s[0:1]
	v_cndmask_b32_e32 v10, v10, v38, vcc
	v_mov_b32_e32 v224, v3
	v_mov_b32_e32 v225, v3
	s_nop 1
	v_permlane16_swap_b32_e32 v224, v225
	v_cndmask_b32_e64 v47, v225, v224, s[0:1]
	v_mul_f32_e32 v38, v3, v39
	s_waitcnt lgkmcnt(0)
	v_mul_f32_e32 v39, v11, v47
	v_sub_f32_e32 v11, v38, v39
	v_add_f32_e32 v38, v38, v39
	v_cndmask_b32_e64 v38, v3, v38, s[0:1]
	v_cndmask_b32_e32 v11, v11, v38, vcc
	v_mov_b32_e32 v224, v4
	v_mov_b32_e32 v225, v4
	s_nop 1
	v_permlane16_swap_b32_e32 v224, v225
	v_cndmask_b32_e64 v39, v225, v224, s[0:1]
	v_mul_f32_e32 v38, v4, v40
	s_waitcnt lgkmcnt(0)
	v_mul_f32_e32 v39, v12, v39
	v_sub_f32_e32 v12, v38, v39
	v_add_f32_e32 v38, v38, v39
	v_cndmask_b32_e64 v38, v4, v38, s[0:1]
	v_cndmask_b32_e32 v12, v12, v38, vcc
	v_mov_b32_e32 v224, v5
	v_mov_b32_e32 v225, v5
	s_nop 1
	v_permlane16_swap_b32_e32 v224, v225
	v_cndmask_b32_e64 v39, v225, v224, s[0:1]
	v_mul_f32_e32 v38, v5, v41
	s_waitcnt lgkmcnt(0)
	v_mul_f32_e32 v39, v13, v39
	v_sub_f32_e32 v13, v38, v39
	v_add_f32_e32 v38, v38, v39
	v_cndmask_b32_e64 v38, v5, v38, s[0:1]
	v_cndmask_b32_e32 v13, v13, v38, vcc
	v_mov_b32_e32 v224, v6
	v_mov_b32_e32 v225, v6
	s_nop 1
	v_permlane16_swap_b32_e32 v224, v225
	v_cndmask_b32_e64 v38, v225, v224, s[0:1]
	s_waitcnt vmcnt(0)
	v_mul_f32_e32 v34, v6, v34
	s_waitcnt lgkmcnt(0)
	v_mul_f32_e32 v38, v14, v38
	v_sub_f32_e32 v14, v34, v38
	v_add_f32_e32 v34, v34, v38
	v_cndmask_b32_e64 v34, v6, v34, s[0:1]
	v_cndmask_b32_e32 v14, v14, v34, vcc
	v_mov_b32_e32 v224, v7
	v_mov_b32_e32 v225, v7
	s_nop 1
	v_permlane16_swap_b32_e32 v224, v225
	v_cndmask_b32_e64 v38, v225, v224, s[0:1]
	v_mul_f32_e32 v34, v7, v35
	s_waitcnt lgkmcnt(0)
	v_mul_f32_e32 v35, v15, v38
	v_sub_f32_e32 v15, v34, v35
	v_add_f32_e32 v34, v34, v35
	v_cndmask_b32_e64 v34, v7, v34, s[0:1]
	v_cndmask_b32_e32 v15, v15, v34, vcc
	v_mov_b32_e32 v224, v8
	v_mov_b32_e32 v225, v8
	s_nop 1
	v_permlane16_swap_b32_e32 v224, v225
	v_cndmask_b32_e64 v35, v225, v224, s[0:1]
	v_mul_f32_e32 v34, v8, v36
	s_waitcnt lgkmcnt(0)
	v_mul_f32_e32 v35, v16, v35
	v_sub_f32_e32 v16, v34, v35
	v_add_f32_e32 v34, v34, v35
	v_cndmask_b32_e64 v34, v8, v34, s[0:1]
	v_cndmask_b32_e32 v16, v16, v34, vcc
	v_mov_b32_e32 v224, v9
	v_mov_b32_e32 v225, v9
	s_nop 1
	v_permlane16_swap_b32_e32 v224, v225
	v_cndmask_b32_e64 v35, v225, v224, s[0:1]
	v_mul_f32_e32 v34, v9, v37
	s_waitcnt lgkmcnt(0)
	v_mul_f32_e32 v35, v17, v35
	v_sub_f32_e32 v17, v34, v35
	v_add_f32_e32 v34, v34, v35
	v_cndmask_b32_e64 v34, v9, v34, s[0:1]
	v_cndmask_b32_e32 v17, v17, v34, vcc

; DI void rope8(float (&v)[8], const float* __restrict__ rope, int s, int fq) {
;     const f32x4 c0 = *(const f32x4*)(rope + s * 16), c1 = *(const f32x4*)(rope + s * 16 + 4), s0 = *(const f32x4*)(rope + s * 16 + 8), s1 = *(const f32x4*)(rope + s * 16 + 12);
;     const float cs[8] = {c0[0], c0[1], c0[2], c0[3], c1[0], c1[1], c1[2], c1[3]}, sn[8] = {s0[0], s0[1], s0[2], s0[3], s1[0], s1[1], s1[2], s1[3]};
; #pragma unroll
;     for (int e = 0; e < 8; ++e) {
;         const float other = __shfl_xor(v[e], 16);
;         const float a = v[e] * cs[e], bq = other * sn[e];
;         v[e] = (fq == 0) ? (a - bq) : ((fq == 1) ? (a + bq) : v[e]);
;     }
.LBB0_2418:
	s_andn2_b64 vcc, exec, s[10:11]
	s_cbranch_vccnz .LBB0_2468
	v_and_b32_e32 v11, 64, v188
	v_xor_b32_e32 v10, 16, v188
	v_add_u32_e32 v11, 64, v11
	v_cmp_lt_i32_e32 vcc, v10, v11
	v_lshlrev_b32_e32 v26, 6, v35
	s_nop 0
	v_cndmask_b32_e32 v10, v188, v10, vcc
	v_lshlrev_b32_e32 v36, 2, v10
	global_load_dwordx4 v[30:33], v26, s[68:69]
	global_load_dwordx4 v[10:13], v26, s[68:69] offset:32
	global_load_dwordx4 v[14:17], v26, s[68:69] offset:48
	s_nop 0
	global_load_dwordx4 v[26:29], v26, s[68:69] offset:16
	v_mov_b32_e32 v224, v2
	v_mov_b32_e32 v225, v2
	v_cmp_eq_u32_e64 s[0:1], 1, v177
	s_nop 0
	v_permlane16_swap_b32_e32 v224, v225
	v_cndmask_b32_e64 v37, v225, v224, s[0:1]
	v_cmp_lt_i32_e32 vcc, 0, v177
	s_waitcnt vmcnt(3)
	v_mul_f32_e32 v30, v2, v30
	s_waitcnt vmcnt(2) lgkmcnt(0)
	v_mul_f32_e32 v37, v10, v37
	v_sub_f32_e32 v10, v30, v37
	v_add_f32_e32 v30, v30, v37
	v_cndmask_b32_e64 v30, v2, v30, s[0:1]
	v_cndmask_b32_e32 v10, v10, v30, vcc
	v_mov_b32_e32 v224, v3
	v_mov_b32_e32 v225, v3
	s_nop 1
	v_permlane16_swap_b32_e32 v224, v225
	v_cndmask_b32_e64 v37, v225, v224, s[0:1]
	v_mul_f32_e32 v30, v3, v31
	s_waitcnt lgkmcnt(0)
	v_mul_f32_e32 v31, v11, v37
	v_sub_f32_e32 v11, v30, v31
	v_add_f32_e32 v30, v30, v31
	v_cndmask_b32_e64 v30, v3, v30, s[0:1]
	v_cndmask_b32_e32 v11, v11, v30, vcc
	v_mov_b32_e32 v224, v4
	v_mov_b32_e32 v225, v4
	s_nop 1
	v_permlane16_swap_b32_e32 v224, v225
	v_cndmask_b32_e64 v31, v225, v224, s[0:1]
	v_mul_f32_e32 v30, v4, v32
	s_waitcnt lgkmcnt(0)
	v_mul_f32_e32 v31, v12, v31
	v_sub_f32_e32 v12, v30, v31
	v_add_f32_e32 v30, v30, v31
	v_cndmask_b32_e64 v30, v4, v30, s[0:1]
	v_cndmask_b32_e32 v12, v12, v30, vcc
	v_mov_b32_e32 v224, v5
	v_mov_b32_e32 v225, v5
	s_nop 1
	v_permlane16_swap_b32_e32 v224, v225
	v_cndmask_b32_e64 v31, v225, v224, s[0:1]
	v_mul_f32_e32 v30, v5, v33
	s_waitcnt lgkmcnt(0)
	v_mul_f32_e32 v31, v13, v31
	v_sub_f32_e32 v13, v30, v31
	v_add_f32_e32 v30, v30, v31
	v_cndmask_b32_e64 v30, v5, v30, s[0:1]
	v_cndmask_b32_e32 v13, v13, v30, vcc
	v_mov_b32_e32 v224, v6
	v_mov_b32_e32 v225, v6
	s_nop 1
	v_permlane16_swap_b32_e32 v224, v225
	v_cndmask_b32_e64 v30, v225, v224, s[0:1]
	s_waitcnt vmcnt(0)
	v_mul_f32_e32 v26, v6, v26
	s_waitcnt lgkmcnt(0)
	v_mul_f32_e32 v30, v14, v30
	v_sub_f32_e32 v14, v26, v30
	v_add_f32_e32 v26, v26, v30
	v_cndmask_b32_e64 v26, v6, v26, s[0:1]
	v_cndmask_b32_e32 v14, v14, v26, vcc
	v_mov_b32_e32 v224, v7
	v_mov_b32_e32 v225, v7
	s_nop 1
	v_permlane16_swap_b32_e32 v224, v225
	v_cndmask_b32_e64 v30, v225, v224, s[0:1]
	v_mul_f32_e32 v26, v7, v27
	s_waitcnt lgkmcnt(0)
	v_mul_f32_e32 v27, v15, v30
	v_sub_f32_e32 v15, v26, v27
	v_add_f32_e32 v26, v26, v27
	v_cndmask_b32_e64 v26, v7, v26, s[0:1]
	v_cndmask_b32_e32 v15, v15, v26, vcc
	v_mov_b32_e32 v224, v8
	v_mov_b32_e32 v225, v8
	s_nop 1
	v_permlane16_swap_b32_e32 v224, v225
	v_cndmask_b32_e64 v27, v225, v224, s[0:1]
	v_mul_f32_e32 v26, v8, v28
	s_waitcnt lgkmcnt(0)
	v_mul_f32_e32 v27, v16, v27
	v_sub_f32_e32 v16, v26, v27
	v_add_f32_e32 v26, v26, v27
	v_cndmask_b32_e64 v26, v8, v26, s[0:1]
	v_cndmask_b32_e32 v16, v16, v26, vcc
	v_mov_b32_e32 v224, v9
	v_mov_b32_e32 v225, v9
	s_nop 1
	v_permlane16_swap_b32_e32 v224, v225
	v_cndmask_b32_e64 v27, v225, v224, s[0:1]
	v_mul_f32_e32 v26, v9, v29
	s_waitcnt lgkmcnt(0)
	v_mul_f32_e32 v27, v17, v27
	v_sub_f32_e32 v17, v26, v27
	v_add_f32_e32 v26, v26, v27
	v_cndmask_b32_e64 v26, v9, v26, s[0:1]
	v_cndmask_b32_e32 v17, v17, v26, vcc

; DI void rope8(float (&v)[8], const float* __restrict__ rope, int s, int fq) {
;     const f32x4 c0 = *(const f32x4*)(rope + s * 16), c1 = *(const f32x4*)(rope + s * 16 + 4), s0 = *(const f32x4*)(rope + s * 16 + 8), s1 = *(const f32x4*)(rope + s * 16 + 12);
;     const float cs[8] = {c0[0], c0[1], c0[2], c0[3], c1[0], c1[1], c1[2], c1[3]}, sn[8] = {s0[0], s0[1], s0[2], s0[3], s1[0], s1[1], s1[2], s1[3]};
; #pragma unroll
;     for (int e = 0; e < 8; ++e) {
;         const float other = __shfl_xor(v[e], 16);
;         const float a = v[e] * cs[e], bq = other * sn[e];
;         v[e] = (fq == 0) ? (a - bq) : ((fq == 1) ? (a + bq) : v[e]);
;     }
.LBB0_2474:
	s_andn2_b64 vcc, exec, s[6:7]
	s_cbranch_vccnz .LBB0_2524
	v_and_b32_e32 v11, 64, v188
	v_xor_b32_e32 v10, 16, v188
	v_add_u32_e32 v11, 64, v11
	v_cmp_lt_i32_e32 vcc, v10, v11
	v_lshlrev_b32_e32 v18, 6, v27
	s_nop 0
	v_cndmask_b32_e32 v10, v188, v10, vcc
	v_lshlrev_b32_e32 v28, 2, v10
	global_load_dwordx4 v[22:25], v18, s[68:69]
	global_load_dwordx4 v[10:13], v18, s[68:69] offset:32
	global_load_dwordx4 v[14:17], v18, s[68:69] offset:48
	s_nop 0
	global_load_dwordx4 v[18:21], v18, s[68:69] offset:16
	v_mov_b32_e32 v224, v2
	v_mov_b32_e32 v225, v2
	v_cmp_eq_u32_e64 s[0:1], 1, v177
	s_nop 0
	v_permlane16_swap_b32_e32 v224, v225
	v_cndmask_b32_e64 v29, v225, v224, s[0:1]
	v_cmp_lt_i32_e32 vcc, 0, v177
	s_waitcnt vmcnt(3)
	v_mul_f32_e32 v22, v2, v22
	s_waitcnt vmcnt(2) lgkmcnt(0)
	v_mul_f32_e32 v29, v10, v29
	v_sub_f32_e32 v10, v22, v29
	v_add_f32_e32 v22, v22, v29
	v_cndmask_b32_e64 v22, v2, v22, s[0:1]
	v_cndmask_b32_e32 v10, v10, v22, vcc
	v_mov_b32_e32 v224, v3
	v_mov_b32_e32 v225, v3
	s_nop 1
	v_permlane16_swap_b32_e32 v224, v225
	v_cndmask_b32_e64 v29, v225, v224, s[0:1]
	v_mul_f32_e32 v22, v3, v23
	s_waitcnt lgkmcnt(0)
	v_mul_f32_e32 v23, v11, v29
	v_sub_f32_e32 v11, v22, v23
	v_add_f32_e32 v22, v22, v23
	v_cndmask_b32_e64 v22, v3, v22, s[0:1]
	v_cndmask_b32_e32 v11, v11, v22, vcc
	v_mov_b32_e32 v224, v4
	v_mov_b32_e32 v225, v4
	s_nop 1
	v_permlane16_swap_b32_e32 v224, v225
	v_cndmask_b32_e64 v23, v225, v224, s[0:1]
	v_mul_f32_e32 v22, v4, v24
	s_waitcnt lgkmcnt(0)
	v_mul_f32_e32 v23, v12, v23
	v_sub_f32_e32 v12, v22, v23
	v_add_f32_e32 v22, v22, v23
	v_cndmask_b32_e64 v22, v4, v22, s[0:1]
	v_cndmask_b32_e32 v12, v12, v22, vcc
	v_mov_b32_e32 v224, v5
	v_mov_b32_e32 v225, v5
	s_nop 1
	v_permlane16_swap_b32_e32 v224, v225
	v_cndmask_b32_e64 v23, v225, v224, s[0:1]
	v_mul_f32_e32 v22, v5, v25
	s_waitcnt lgkmcnt(0)
	v_mul_f32_e32 v23, v13, v23
	v_sub_f32_e32 v13, v22, v23
	v_add_f32_e32 v22, v22, v23
	v_cndmask_b32_e64 v22, v5, v22, s[0:1]
	v_cndmask_b32_e32 v13, v13, v22, vcc
	v_mov_b32_e32 v224, v6
	v_mov_b32_e32 v225, v6
	s_nop 1
	v_permlane16_swap_b32_e32 v224, v225
	v_cndmask_b32_e64 v22, v225, v224, s[0:1]
	s_waitcnt vmcnt(0)
	v_mul_f32_e32 v18, v6, v18
	s_waitcnt lgkmcnt(0)
	v_mul_f32_e32 v22, v14, v22
	v_sub_f32_e32 v14, v18, v22
	v_add_f32_e32 v18, v18, v22
	v_cndmask_b32_e64 v18, v6, v18, s[0:1]
	v_cndmask_b32_e32 v14, v14, v18, vcc
	v_mov_b32_e32 v224, v7
	v_mov_b32_e32 v225, v7
	s_nop 1
	v_permlane16_swap_b32_e32 v224, v225
	v_cndmask_b32_e64 v22, v225, v224, s[0:1]
	v_mul_f32_e32 v18, v7, v19
	s_waitcnt lgkmcnt(0)
	v_mul_f32_e32 v19, v15, v22
	v_sub_f32_e32 v15, v18, v19
	v_add_f32_e32 v18, v18, v19
	v_cndmask_b32_e64 v18, v7, v18, s[0:1]
	v_cndmask_b32_e32 v15, v15, v18, vcc
	v_mov_b32_e32 v224, v8
	v_mov_b32_e32 v225, v8
	s_nop 1
	v_permlane16_swap_b32_e32 v224, v225
	v_cndmask_b32_e64 v19, v225, v224, s[0:1]
	v_mul_f32_e32 v18, v8, v20
	s_waitcnt lgkmcnt(0)
	v_mul_f32_e32 v19, v16, v19
	v_sub_f32_e32 v16, v18, v19
	v_add_f32_e32 v18, v18, v19
	v_cndmask_b32_e64 v18, v8, v18, s[0:1]
	v_cndmask_b32_e32 v16, v16, v18, vcc
	v_mov_b32_e32 v224, v9
	v_mov_b32_e32 v225, v9
	s_nop 1
	v_permlane16_swap_b32_e32 v224, v225
	v_cndmask_b32_e64 v19, v225, v224, s[0:1]
	v_mul_f32_e32 v18, v9, v21
	s_waitcnt lgkmcnt(0)
	v_mul_f32_e32 v19, v17, v19
	v_sub_f32_e32 v17, v18, v19
	v_add_f32_e32 v18, v18, v19
	v_cndmask_b32_e64 v18, v9, v18, s[0:1]
	v_cndmask_b32_e32 v17, v17, v18, vcc
